# v49 plus K-loop final barrier skipped on exit: wr0 half takes it as ALIGN, wr1 half after its epilogue; loop-control SALU moved into L4
# baseline (speedup 1.0000x reference)
.LBB0_402:
	ds_read_b128 v[130:133], v167
	ds_read_b128 v[134:137], v167 offset:1024
	ds_read_b128 v[138:141], v167 offset:2048
	ds_read_b128 v[178:181], v167 offset:3072
	ds_read_b128 v[182:185], v168
	ds_read_b128 v[188:191], v168 offset:1024
	ds_read_b128 v[192:195], v168 offset:2048
	ds_read_b128 v[196:199], v168 offset:3072
	s_add_u32 s41, s60, 0xfff00080
	s_addc_u32 s62, s61, -1
	s_cmp_eq_u32 s39, 60
	s_cselect_b32 s65, s43, s62
	s_cselect_b32 s64, s42, s41
	s_cselect_b32 s63, s45, s10
	s_cselect_b32 s62, s44, s9
	s_add_i32 m0, s47, 0xc000
	ds_read_b128 v[200:203], v169
	ds_read_b128 v[204:207], v169 offset:1024
	ds_read_b128 v[208:211], v169 offset:2048
	ds_read_b128 v[212:215], v169 offset:3072
	ds_read_b128 v[216:219], v169 offset:4096
	ds_read_b128 v[220:223], v169 offset:5120
	ds_read_b128 v[224:227], v169 offset:6144
	ds_read_b128 v[228:231], v169 offset:7168
	global_load_lds_dwordx4 v158, s[60:61]
	s_add_i32 m0, s47, 0xe000
	s_nop 0
	global_load_lds_dwordx4 v156, s[60:61]
	s_waitcnt vmcnt(8)
	s_waitcnt lgkmcnt(0)
	s_setprio 1
	s_barrier
	v_mfma_f32_16x16x32_bf16 v[126:129], v[130:133], v[200:203], v[126:129]
	v_mfma_f32_16x16x32_bf16 v[122:125], v[138:141], v[200:203], v[122:125]
	v_mfma_f32_16x16x32_bf16 v[110:113], v[130:133], v[208:211], v[110:113]
	v_mfma_f32_16x16x32_bf16 v[106:109], v[138:141], v[208:211], v[106:109]
	v_mfma_f32_16x16x32_bf16 v[94:97], v[130:133], v[216:219], v[94:97]
	v_mfma_f32_16x16x32_bf16 v[90:93], v[138:141], v[216:219], v[90:93]
	v_mfma_f32_16x16x32_bf16 v[78:81], v[130:133], v[224:227], v[78:81]
	v_mfma_f32_16x16x32_bf16 v[74:77], v[138:141], v[224:227], v[74:77]
	v_mfma_f32_16x16x32_bf16 v[126:129], v[134:137], v[204:207], v[126:129]
	v_mfma_f32_16x16x32_bf16 v[122:125], v[178:181], v[204:207], v[122:125]
	v_mfma_f32_16x16x32_bf16 v[110:113], v[134:137], v[212:215], v[110:113]
	v_mfma_f32_16x16x32_bf16 v[106:109], v[178:181], v[212:215], v[106:109]
	v_mfma_f32_16x16x32_bf16 v[94:97], v[134:137], v[220:223], v[94:97]
	v_mfma_f32_16x16x32_bf16 v[90:93], v[178:181], v[220:223], v[90:93]
	v_mfma_f32_16x16x32_bf16 v[78:81], v[134:137], v[228:231], v[78:81]
	v_mfma_f32_16x16x32_bf16 v[74:77], v[178:181], v[228:231], v[74:77]
	v_mfma_f32_16x16x32_bf16 v[118:121], v[182:185], v[200:203], v[118:121]
	v_mfma_f32_16x16x32_bf16 v[114:117], v[192:195], v[200:203], v[114:117]
	v_mfma_f32_16x16x32_bf16 v[102:105], v[182:185], v[208:211], v[102:105]
	v_mfma_f32_16x16x32_bf16 v[98:101], v[192:195], v[208:211], v[98:101]
	v_mfma_f32_16x16x32_bf16 v[86:89], v[182:185], v[216:219], v[86:89]
	v_mfma_f32_16x16x32_bf16 v[82:85], v[192:195], v[216:219], v[82:85]
	v_mfma_f32_16x16x32_bf16 v[70:73], v[182:185], v[224:227], v[70:73]
	v_mfma_f32_16x16x32_bf16 v[66:69], v[192:195], v[224:227], v[66:69]
	v_mfma_f32_16x16x32_bf16 v[118:121], v[188:191], v[204:207], v[118:121]
	v_mfma_f32_16x16x32_bf16 v[114:117], v[196:199], v[204:207], v[114:117]
	v_mfma_f32_16x16x32_bf16 v[102:105], v[188:191], v[212:215], v[102:105]
	v_mfma_f32_16x16x32_bf16 v[98:101], v[196:199], v[212:215], v[98:101]
	v_mfma_f32_16x16x32_bf16 v[86:89], v[188:191], v[220:223], v[86:89]
	v_mfma_f32_16x16x32_bf16 v[82:85], v[196:199], v[220:223], v[82:85]
	v_mfma_f32_16x16x32_bf16 v[70:73], v[188:191], v[228:231], v[70:73]
	v_mfma_f32_16x16x32_bf16 v[66:69], v[196:199], v[228:231], v[66:69]
	s_barrier
	s_setprio 0
	s_add_i32 s41, s83, s70
	v_lshl_add_u64 v[164:165], s[62:63], 0, v[144:145]
	s_mov_b32 m0, s41
	ds_read_b128 v[200:203], v169 offset:16384
	ds_read_b128 v[204:207], v169 offset:17408
	ds_read_b128 v[208:211], v169 offset:18432
	ds_read_b128 v[212:215], v169 offset:19456
	ds_read_b128 v[216:219], v169 offset:20480
	ds_read_b128 v[220:223], v169 offset:21504
	ds_read_b128 v[224:227], v169 offset:22528
	ds_read_b128 v[228:231], v169 offset:23552
	global_load_lds_dwordx4 v[164:165], off
	s_add_i32 m0, s41, 0x2000
	s_add_u32 vcc_lo, s62, 0x100000
	v_lshl_add_u64 v[232:233], s[62:63], 0, v[148:149]
	s_addc_u32 vcc_hi, s63, 0
	s_add_i32 s41, s84, s70
	global_load_lds_dwordx4 v[232:233], off
	s_mov_b32 m0, s41
	v_lshl_add_u64 v[236:237], s[64:65], 0, v[146:147]
	global_load_lds_dwordx4 v144, vcc
	s_add_i32 m0, s41, 0x2000
	s_nop 0
	global_load_lds_dwordx4 v148, vcc
	v_lshl_add_u64 v[234:235], s[64:65], 0, v[142:143]
	s_mov_b32 m0, s47
	s_nop 0
	global_load_lds_dwordx4 v[234:235], off
	s_mov_b32 m0, s71
	s_nop 0
	global_load_lds_dwordx4 v[236:237], off
	s_waitcnt vmcnt(8)
	s_waitcnt lgkmcnt(0)
	s_setprio 1
	s_barrier
	v_mfma_f32_16x16x32_bf16 v[62:65], v[130:133], v[200:203], v[62:65]
	v_mfma_f32_16x16x32_bf16 v[58:61], v[138:141], v[200:203], v[58:61]
	v_mfma_f32_16x16x32_bf16 v[46:49], v[130:133], v[208:211], v[46:49]
	v_mfma_f32_16x16x32_bf16 v[42:45], v[138:141], v[208:211], v[42:45]
	v_mfma_f32_16x16x32_bf16 v[30:33], v[130:133], v[216:219], v[30:33]
	v_mfma_f32_16x16x32_bf16 v[26:29], v[138:141], v[216:219], v[26:29]
	v_mfma_f32_16x16x32_bf16 v[14:17], v[130:133], v[224:227], v[14:17]
	v_mfma_f32_16x16x32_bf16 v[10:13], v[138:141], v[224:227], v[10:13]
	v_mfma_f32_16x16x32_bf16 v[62:65], v[134:137], v[204:207], v[62:65]
	v_mfma_f32_16x16x32_bf16 v[58:61], v[178:181], v[204:207], v[58:61]
	v_mfma_f32_16x16x32_bf16 v[46:49], v[134:137], v[212:215], v[46:49]
	v_mfma_f32_16x16x32_bf16 v[42:45], v[178:181], v[212:215], v[42:45]
	v_mfma_f32_16x16x32_bf16 v[30:33], v[134:137], v[220:223], v[30:33]
	v_mfma_f32_16x16x32_bf16 v[26:29], v[178:181], v[220:223], v[26:29]
	v_mfma_f32_16x16x32_bf16 v[14:17], v[134:137], v[228:231], v[14:17]
	v_mfma_f32_16x16x32_bf16 v[10:13], v[178:181], v[228:231], v[10:13]
	v_mfma_f32_16x16x32_bf16 v[54:57], v[182:185], v[200:203], v[54:57]
	v_mfma_f32_16x16x32_bf16 v[50:53], v[192:195], v[200:203], v[50:53]
	v_mfma_f32_16x16x32_bf16 v[38:41], v[182:185], v[208:211], v[38:41]
	v_mfma_f32_16x16x32_bf16 v[34:37], v[192:195], v[208:211], v[34:37]
	v_mfma_f32_16x16x32_bf16 v[22:25], v[182:185], v[216:219], v[22:25]
	v_mfma_f32_16x16x32_bf16 v[18:21], v[192:195], v[216:219], v[18:21]
	v_mfma_f32_16x16x32_bf16 v[6:9], v[182:185], v[224:227], v[6:9]
	v_mfma_f32_16x16x32_bf16 v[2:5], v[192:195], v[224:227], v[2:5]
	v_mfma_f32_16x16x32_bf16 v[54:57], v[188:191], v[204:207], v[54:57]
	v_mfma_f32_16x16x32_bf16 v[50:53], v[196:199], v[204:207], v[50:53]
	v_mfma_f32_16x16x32_bf16 v[38:41], v[188:191], v[212:215], v[38:41]
	v_mfma_f32_16x16x32_bf16 v[34:37], v[196:199], v[212:215], v[34:37]
	v_mfma_f32_16x16x32_bf16 v[22:25], v[188:191], v[220:223], v[22:25]
	v_mfma_f32_16x16x32_bf16 v[18:21], v[196:199], v[220:223], v[18:21]
	v_mfma_f32_16x16x32_bf16 v[6:9], v[188:191], v[228:231], v[6:9]
	v_mfma_f32_16x16x32_bf16 v[2:5], v[196:199], v[228:231], v[2:5]
	s_barrier
	s_setprio 0
	s_add_i32 s41, 0, 0x18000
	v_add_u32_e32 v150, s41, v153
	s_add_i32 s90, 0, 0x1c000
	ds_read_b128 v[130:133], v150
	ds_read_b128 v[134:137], v150 offset:1024
	ds_read_b128 v[138:141], v150 offset:2048
	ds_read_b128 v[178:181], v150 offset:3072
	v_add_u32_e32 v150, s90, v153
	ds_read_b128 v[182:185], v150
	ds_read_b128 v[188:191], v150 offset:1024
	ds_read_b128 v[192:195], v150 offset:2048
	ds_read_b128 v[196:199], v150 offset:3072
	s_add_u32 s64, s64, 0x100000
	s_addc_u32 s65, s65, 0
	s_mov_b32 m0, s72
	ds_read_b128 v[200:203], v169 offset:32768
	ds_read_b128 v[204:207], v169 offset:33792
	ds_read_b128 v[208:211], v169 offset:34816
	ds_read_b128 v[212:215], v169 offset:35840
	ds_read_b128 v[216:219], v169 offset:36864
	ds_read_b128 v[220:223], v169 offset:37888
	ds_read_b128 v[224:227], v169 offset:38912
	ds_read_b128 v[228:231], v169 offset:39936
	global_load_lds_dwordx4 v142, s[64:65]
	s_mov_b32 m0, s73
	s_nop 0
	global_load_lds_dwordx4 v146, s[64:65]
	s_waitcnt vmcnt(8)
	s_waitcnt lgkmcnt(0)
	s_setprio 1
	s_barrier
	v_mfma_f32_16x16x32_bf16 v[126:129], v[130:133], v[200:203], v[126:129]
	v_mfma_f32_16x16x32_bf16 v[122:125], v[138:141], v[200:203], v[122:125]
	v_mfma_f32_16x16x32_bf16 v[110:113], v[130:133], v[208:211], v[110:113]
	v_mfma_f32_16x16x32_bf16 v[106:109], v[138:141], v[208:211], v[106:109]
	v_mfma_f32_16x16x32_bf16 v[94:97], v[130:133], v[216:219], v[94:97]
	v_mfma_f32_16x16x32_bf16 v[90:93], v[138:141], v[216:219], v[90:93]
	v_mfma_f32_16x16x32_bf16 v[78:81], v[130:133], v[224:227], v[78:81]
	v_mfma_f32_16x16x32_bf16 v[74:77], v[138:141], v[224:227], v[74:77]
	v_mfma_f32_16x16x32_bf16 v[126:129], v[134:137], v[204:207], v[126:129]
	v_mfma_f32_16x16x32_bf16 v[122:125], v[178:181], v[204:207], v[122:125]
	v_mfma_f32_16x16x32_bf16 v[110:113], v[134:137], v[212:215], v[110:113]
	v_mfma_f32_16x16x32_bf16 v[106:109], v[178:181], v[212:215], v[106:109]
	v_mfma_f32_16x16x32_bf16 v[94:97], v[134:137], v[220:223], v[94:97]
	v_mfma_f32_16x16x32_bf16 v[90:93], v[178:181], v[220:223], v[90:93]
	v_mfma_f32_16x16x32_bf16 v[78:81], v[134:137], v[228:231], v[78:81]
	v_mfma_f32_16x16x32_bf16 v[74:77], v[178:181], v[228:231], v[74:77]
	v_mfma_f32_16x16x32_bf16 v[118:121], v[182:185], v[200:203], v[118:121]
	v_mfma_f32_16x16x32_bf16 v[114:117], v[192:195], v[200:203], v[114:117]
	v_mfma_f32_16x16x32_bf16 v[102:105], v[182:185], v[208:211], v[102:105]
	v_mfma_f32_16x16x32_bf16 v[98:101], v[192:195], v[208:211], v[98:101]
	v_mfma_f32_16x16x32_bf16 v[86:89], v[182:185], v[216:219], v[86:89]
	v_mfma_f32_16x16x32_bf16 v[82:85], v[192:195], v[216:219], v[82:85]
	v_mfma_f32_16x16x32_bf16 v[70:73], v[182:185], v[224:227], v[70:73]
	v_mfma_f32_16x16x32_bf16 v[66:69], v[192:195], v[224:227], v[66:69]
	v_mfma_f32_16x16x32_bf16 v[118:121], v[188:191], v[204:207], v[118:121]
	v_mfma_f32_16x16x32_bf16 v[114:117], v[196:199], v[204:207], v[114:117]
	v_mfma_f32_16x16x32_bf16 v[102:105], v[188:191], v[212:215], v[102:105]
	v_mfma_f32_16x16x32_bf16 v[98:101], v[196:199], v[212:215], v[98:101]
	v_mfma_f32_16x16x32_bf16 v[86:89], v[188:191], v[220:223], v[86:89]
	v_mfma_f32_16x16x32_bf16 v[82:85], v[196:199], v[220:223], v[82:85]
	v_mfma_f32_16x16x32_bf16 v[70:73], v[188:191], v[228:231], v[70:73]
	v_mfma_f32_16x16x32_bf16 v[66:69], v[196:199], v[228:231], v[66:69]
	s_barrier
	s_setprio 0
	s_add_i32 s41, s41, s70
	v_lshl_add_u64 v[164:165], v[164:165], 0, s[26:27]
	s_mov_b32 m0, s41
	ds_read_b128 v[200:203], v169 offset:49152
	ds_read_b128 v[204:207], v169 offset:50176
	ds_read_b128 v[208:211], v169 offset:51200
	ds_read_b128 v[212:215], v169 offset:52224
	ds_read_b128 v[216:219], v169 offset:53248
	ds_read_b128 v[220:223], v169 offset:54272
	ds_read_b128 v[224:227], v169 offset:55296
	ds_read_b128 v[228:231], v169 offset:56320
	global_load_lds_dwordx4 v[164:165], off
	s_add_i32 m0, s41, 0x2000
	s_add_u32 s62, s62, 0x100080
	v_lshl_add_u64 v[164:165], v[232:233], 0, s[26:27]
	s_addc_u32 s63, s63, 0
	s_add_i32 s41, s90, s70
	global_load_lds_dwordx4 v[164:165], off
	s_mov_b32 m0, s41
	s_nop 0
	global_load_lds_dwordx4 v144, s[62:63]
	s_add_i32 m0, s41, 0x2000
	s_nop 0
	global_load_lds_dwordx4 v148, s[62:63]
	v_lshl_add_u64 v[164:165], v[234:235], 0, s[26:27]
	s_mov_b32 m0, s77
	s_nop 0
	global_load_lds_dwordx4 v[164:165], off
	v_lshl_add_u64 v[164:165], v[236:237], 0, s[26:27]
	s_mov_b32 m0, s78
	s_nop 0
	global_load_lds_dwordx4 v[164:165], off
	s_add_i32 s39, s39, 2
	s_add_u32 s9, s9, 0x100
	s_addc_u32 s10, s10, 0
	s_add_u32 s60, s60, 0x100
	s_addc_u32 s61, s61, 0
	s_cmp_gt_u32 s39, 61
	s_waitcnt vmcnt(8)
	s_waitcnt lgkmcnt(0)
	s_setprio 1
	s_barrier
	v_mfma_f32_16x16x32_bf16 v[62:65], v[130:133], v[200:203], v[62:65]
	v_mfma_f32_16x16x32_bf16 v[58:61], v[138:141], v[200:203], v[58:61]
	v_mfma_f32_16x16x32_bf16 v[46:49], v[130:133], v[208:211], v[46:49]
	v_mfma_f32_16x16x32_bf16 v[42:45], v[138:141], v[208:211], v[42:45]
	v_mfma_f32_16x16x32_bf16 v[30:33], v[130:133], v[216:219], v[30:33]
	v_mfma_f32_16x16x32_bf16 v[26:29], v[138:141], v[216:219], v[26:29]
	v_mfma_f32_16x16x32_bf16 v[14:17], v[130:133], v[224:227], v[14:17]
	v_mfma_f32_16x16x32_bf16 v[10:13], v[138:141], v[224:227], v[10:13]
	v_mfma_f32_16x16x32_bf16 v[62:65], v[134:137], v[204:207], v[62:65]
	v_mfma_f32_16x16x32_bf16 v[58:61], v[178:181], v[204:207], v[58:61]
	v_mfma_f32_16x16x32_bf16 v[46:49], v[134:137], v[212:215], v[46:49]
	v_mfma_f32_16x16x32_bf16 v[42:45], v[178:181], v[212:215], v[42:45]
	v_mfma_f32_16x16x32_bf16 v[30:33], v[134:137], v[220:223], v[30:33]
	v_mfma_f32_16x16x32_bf16 v[26:29], v[178:181], v[220:223], v[26:29]
	v_mfma_f32_16x16x32_bf16 v[14:17], v[134:137], v[228:231], v[14:17]
	v_mfma_f32_16x16x32_bf16 v[10:13], v[178:181], v[228:231], v[10:13]
	v_mfma_f32_16x16x32_bf16 v[54:57], v[182:185], v[200:203], v[54:57]
	v_mfma_f32_16x16x32_bf16 v[50:53], v[192:195], v[200:203], v[50:53]
	v_mfma_f32_16x16x32_bf16 v[38:41], v[182:185], v[208:211], v[38:41]
	v_mfma_f32_16x16x32_bf16 v[34:37], v[192:195], v[208:211], v[34:37]
	v_mfma_f32_16x16x32_bf16 v[22:25], v[182:185], v[216:219], v[22:25]
	v_mfma_f32_16x16x32_bf16 v[18:21], v[192:195], v[216:219], v[18:21]
	v_mfma_f32_16x16x32_bf16 v[6:9], v[182:185], v[224:227], v[6:9]
	v_mfma_f32_16x16x32_bf16 v[2:5], v[192:195], v[224:227], v[2:5]
	v_mfma_f32_16x16x32_bf16 v[54:57], v[188:191], v[204:207], v[54:57]
	v_mfma_f32_16x16x32_bf16 v[50:53], v[196:199], v[204:207], v[50:53]
	v_mfma_f32_16x16x32_bf16 v[38:41], v[188:191], v[212:215], v[38:41]
	v_mfma_f32_16x16x32_bf16 v[34:37], v[196:199], v[212:215], v[34:37]
	v_mfma_f32_16x16x32_bf16 v[22:25], v[188:191], v[220:223], v[22:25]
	v_mfma_f32_16x16x32_bf16 v[18:21], v[196:199], v[220:223], v[18:21]
	v_mfma_f32_16x16x32_bf16 v[6:9], v[188:191], v[228:231], v[6:9]
	v_mfma_f32_16x16x32_bf16 v[2:5], v[196:199], v[228:231], v[2:5]
	s_cbranch_scc1 .Ltb0_e
	s_barrier
	s_setprio 0
	s_branch .LBB0_402
.Ltb0_e:
	s_setprio 0
	s_and_b64 vcc, exec, s[28:29]
	s_cbranch_vccz .LBB0_405
	s_barrier

.Ltb0_x:
	s_barrier
	s_branch .LBB0_391

.LBB0_697:
	s_waitcnt lgkmcnt(0)
	ds_read_b128 v[2:5], v188
	ds_read_b128 v[6:9], v188 offset:1024
	s_waitcnt vmcnt(0)
	ds_read_b128 v[138:141], v188 offset:2048
	ds_read_b128 v[142:145], v188 offset:3072
	ds_read_b128 v[146:149], v189
	ds_read_b128 v[150:153], v189 offset:1024
	ds_read_b128 v[172:175], v189 offset:2048
	ds_read_b128 v[176:179], v189 offset:3072
	s_add_u32 s38, s36, 0xfff80080
	s_addc_u32 s39, s37, -1
	s_cmp_eq_u32 s72, 28
	s_cselect_b32 s41, s29, s39
	s_cselect_b32 s40, s68, s38
	s_cselect_b32 s39, s27, s71
	s_cselect_b32 s38, s69, s70
	s_add_i32 m0, s9, 0xc000
	ds_read_b128 v[192:195], v190
	ds_read_b128 v[196:199], v190 offset:1024
	ds_read_b128 v[200:203], v190 offset:2048
	ds_read_b128 v[204:207], v190 offset:3072
	ds_read_b128 v[208:211], v190 offset:4096
	ds_read_b128 v[212:215], v190 offset:5120
	ds_read_b128 v[216:219], v190 offset:6144
	ds_read_b128 v[220:223], v190 offset:7168
	global_load_lds_dwordx4 v166, s[36:37]
	s_add_i32 m0, s9, 0xe000
	s_nop 0
	global_load_lds_dwordx4 v164, s[36:37]
	s_waitcnt vmcnt(8)
	s_waitcnt lgkmcnt(0)
	s_setprio 1
	s_barrier
	v_mfma_i32_16x16x64_i8 v[134:137], v[2:5], v[192:195], v[134:137]
	v_mfma_i32_16x16x64_i8 v[130:133], v[138:141], v[192:195], v[130:133]
	v_mfma_i32_16x16x64_i8 v[118:121], v[2:5], v[200:203], v[118:121]
	v_mfma_i32_16x16x64_i8 v[114:117], v[138:141], v[200:203], v[114:117]
	v_mfma_i32_16x16x64_i8 v[102:105], v[2:5], v[208:211], v[102:105]
	v_mfma_i32_16x16x64_i8 v[98:101], v[138:141], v[208:211], v[98:101]
	v_mfma_i32_16x16x64_i8 v[86:89], v[2:5], v[216:219], v[86:89]
	v_mfma_i32_16x16x64_i8 v[82:85], v[138:141], v[216:219], v[82:85]
	v_mfma_i32_16x16x64_i8 v[134:137], v[6:9], v[196:199], v[134:137]
	v_mfma_i32_16x16x64_i8 v[130:133], v[142:145], v[196:199], v[130:133]
	v_mfma_i32_16x16x64_i8 v[118:121], v[6:9], v[204:207], v[118:121]
	v_mfma_i32_16x16x64_i8 v[114:117], v[142:145], v[204:207], v[114:117]
	v_mfma_i32_16x16x64_i8 v[102:105], v[6:9], v[212:215], v[102:105]
	v_mfma_i32_16x16x64_i8 v[98:101], v[142:145], v[212:215], v[98:101]
	v_mfma_i32_16x16x64_i8 v[86:89], v[6:9], v[220:223], v[86:89]
	v_mfma_i32_16x16x64_i8 v[82:85], v[142:145], v[220:223], v[82:85]
	v_mfma_i32_16x16x64_i8 v[126:129], v[146:149], v[192:195], v[126:129]
	v_mfma_i32_16x16x64_i8 v[122:125], v[172:175], v[192:195], v[122:125]
	v_mfma_i32_16x16x64_i8 v[110:113], v[146:149], v[200:203], v[110:113]
	v_mfma_i32_16x16x64_i8 v[106:109], v[172:175], v[200:203], v[106:109]
	v_mfma_i32_16x16x64_i8 v[94:97], v[146:149], v[208:211], v[94:97]
	v_mfma_i32_16x16x64_i8 v[90:93], v[172:175], v[208:211], v[90:93]
	v_mfma_i32_16x16x64_i8 v[78:81], v[146:149], v[216:219], v[78:81]
	v_mfma_i32_16x16x64_i8 v[74:77], v[172:175], v[216:219], v[74:77]
	v_mfma_i32_16x16x64_i8 v[126:129], v[150:153], v[196:199], v[126:129]
	v_mfma_i32_16x16x64_i8 v[122:125], v[176:179], v[196:199], v[122:125]
	v_mfma_i32_16x16x64_i8 v[110:113], v[150:153], v[204:207], v[110:113]
	v_mfma_i32_16x16x64_i8 v[106:109], v[176:179], v[204:207], v[106:109]
	v_mfma_i32_16x16x64_i8 v[94:97], v[150:153], v[212:215], v[94:97]
	v_mfma_i32_16x16x64_i8 v[90:93], v[176:179], v[212:215], v[90:93]
	v_mfma_i32_16x16x64_i8 v[78:81], v[150:153], v[220:223], v[78:81]
	v_mfma_i32_16x16x64_i8 v[74:77], v[176:179], v[220:223], v[74:77]
	s_barrier
	s_setprio 0
	s_add_i32 s73, s65, s44
	v_lshl_add_u64 v[180:181], s[38:39], 0, v[158:159]
	s_mov_b32 m0, s73
	ds_read_b128 v[192:195], v190 offset:16384
	ds_read_b128 v[196:199], v190 offset:17408
	ds_read_b128 v[200:203], v190 offset:18432
	ds_read_b128 v[204:207], v190 offset:19456
	ds_read_b128 v[208:211], v190 offset:20480
	ds_read_b128 v[212:215], v190 offset:21504
	ds_read_b128 v[216:219], v190 offset:22528
	ds_read_b128 v[220:223], v190 offset:23552
	global_load_lds_dwordx4 v[180:181], off
	s_add_i32 m0, s73, 0x2000
	s_add_u32 s76, s38, 0x80000
	v_lshl_add_u64 v[224:225], s[38:39], 0, v[154:155]
	s_addc_u32 s77, s39, 0
	s_add_i32 s73, s66, s44
	global_load_lds_dwordx4 v[224:225], off
	s_mov_b32 m0, s73
	v_lshl_add_u64 v[228:229], s[40:41], 0, v[156:157]
	global_load_lds_dwordx4 v158, s[76:77]
	s_add_i32 m0, s73, 0x2000
	s_nop 0
	global_load_lds_dwordx4 v154, s[76:77]
	v_lshl_add_u64 v[226:227], s[40:41], 0, v[160:161]
	s_mov_b32 m0, s9
	s_nop 0
	global_load_lds_dwordx4 v[226:227], off
	s_mov_b32 m0, s47
	s_nop 0
	global_load_lds_dwordx4 v[228:229], off
	s_waitcnt vmcnt(8)
	s_waitcnt lgkmcnt(0)
	s_setprio 1
	s_barrier
	v_mfma_i32_16x16x64_i8 v[70:73], v[2:5], v[192:195], v[70:73]
	v_mfma_i32_16x16x64_i8 v[66:69], v[138:141], v[192:195], v[66:69]
	v_mfma_i32_16x16x64_i8 v[54:57], v[2:5], v[200:203], v[54:57]
	v_mfma_i32_16x16x64_i8 v[50:53], v[138:141], v[200:203], v[50:53]
	v_mfma_i32_16x16x64_i8 v[38:41], v[2:5], v[208:211], v[38:41]
	v_mfma_i32_16x16x64_i8 v[34:37], v[138:141], v[208:211], v[34:37]
	v_mfma_i32_16x16x64_i8 v[2:5], v[2:5], v[216:219], v[22:25]
	v_mfma_i32_16x16x64_i8 v[70:73], v[6:9], v[196:199], v[70:73]
	v_mfma_i32_16x16x64_i8 v[66:69], v[142:145], v[196:199], v[66:69]
	v_mfma_i32_16x16x64_i8 v[54:57], v[6:9], v[204:207], v[54:57]
	v_mfma_i32_16x16x64_i8 v[50:53], v[142:145], v[204:207], v[50:53]
	v_mfma_i32_16x16x64_i8 v[38:41], v[6:9], v[212:215], v[38:41]
	v_mfma_i32_16x16x64_i8 v[34:37], v[142:145], v[212:215], v[34:37]
	v_mfma_i32_16x16x64_i8 v[2:5], v[6:9], v[220:223], v[2:5]
	v_mfma_i32_16x16x64_i8 v[6:9], v[138:141], v[216:219], v[18:21]
	v_mfma_i32_16x16x64_i8 v[6:9], v[142:145], v[220:223], v[6:9]
	v_mfma_i32_16x16x64_i8 v[18:21], v[146:149], v[192:195], v[62:65]
	v_mfma_i32_16x16x64_i8 v[62:65], v[150:153], v[196:199], v[18:21]
	v_mfma_i32_16x16x64_i8 v[18:21], v[172:175], v[192:195], v[58:61]
	v_mfma_i32_16x16x64_i8 v[58:61], v[176:179], v[196:199], v[18:21]
	v_mfma_i32_16x16x64_i8 v[18:21], v[146:149], v[200:203], v[46:49]
	v_mfma_i32_16x16x64_i8 v[46:49], v[150:153], v[204:207], v[18:21]
	v_mfma_i32_16x16x64_i8 v[18:21], v[172:175], v[200:203], v[42:45]
	v_mfma_i32_16x16x64_i8 v[42:45], v[176:179], v[204:207], v[18:21]
	v_mfma_i32_16x16x64_i8 v[18:21], v[146:149], v[208:211], v[30:33]
	v_mfma_i32_16x16x64_i8 v[30:33], v[150:153], v[212:215], v[18:21]
	v_mfma_i32_16x16x64_i8 v[18:21], v[172:175], v[208:211], v[26:29]
	v_mfma_i32_16x16x64_i8 v[14:17], v[146:149], v[216:219], v[14:17]
	v_mfma_i32_16x16x64_i8 v[10:13], v[172:175], v[216:219], v[10:13]
	v_mfma_i32_16x16x64_i8 v[26:29], v[176:179], v[212:215], v[18:21]
	v_mfma_i32_16x16x64_i8 v[14:17], v[150:153], v[220:223], v[14:17]
	v_mfma_i32_16x16x64_i8 v[10:13], v[176:179], v[220:223], v[10:13]
	s_barrier
	s_setprio 0
	s_add_i32 s73, 0, 0x18000
	s_add_i32 s75, 0, 0x1c000
	v_add_u32_e32 v142, s73, v182
	v_add_u32_e32 v162, s75, v182
	ds_read_b128 v[18:21], v142
	ds_read_b128 v[22:25], v142 offset:1024
	ds_read_b128 v[138:141], v142 offset:2048
	ds_read_b128 v[142:145], v142 offset:3072
	ds_read_b128 v[146:149], v162
	ds_read_b128 v[150:153], v162 offset:1024
	ds_read_b128 v[172:175], v162 offset:2048
	ds_read_b128 v[176:179], v162 offset:3072
	s_add_u32 s40, s40, 0x80000
	s_addc_u32 s41, s41, 0
	s_mov_b32 m0, s49
	ds_read_b128 v[192:195], v190 offset:32768
	ds_read_b128 v[196:199], v190 offset:33792
	ds_read_b128 v[200:203], v190 offset:34816
	ds_read_b128 v[204:207], v190 offset:35840
	ds_read_b128 v[208:211], v190 offset:36864
	ds_read_b128 v[212:215], v190 offset:37888
	ds_read_b128 v[216:219], v190 offset:38912
	ds_read_b128 v[220:223], v190 offset:39936
	global_load_lds_dwordx4 v160, s[40:41]
	s_mov_b32 m0, s60
	s_nop 0
	global_load_lds_dwordx4 v156, s[40:41]
	s_waitcnt vmcnt(8)
	s_waitcnt lgkmcnt(0)
	s_setprio 1
	s_barrier
	v_mfma_i32_16x16x64_i8 v[134:137], v[18:21], v[192:195], v[134:137]
	v_mfma_i32_16x16x64_i8 v[130:133], v[138:141], v[192:195], v[130:133]
	v_mfma_i32_16x16x64_i8 v[118:121], v[18:21], v[200:203], v[118:121]
	v_mfma_i32_16x16x64_i8 v[114:117], v[138:141], v[200:203], v[114:117]
	v_mfma_i32_16x16x64_i8 v[102:105], v[18:21], v[208:211], v[102:105]
	v_mfma_i32_16x16x64_i8 v[98:101], v[138:141], v[208:211], v[98:101]
	v_mfma_i32_16x16x64_i8 v[86:89], v[18:21], v[216:219], v[86:89]
	v_mfma_i32_16x16x64_i8 v[82:85], v[138:141], v[216:219], v[82:85]
	v_mfma_i32_16x16x64_i8 v[134:137], v[22:25], v[196:199], v[134:137]
	v_mfma_i32_16x16x64_i8 v[130:133], v[142:145], v[196:199], v[130:133]
	v_mfma_i32_16x16x64_i8 v[118:121], v[22:25], v[204:207], v[118:121]
	v_mfma_i32_16x16x64_i8 v[114:117], v[142:145], v[204:207], v[114:117]
	v_mfma_i32_16x16x64_i8 v[102:105], v[22:25], v[212:215], v[102:105]
	v_mfma_i32_16x16x64_i8 v[98:101], v[142:145], v[212:215], v[98:101]
	v_mfma_i32_16x16x64_i8 v[86:89], v[22:25], v[220:223], v[86:89]
	v_mfma_i32_16x16x64_i8 v[82:85], v[142:145], v[220:223], v[82:85]
	v_mfma_i32_16x16x64_i8 v[126:129], v[146:149], v[192:195], v[126:129]
	v_mfma_i32_16x16x64_i8 v[122:125], v[172:175], v[192:195], v[122:125]
	v_mfma_i32_16x16x64_i8 v[110:113], v[146:149], v[200:203], v[110:113]
	v_mfma_i32_16x16x64_i8 v[106:109], v[172:175], v[200:203], v[106:109]
	v_mfma_i32_16x16x64_i8 v[94:97], v[146:149], v[208:211], v[94:97]
	v_mfma_i32_16x16x64_i8 v[90:93], v[172:175], v[208:211], v[90:93]
	v_mfma_i32_16x16x64_i8 v[78:81], v[146:149], v[216:219], v[78:81]
	v_mfma_i32_16x16x64_i8 v[74:77], v[172:175], v[216:219], v[74:77]
	v_mfma_i32_16x16x64_i8 v[126:129], v[150:153], v[196:199], v[126:129]
	v_mfma_i32_16x16x64_i8 v[122:125], v[176:179], v[196:199], v[122:125]
	v_mfma_i32_16x16x64_i8 v[110:113], v[150:153], v[204:207], v[110:113]
	v_mfma_i32_16x16x64_i8 v[106:109], v[176:179], v[204:207], v[106:109]
	v_mfma_i32_16x16x64_i8 v[94:97], v[150:153], v[212:215], v[94:97]
	v_mfma_i32_16x16x64_i8 v[90:93], v[176:179], v[212:215], v[90:93]
	v_mfma_i32_16x16x64_i8 v[78:81], v[150:153], v[220:223], v[78:81]
	v_mfma_i32_16x16x64_i8 v[74:77], v[176:179], v[220:223], v[74:77]
	s_barrier
	s_setprio 0
	s_add_i32 s40, s73, s44
	v_lshl_add_u64 v[180:181], v[180:181], 0, s[20:21]
	s_mov_b32 m0, s40
	ds_read_b128 v[192:195], v190 offset:49152
	ds_read_b128 v[196:199], v190 offset:50176
	ds_read_b128 v[200:203], v190 offset:51200
	ds_read_b128 v[204:207], v190 offset:52224
	ds_read_b128 v[208:211], v190 offset:53248
	ds_read_b128 v[212:215], v190 offset:54272
	ds_read_b128 v[216:219], v190 offset:55296
	ds_read_b128 v[220:223], v190 offset:56320
	global_load_lds_dwordx4 v[180:181], off
	s_add_i32 m0, s40, 0x2000
	s_add_u32 s38, s38, 0x80080
	v_lshl_add_u64 v[180:181], v[224:225], 0, s[20:21]
	s_addc_u32 s39, s39, 0
	s_add_i32 s40, s75, s44
	global_load_lds_dwordx4 v[180:181], off
	s_mov_b32 m0, s40
	s_nop 0
	global_load_lds_dwordx4 v158, s[38:39]
	s_add_i32 m0, s40, 0x2000
	s_nop 0
	global_load_lds_dwordx4 v154, s[38:39]
	v_lshl_add_u64 v[180:181], v[226:227], 0, s[20:21]
	s_mov_b32 m0, s62
	s_nop 0
	global_load_lds_dwordx4 v[180:181], off
	v_lshl_add_u64 v[180:181], v[228:229], 0, s[20:21]
	s_mov_b32 m0, s63
	s_nop 0
	global_load_lds_dwordx4 v[180:181], off
	s_add_i32 s72, s72, 2
	s_add_u32 s70, s70, 0x100
	s_addc_u32 s71, s71, 0
	s_add_u32 s36, s36, 0x100
	s_addc_u32 s37, s37, 0
	s_cmp_gt_u32 s72, 29
	s_waitcnt vmcnt(8)
	s_waitcnt lgkmcnt(0)
	s_setprio 1
	s_barrier
	v_mfma_i32_16x16x64_i8 v[70:73], v[18:21], v[192:195], v[70:73]
	v_mfma_i32_16x16x64_i8 v[54:57], v[18:21], v[200:203], v[54:57]
	v_mfma_i32_16x16x64_i8 v[38:41], v[18:21], v[208:211], v[38:41]
	v_mfma_i32_16x16x64_i8 v[2:5], v[18:21], v[216:219], v[2:5]
	v_mfma_i32_16x16x64_i8 v[70:73], v[22:25], v[196:199], v[70:73]
	v_mfma_i32_16x16x64_i8 v[66:69], v[138:141], v[192:195], v[66:69]
	v_mfma_i32_16x16x64_i8 v[54:57], v[22:25], v[204:207], v[54:57]
	v_mfma_i32_16x16x64_i8 v[50:53], v[138:141], v[200:203], v[50:53]
	v_mfma_i32_16x16x64_i8 v[38:41], v[22:25], v[212:215], v[38:41]
	v_mfma_i32_16x16x64_i8 v[34:37], v[138:141], v[208:211], v[34:37]
	v_mfma_i32_16x16x64_i8 v[22:25], v[22:25], v[220:223], v[2:5]
	v_mfma_i32_16x16x64_i8 v[2:5], v[138:141], v[216:219], v[6:9]
	v_mfma_i32_16x16x64_i8 v[66:69], v[142:145], v[196:199], v[66:69]
	v_mfma_i32_16x16x64_i8 v[50:53], v[142:145], v[204:207], v[50:53]
	v_mfma_i32_16x16x64_i8 v[34:37], v[142:145], v[212:215], v[34:37]
	v_mfma_i32_16x16x64_i8 v[18:21], v[142:145], v[220:223], v[2:5]
	v_mfma_i32_16x16x64_i8 v[2:5], v[146:149], v[192:195], v[62:65]
	v_mfma_i32_16x16x64_i8 v[62:65], v[150:153], v[196:199], v[2:5]
	v_mfma_i32_16x16x64_i8 v[2:5], v[172:175], v[192:195], v[58:61]
	v_mfma_i32_16x16x64_i8 v[58:61], v[176:179], v[196:199], v[2:5]
	v_mfma_i32_16x16x64_i8 v[2:5], v[146:149], v[200:203], v[46:49]
	v_mfma_i32_16x16x64_i8 v[46:49], v[150:153], v[204:207], v[2:5]
	v_mfma_i32_16x16x64_i8 v[2:5], v[172:175], v[200:203], v[42:45]
	v_mfma_i32_16x16x64_i8 v[42:45], v[176:179], v[204:207], v[2:5]
	v_mfma_i32_16x16x64_i8 v[2:5], v[146:149], v[208:211], v[30:33]
	v_mfma_i32_16x16x64_i8 v[30:33], v[150:153], v[212:215], v[2:5]
	v_mfma_i32_16x16x64_i8 v[2:5], v[172:175], v[208:211], v[26:29]
	v_mfma_i32_16x16x64_i8 v[26:29], v[176:179], v[212:215], v[2:5]
	v_mfma_i32_16x16x64_i8 v[2:5], v[146:149], v[216:219], v[14:17]
	v_mfma_i32_16x16x64_i8 v[14:17], v[150:153], v[220:223], v[2:5]
	v_mfma_i32_16x16x64_i8 v[2:5], v[172:175], v[216:219], v[10:13]
	v_mfma_i32_16x16x64_i8 v[10:13], v[176:179], v[220:223], v[2:5]
	s_cbranch_scc1 .Ltb1_e
	s_barrier
	s_setprio 0
	s_branch .LBB0_697
.Ltb1_e:
	s_setprio 0
	s_and_b64 vcc, exec, s[22:23]
	s_cbranch_vccz .LBB0_700
	s_barrier

.LBB0_790:
	ds_read_b128 v[164:167], v1
	ds_read_b128 v[168:171], v1 offset:1024
	ds_read_b128 v[172:175], v1 offset:2048
	ds_read_b128 v[176:179], v1 offset:3072
	ds_read_b128 v[180:183], v143
	ds_read_b128 v[188:191], v143 offset:1024
	ds_read_b128 v[192:195], v143 offset:2048
	ds_read_b128 v[196:199], v143 offset:3072
	s_add_u32 s26, s24, 0xfff00080
	s_addc_u32 s27, s25, -1
	s_cmp_eq_u32 s77, 12
	s_cselect_b32 s29, s21, s27
	s_cselect_b32 s28, s20, s26
	s_cselect_b32 s27, s9, s76
	s_cselect_b32 s26, s8, s75
	s_mov_b32 m0, s61
	ds_read_b128 v[200:203], v141
	ds_read_b128 v[204:207], v141 offset:1024
	ds_read_b128 v[208:211], v141 offset:2048
	ds_read_b128 v[212:215], v141 offset:3072
	ds_read_b128 v[216:219], v141 offset:4096
	ds_read_b128 v[220:223], v141 offset:5120
	ds_read_b128 v[224:227], v141 offset:6144
	ds_read_b128 v[228:231], v141 offset:7168
	global_load_lds_dwordx4 v158, s[24:25]
	s_mov_b32 m0, s62
	s_nop 0
	global_load_lds_dwordx4 v156, s[24:25]
	s_waitcnt vmcnt(8)
	s_waitcnt lgkmcnt(0)
	s_setprio 1
	s_barrier
	v_mfma_f32_16x16x32_bf16 v[126:129], v[164:167], v[200:203], v[126:129]
	v_mfma_f32_16x16x32_bf16 v[122:125], v[172:175], v[200:203], v[122:125]
	v_mfma_f32_16x16x32_bf16 v[118:121], v[164:167], v[208:211], v[118:121]
	v_mfma_f32_16x16x32_bf16 v[110:113], v[172:175], v[208:211], v[110:113]
	v_mfma_f32_16x16x32_bf16 v[102:105], v[164:167], v[216:219], v[102:105]
	v_mfma_f32_16x16x32_bf16 v[94:97], v[172:175], v[216:219], v[94:97]
	v_mfma_f32_16x16x32_bf16 v[86:89], v[164:167], v[224:227], v[86:89]
	v_mfma_f32_16x16x32_bf16 v[78:81], v[172:175], v[224:227], v[78:81]
	v_mfma_f32_16x16x32_bf16 v[126:129], v[168:171], v[204:207], v[126:129]
	v_mfma_f32_16x16x32_bf16 v[122:125], v[176:179], v[204:207], v[122:125]
	v_mfma_f32_16x16x32_bf16 v[118:121], v[168:171], v[212:215], v[118:121]
	v_mfma_f32_16x16x32_bf16 v[110:113], v[176:179], v[212:215], v[110:113]
	v_mfma_f32_16x16x32_bf16 v[102:105], v[168:171], v[220:223], v[102:105]
	v_mfma_f32_16x16x32_bf16 v[94:97], v[176:179], v[220:223], v[94:97]
	v_mfma_f32_16x16x32_bf16 v[86:89], v[168:171], v[228:231], v[86:89]
	v_mfma_f32_16x16x32_bf16 v[78:81], v[176:179], v[228:231], v[78:81]
	v_mfma_f32_16x16x32_bf16 v[114:117], v[180:183], v[200:203], v[114:117]
	v_mfma_f32_16x16x32_bf16 v[106:109], v[192:195], v[200:203], v[106:109]
	v_mfma_f32_16x16x32_bf16 v[98:101], v[180:183], v[208:211], v[98:101]
	v_mfma_f32_16x16x32_bf16 v[90:93], v[192:195], v[208:211], v[90:93]
	v_mfma_f32_16x16x32_bf16 v[82:85], v[180:183], v[216:219], v[82:85]
	v_mfma_f32_16x16x32_bf16 v[74:77], v[192:195], v[216:219], v[74:77]
	v_mfma_f32_16x16x32_bf16 v[70:73], v[180:183], v[224:227], v[70:73]
	v_mfma_f32_16x16x32_bf16 v[66:69], v[192:195], v[224:227], v[66:69]
	v_mfma_f32_16x16x32_bf16 v[114:117], v[188:191], v[204:207], v[114:117]
	v_mfma_f32_16x16x32_bf16 v[106:109], v[196:199], v[204:207], v[106:109]
	v_mfma_f32_16x16x32_bf16 v[98:101], v[188:191], v[212:215], v[98:101]
	v_mfma_f32_16x16x32_bf16 v[90:93], v[196:199], v[212:215], v[90:93]
	v_mfma_f32_16x16x32_bf16 v[82:85], v[188:191], v[220:223], v[82:85]
	v_mfma_f32_16x16x32_bf16 v[74:77], v[196:199], v[220:223], v[74:77]
	v_mfma_f32_16x16x32_bf16 v[70:73], v[188:191], v[228:231], v[70:73]
	v_mfma_f32_16x16x32_bf16 v[66:69], v[196:199], v[228:231], v[66:69]
	s_barrier
	s_setprio 0
	s_mov_b32 m0, s63
	v_lshl_add_u64 v[184:185], s[26:27], 0, v[134:135]
	s_add_u32 s78, s26, 0x100000
	ds_read_b128 v[200:203], v141 offset:16384
	ds_read_b128 v[204:207], v141 offset:17408
	ds_read_b128 v[208:211], v141 offset:18432
	ds_read_b128 v[212:215], v141 offset:19456
	ds_read_b128 v[216:219], v141 offset:20480
	ds_read_b128 v[220:223], v141 offset:21504
	ds_read_b128 v[224:227], v141 offset:22528
	ds_read_b128 v[228:231], v141 offset:23552
	global_load_lds_dwordx4 v[184:185], off
	v_lshl_add_u64 v[232:233], s[26:27], 0, v[130:131]
	s_mov_b32 m0, s64
	s_addc_u32 s79, s27, 0
	global_load_lds_dwordx4 v[232:233], off
	s_mov_b32 m0, s65
	v_lshl_add_u64 v[236:237], s[28:29], 0, v[132:133]
	global_load_lds_dwordx4 v134, s[78:79]
	s_mov_b32 m0, s66
	s_nop 0
	global_load_lds_dwordx4 v130, s[78:79]
	v_lshl_add_u64 v[234:235], s[28:29], 0, v[136:137]
	s_mov_b32 m0, s39
	s_nop 0
	global_load_lds_dwordx4 v[234:235], off
	s_mov_b32 m0, s40
	s_nop 0
	global_load_lds_dwordx4 v[236:237], off
	s_waitcnt vmcnt(8)
	s_waitcnt lgkmcnt(0)
	s_setprio 1
	s_barrier
	v_mfma_f32_16x16x32_bf16 v[62:65], v[164:167], v[200:203], v[62:65]
	v_mfma_f32_16x16x32_bf16 v[58:61], v[172:175], v[200:203], v[58:61]
	v_mfma_f32_16x16x32_bf16 v[54:57], v[164:167], v[208:211], v[54:57]
	v_mfma_f32_16x16x32_bf16 v[46:49], v[172:175], v[208:211], v[46:49]
	v_mfma_f32_16x16x32_bf16 v[38:41], v[164:167], v[216:219], v[38:41]
	v_mfma_f32_16x16x32_bf16 v[30:33], v[172:175], v[216:219], v[30:33]
	v_mfma_f32_16x16x32_bf16 v[22:25], v[164:167], v[224:227], v[22:25]
	v_mfma_f32_16x16x32_bf16 v[14:17], v[172:175], v[224:227], v[14:17]
	v_mfma_f32_16x16x32_bf16 v[62:65], v[168:171], v[204:207], v[62:65]
	v_mfma_f32_16x16x32_bf16 v[58:61], v[176:179], v[204:207], v[58:61]
	v_mfma_f32_16x16x32_bf16 v[54:57], v[168:171], v[212:215], v[54:57]
	v_mfma_f32_16x16x32_bf16 v[46:49], v[176:179], v[212:215], v[46:49]
	v_mfma_f32_16x16x32_bf16 v[38:41], v[168:171], v[220:223], v[38:41]
	v_mfma_f32_16x16x32_bf16 v[30:33], v[176:179], v[220:223], v[30:33]
	v_mfma_f32_16x16x32_bf16 v[22:25], v[168:171], v[228:231], v[22:25]
	v_mfma_f32_16x16x32_bf16 v[14:17], v[176:179], v[228:231], v[14:17]
	v_mfma_f32_16x16x32_bf16 v[50:53], v[180:183], v[200:203], v[50:53]
	v_mfma_f32_16x16x32_bf16 v[42:45], v[192:195], v[200:203], v[42:45]
	v_mfma_f32_16x16x32_bf16 v[34:37], v[180:183], v[208:211], v[34:37]
	v_mfma_f32_16x16x32_bf16 v[26:29], v[192:195], v[208:211], v[26:29]
	v_mfma_f32_16x16x32_bf16 v[18:21], v[180:183], v[216:219], v[18:21]
	v_mfma_f32_16x16x32_bf16 v[10:13], v[192:195], v[216:219], v[10:13]
	v_mfma_f32_16x16x32_bf16 v[6:9], v[180:183], v[224:227], v[6:9]
	v_mfma_f32_16x16x32_bf16 v[2:5], v[192:195], v[224:227], v[2:5]
	v_mfma_f32_16x16x32_bf16 v[50:53], v[188:191], v[204:207], v[50:53]
	v_mfma_f32_16x16x32_bf16 v[42:45], v[196:199], v[204:207], v[42:45]
	v_mfma_f32_16x16x32_bf16 v[34:37], v[188:191], v[212:215], v[34:37]
	v_mfma_f32_16x16x32_bf16 v[26:29], v[196:199], v[212:215], v[26:29]
	v_mfma_f32_16x16x32_bf16 v[18:21], v[188:191], v[220:223], v[18:21]
	v_mfma_f32_16x16x32_bf16 v[10:13], v[196:199], v[220:223], v[10:13]
	v_mfma_f32_16x16x32_bf16 v[6:9], v[188:191], v[228:231], v[6:9]
	v_mfma_f32_16x16x32_bf16 v[2:5], v[196:199], v[228:231], v[2:5]
	s_barrier
	s_setprio 0
	ds_read_b128 v[164:167], v145
	ds_read_b128 v[168:171], v145 offset:1024
	ds_read_b128 v[172:175], v145 offset:2048
	ds_read_b128 v[176:179], v145 offset:3072
	ds_read_b128 v[180:183], v147
	ds_read_b128 v[188:191], v147 offset:1024
	ds_read_b128 v[192:195], v147 offset:2048
	ds_read_b128 v[196:199], v147 offset:3072
	s_add_u32 s28, s28, 0x100000
	s_addc_u32 s29, s29, 0
	s_mov_b32 m0, s41
	ds_read_b128 v[200:203], v141 offset:32768
	ds_read_b128 v[204:207], v141 offset:33792
	ds_read_b128 v[208:211], v141 offset:34816
	ds_read_b128 v[212:215], v141 offset:35840
	ds_read_b128 v[216:219], v141 offset:36864
	ds_read_b128 v[220:223], v141 offset:37888
	ds_read_b128 v[224:227], v141 offset:38912
	ds_read_b128 v[228:231], v141 offset:39936
	global_load_lds_dwordx4 v136, s[28:29]
	s_mov_b32 m0, s42
	s_nop 0
	global_load_lds_dwordx4 v132, s[28:29]
	s_waitcnt vmcnt(8)
	s_waitcnt lgkmcnt(0)
	s_setprio 1
	s_barrier
	v_mfma_f32_16x16x32_bf16 v[126:129], v[164:167], v[200:203], v[126:129]
	v_mfma_f32_16x16x32_bf16 v[122:125], v[172:175], v[200:203], v[122:125]
	v_mfma_f32_16x16x32_bf16 v[118:121], v[164:167], v[208:211], v[118:121]
	v_mfma_f32_16x16x32_bf16 v[110:113], v[172:175], v[208:211], v[110:113]
	v_mfma_f32_16x16x32_bf16 v[102:105], v[164:167], v[216:219], v[102:105]
	v_mfma_f32_16x16x32_bf16 v[94:97], v[172:175], v[216:219], v[94:97]
	v_mfma_f32_16x16x32_bf16 v[86:89], v[164:167], v[224:227], v[86:89]
	v_mfma_f32_16x16x32_bf16 v[78:81], v[172:175], v[224:227], v[78:81]
	v_mfma_f32_16x16x32_bf16 v[126:129], v[168:171], v[204:207], v[126:129]
	v_mfma_f32_16x16x32_bf16 v[122:125], v[176:179], v[204:207], v[122:125]
	v_mfma_f32_16x16x32_bf16 v[118:121], v[168:171], v[212:215], v[118:121]
	v_mfma_f32_16x16x32_bf16 v[110:113], v[176:179], v[212:215], v[110:113]
	v_mfma_f32_16x16x32_bf16 v[102:105], v[168:171], v[220:223], v[102:105]
	v_mfma_f32_16x16x32_bf16 v[94:97], v[176:179], v[220:223], v[94:97]
	v_mfma_f32_16x16x32_bf16 v[86:89], v[168:171], v[228:231], v[86:89]
	v_mfma_f32_16x16x32_bf16 v[78:81], v[176:179], v[228:231], v[78:81]
	v_mfma_f32_16x16x32_bf16 v[114:117], v[180:183], v[200:203], v[114:117]
	v_mfma_f32_16x16x32_bf16 v[106:109], v[192:195], v[200:203], v[106:109]
	v_mfma_f32_16x16x32_bf16 v[98:101], v[180:183], v[208:211], v[98:101]
	v_mfma_f32_16x16x32_bf16 v[90:93], v[192:195], v[208:211], v[90:93]
	v_mfma_f32_16x16x32_bf16 v[82:85], v[180:183], v[216:219], v[82:85]
	v_mfma_f32_16x16x32_bf16 v[74:77], v[192:195], v[216:219], v[74:77]
	v_mfma_f32_16x16x32_bf16 v[70:73], v[180:183], v[224:227], v[70:73]
	v_mfma_f32_16x16x32_bf16 v[66:69], v[192:195], v[224:227], v[66:69]
	v_mfma_f32_16x16x32_bf16 v[114:117], v[188:191], v[204:207], v[114:117]
	v_mfma_f32_16x16x32_bf16 v[106:109], v[196:199], v[204:207], v[106:109]
	v_mfma_f32_16x16x32_bf16 v[98:101], v[188:191], v[212:215], v[98:101]
	v_mfma_f32_16x16x32_bf16 v[90:93], v[196:199], v[212:215], v[90:93]
	v_mfma_f32_16x16x32_bf16 v[82:85], v[188:191], v[220:223], v[82:85]
	v_mfma_f32_16x16x32_bf16 v[74:77], v[196:199], v[220:223], v[74:77]
	v_mfma_f32_16x16x32_bf16 v[70:73], v[188:191], v[228:231], v[70:73]
	v_mfma_f32_16x16x32_bf16 v[66:69], v[196:199], v[228:231], v[66:69]
	s_barrier
	s_setprio 0
	s_mov_b32 m0, s67
	v_lshl_add_u64 v[184:185], v[184:185], 0, s[12:13]
	s_add_u32 s26, s26, 0x100080
	ds_read_b128 v[200:203], v141 offset:49152
	ds_read_b128 v[204:207], v141 offset:50176
	ds_read_b128 v[208:211], v141 offset:51200
	ds_read_b128 v[212:215], v141 offset:52224
	ds_read_b128 v[216:219], v141 offset:53248
	ds_read_b128 v[220:223], v141 offset:54272
	ds_read_b128 v[224:227], v141 offset:55296
	ds_read_b128 v[228:231], v141 offset:56320
	global_load_lds_dwordx4 v[184:185], off
	v_lshl_add_u64 v[184:185], v[232:233], 0, s[12:13]
	s_mov_b32 m0, s68
	s_addc_u32 s27, s27, 0
	global_load_lds_dwordx4 v[184:185], off
	s_mov_b32 m0, s69
	s_nop 0
	global_load_lds_dwordx4 v134, s[26:27]
	s_add_i32 m0, s69, 0x2000
	s_nop 0
	global_load_lds_dwordx4 v130, s[26:27]
	v_lshl_add_u64 v[184:185], v[234:235], 0, s[12:13]
	s_mov_b32 m0, s49
	s_nop 0
	global_load_lds_dwordx4 v[184:185], off
	v_lshl_add_u64 v[184:185], v[236:237], 0, s[12:13]
	s_mov_b32 m0, s56
	s_nop 0
	global_load_lds_dwordx4 v[184:185], off
	s_add_i32 s77, s77, 2
	s_add_u32 s75, s75, 0x100
	s_addc_u32 s76, s76, 0
	s_add_u32 s24, s24, 0x100
	s_addc_u32 s25, s25, 0
	s_cmp_gt_u32 s77, 13
	s_waitcnt vmcnt(8)
	s_waitcnt lgkmcnt(0)
	s_setprio 1
	s_barrier
	v_mfma_f32_16x16x32_bf16 v[62:65], v[164:167], v[200:203], v[62:65]
	v_mfma_f32_16x16x32_bf16 v[58:61], v[172:175], v[200:203], v[58:61]
	v_mfma_f32_16x16x32_bf16 v[54:57], v[164:167], v[208:211], v[54:57]
	v_mfma_f32_16x16x32_bf16 v[46:49], v[172:175], v[208:211], v[46:49]
	v_mfma_f32_16x16x32_bf16 v[38:41], v[164:167], v[216:219], v[38:41]
	v_mfma_f32_16x16x32_bf16 v[30:33], v[172:175], v[216:219], v[30:33]
	v_mfma_f32_16x16x32_bf16 v[22:25], v[164:167], v[224:227], v[22:25]
	v_mfma_f32_16x16x32_bf16 v[14:17], v[172:175], v[224:227], v[14:17]
	v_mfma_f32_16x16x32_bf16 v[62:65], v[168:171], v[204:207], v[62:65]
	v_mfma_f32_16x16x32_bf16 v[58:61], v[176:179], v[204:207], v[58:61]
	v_mfma_f32_16x16x32_bf16 v[54:57], v[168:171], v[212:215], v[54:57]
	v_mfma_f32_16x16x32_bf16 v[46:49], v[176:179], v[212:215], v[46:49]
	v_mfma_f32_16x16x32_bf16 v[38:41], v[168:171], v[220:223], v[38:41]
	v_mfma_f32_16x16x32_bf16 v[30:33], v[176:179], v[220:223], v[30:33]
	v_mfma_f32_16x16x32_bf16 v[22:25], v[168:171], v[228:231], v[22:25]
	v_mfma_f32_16x16x32_bf16 v[14:17], v[176:179], v[228:231], v[14:17]
	v_mfma_f32_16x16x32_bf16 v[50:53], v[180:183], v[200:203], v[50:53]
	v_mfma_f32_16x16x32_bf16 v[42:45], v[192:195], v[200:203], v[42:45]
	v_mfma_f32_16x16x32_bf16 v[34:37], v[180:183], v[208:211], v[34:37]
	v_mfma_f32_16x16x32_bf16 v[26:29], v[192:195], v[208:211], v[26:29]
	v_mfma_f32_16x16x32_bf16 v[18:21], v[180:183], v[216:219], v[18:21]
	v_mfma_f32_16x16x32_bf16 v[10:13], v[192:195], v[216:219], v[10:13]
	v_mfma_f32_16x16x32_bf16 v[6:9], v[180:183], v[224:227], v[6:9]
	v_mfma_f32_16x16x32_bf16 v[2:5], v[192:195], v[224:227], v[2:5]
	v_mfma_f32_16x16x32_bf16 v[50:53], v[188:191], v[204:207], v[50:53]
	v_mfma_f32_16x16x32_bf16 v[42:45], v[196:199], v[204:207], v[42:45]
	v_mfma_f32_16x16x32_bf16 v[34:37], v[188:191], v[212:215], v[34:37]
	v_mfma_f32_16x16x32_bf16 v[26:29], v[196:199], v[212:215], v[26:29]
	v_mfma_f32_16x16x32_bf16 v[18:21], v[188:191], v[220:223], v[18:21]
	v_mfma_f32_16x16x32_bf16 v[10:13], v[196:199], v[220:223], v[10:13]
	v_mfma_f32_16x16x32_bf16 v[6:9], v[188:191], v[228:231], v[6:9]
	v_mfma_f32_16x16x32_bf16 v[2:5], v[196:199], v[228:231], v[2:5]
	s_cbranch_scc1 .Ltb2_e
	s_barrier
	s_setprio 0
	s_branch .LBB0_790
.Ltb2_e:
	s_setprio 0
	s_and_b64 vcc, exec, s[18:19]
	s_cbranch_vccz .LBB0_793
	s_barrier

.LBB0_1281:
	ds_read_b128 v[146:149], v152
	ds_read_b128 v[156:159], v152 offset:1024
	ds_read_b128 v[160:163], v152 offset:2048
	ds_read_b128 v[164:167], v152 offset:3072
	ds_read_b128 v[168:171], v153
	ds_read_b128 v[172:175], v153 offset:1024
	ds_read_b128 v[176:179], v153 offset:2048
	ds_read_b128 v[180:183], v153 offset:3072
	s_add_u32 s40, s38, 0xfff00080
	s_addc_u32 s41, s39, -1
	s_cmp_eq_u32 s72, 60
	s_cselect_b32 s43, s27, s41
	s_cselect_b32 s42, s35, s40
	s_cselect_b32 s41, s15, s71
	s_cselect_b32 s40, s37, s70
	s_add_i32 m0, s49, 0xc000
	ds_read_b128 v[188:191], v154
	ds_read_b128 v[192:195], v154 offset:1024
	ds_read_b128 v[196:199], v154 offset:2048
	ds_read_b128 v[200:203], v154 offset:3072
	ds_read_b128 v[204:207], v154 offset:4096
	ds_read_b128 v[208:211], v154 offset:5120
	ds_read_b128 v[212:215], v154 offset:6144
	ds_read_b128 v[216:219], v154 offset:7168
	global_load_lds_dwordx4 v140, s[38:39]
	s_add_i32 m0, s49, 0xe000
	s_nop 0
	global_load_lds_dwordx4 v138, s[38:39]
	s_waitcnt vmcnt(8)
	s_waitcnt lgkmcnt(0)
	s_setprio 1
	s_barrier
	v_mfma_f32_16x16x32_bf16 v[126:129], v[146:149], v[188:191], v[126:129]
	v_mfma_f32_16x16x32_bf16 v[122:125], v[160:163], v[188:191], v[122:125]
	v_mfma_f32_16x16x32_bf16 v[110:113], v[146:149], v[196:199], v[110:113]
	v_mfma_f32_16x16x32_bf16 v[106:109], v[160:163], v[196:199], v[106:109]
	v_mfma_f32_16x16x32_bf16 v[94:97], v[146:149], v[204:207], v[94:97]
	v_mfma_f32_16x16x32_bf16 v[90:93], v[160:163], v[204:207], v[90:93]
	v_mfma_f32_16x16x32_bf16 v[78:81], v[146:149], v[212:215], v[78:81]
	v_mfma_f32_16x16x32_bf16 v[74:77], v[160:163], v[212:215], v[74:77]
	v_mfma_f32_16x16x32_bf16 v[126:129], v[156:159], v[192:195], v[126:129]
	v_mfma_f32_16x16x32_bf16 v[122:125], v[164:167], v[192:195], v[122:125]
	v_mfma_f32_16x16x32_bf16 v[110:113], v[156:159], v[200:203], v[110:113]
	v_mfma_f32_16x16x32_bf16 v[106:109], v[164:167], v[200:203], v[106:109]
	v_mfma_f32_16x16x32_bf16 v[94:97], v[156:159], v[208:211], v[94:97]
	v_mfma_f32_16x16x32_bf16 v[90:93], v[164:167], v[208:211], v[90:93]
	v_mfma_f32_16x16x32_bf16 v[78:81], v[156:159], v[216:219], v[78:81]
	v_mfma_f32_16x16x32_bf16 v[74:77], v[164:167], v[216:219], v[74:77]
	v_mfma_f32_16x16x32_bf16 v[118:121], v[168:171], v[188:191], v[118:121]
	v_mfma_f32_16x16x32_bf16 v[114:117], v[176:179], v[188:191], v[114:117]
	v_mfma_f32_16x16x32_bf16 v[102:105], v[168:171], v[196:199], v[102:105]
	v_mfma_f32_16x16x32_bf16 v[98:101], v[176:179], v[196:199], v[98:101]
	v_mfma_f32_16x16x32_bf16 v[86:89], v[168:171], v[204:207], v[86:89]
	v_mfma_f32_16x16x32_bf16 v[82:85], v[176:179], v[204:207], v[82:85]
	v_mfma_f32_16x16x32_bf16 v[70:73], v[168:171], v[212:215], v[70:73]
	v_mfma_f32_16x16x32_bf16 v[66:69], v[176:179], v[212:215], v[66:69]
	v_mfma_f32_16x16x32_bf16 v[118:121], v[172:175], v[192:195], v[118:121]
	v_mfma_f32_16x16x32_bf16 v[114:117], v[180:183], v[192:195], v[114:117]
	v_mfma_f32_16x16x32_bf16 v[102:105], v[172:175], v[200:203], v[102:105]
	v_mfma_f32_16x16x32_bf16 v[98:101], v[180:183], v[200:203], v[98:101]
	v_mfma_f32_16x16x32_bf16 v[86:89], v[172:175], v[208:211], v[86:89]
	v_mfma_f32_16x16x32_bf16 v[82:85], v[180:183], v[208:211], v[82:85]
	v_mfma_f32_16x16x32_bf16 v[70:73], v[172:175], v[216:219], v[70:73]
	v_mfma_f32_16x16x32_bf16 v[66:69], v[180:183], v[216:219], v[66:69]
	s_barrier
	s_setprio 0
	s_add_i32 s73, s68, s47
	v_lshl_add_u64 v[184:185], s[40:41], 0, v[132:133]
	s_mov_b32 m0, s73
	ds_read_b128 v[188:191], v154 offset:16384
	ds_read_b128 v[192:195], v154 offset:17408
	ds_read_b128 v[196:199], v154 offset:18432
	ds_read_b128 v[200:203], v154 offset:19456
	ds_read_b128 v[204:207], v154 offset:20480
	ds_read_b128 v[208:211], v154 offset:21504
	ds_read_b128 v[212:215], v154 offset:22528
	ds_read_b128 v[216:219], v154 offset:23552
	global_load_lds_dwordx4 v[184:185], off
	s_add_i32 m0, s73, 0x2000
	s_add_u32 s74, s40, 0x100000
	v_lshl_add_u64 v[220:221], s[40:41], 0, v[136:137]
	s_addc_u32 s75, s41, 0
	s_add_i32 s73, s69, s47
	global_load_lds_dwordx4 v[220:221], off
	s_mov_b32 m0, s73
	v_lshl_add_u64 v[224:225], s[42:43], 0, v[134:135]
	global_load_lds_dwordx4 v132, s[74:75]
	s_add_i32 m0, s73, 0x2000
	s_nop 0
	global_load_lds_dwordx4 v136, s[74:75]
	v_lshl_add_u64 v[222:223], s[42:43], 0, v[130:131]
	s_mov_b32 m0, s49
	s_nop 0
	global_load_lds_dwordx4 v[222:223], off
	s_mov_b32 m0, s56
	s_nop 0
	global_load_lds_dwordx4 v[224:225], off
	s_waitcnt vmcnt(8)
	s_waitcnt lgkmcnt(0)
	s_setprio 1
	s_barrier
	v_mfma_f32_16x16x32_bf16 v[62:65], v[146:149], v[188:191], v[62:65]
	v_mfma_f32_16x16x32_bf16 v[58:61], v[160:163], v[188:191], v[58:61]
	v_mfma_f32_16x16x32_bf16 v[46:49], v[146:149], v[196:199], v[46:49]
	v_mfma_f32_16x16x32_bf16 v[42:45], v[160:163], v[196:199], v[42:45]
	v_mfma_f32_16x16x32_bf16 v[30:33], v[146:149], v[204:207], v[30:33]
	v_mfma_f32_16x16x32_bf16 v[26:29], v[160:163], v[204:207], v[26:29]
	v_mfma_f32_16x16x32_bf16 v[14:17], v[146:149], v[212:215], v[14:17]
	v_mfma_f32_16x16x32_bf16 v[10:13], v[160:163], v[212:215], v[10:13]
	v_mfma_f32_16x16x32_bf16 v[62:65], v[156:159], v[192:195], v[62:65]
	v_mfma_f32_16x16x32_bf16 v[58:61], v[164:167], v[192:195], v[58:61]
	v_mfma_f32_16x16x32_bf16 v[46:49], v[156:159], v[200:203], v[46:49]
	v_mfma_f32_16x16x32_bf16 v[42:45], v[164:167], v[200:203], v[42:45]
	v_mfma_f32_16x16x32_bf16 v[30:33], v[156:159], v[208:211], v[30:33]
	v_mfma_f32_16x16x32_bf16 v[26:29], v[164:167], v[208:211], v[26:29]
	v_mfma_f32_16x16x32_bf16 v[14:17], v[156:159], v[216:219], v[14:17]
	v_mfma_f32_16x16x32_bf16 v[10:13], v[164:167], v[216:219], v[10:13]
	v_mfma_f32_16x16x32_bf16 v[54:57], v[168:171], v[188:191], v[54:57]
	v_mfma_f32_16x16x32_bf16 v[50:53], v[176:179], v[188:191], v[50:53]
	v_mfma_f32_16x16x32_bf16 v[38:41], v[168:171], v[196:199], v[38:41]
	v_mfma_f32_16x16x32_bf16 v[34:37], v[176:179], v[196:199], v[34:37]
	v_mfma_f32_16x16x32_bf16 v[22:25], v[168:171], v[204:207], v[22:25]
	v_mfma_f32_16x16x32_bf16 v[18:21], v[176:179], v[204:207], v[18:21]
	v_mfma_f32_16x16x32_bf16 v[6:9], v[168:171], v[212:215], v[6:9]
	v_mfma_f32_16x16x32_bf16 v[2:5], v[176:179], v[212:215], v[2:5]
	v_mfma_f32_16x16x32_bf16 v[54:57], v[172:175], v[192:195], v[54:57]
	v_mfma_f32_16x16x32_bf16 v[50:53], v[180:183], v[192:195], v[50:53]
	v_mfma_f32_16x16x32_bf16 v[38:41], v[172:175], v[200:203], v[38:41]
	v_mfma_f32_16x16x32_bf16 v[34:37], v[180:183], v[200:203], v[34:37]
	v_mfma_f32_16x16x32_bf16 v[22:25], v[172:175], v[208:211], v[22:25]
	v_mfma_f32_16x16x32_bf16 v[18:21], v[180:183], v[208:211], v[18:21]
	v_mfma_f32_16x16x32_bf16 v[6:9], v[172:175], v[216:219], v[6:9]
	v_mfma_f32_16x16x32_bf16 v[2:5], v[180:183], v[216:219], v[2:5]
	s_barrier
	s_setprio 0
	s_add_i32 s73, 0, 0x18000
	s_add_i32 s74, 0, 0x1c000
	v_add_u32_e32 v164, s73, v150
	v_add_u32_e32 v180, s74, v150
	ds_read_b128 v[146:149], v164
	ds_read_b128 v[156:159], v164 offset:1024
	ds_read_b128 v[160:163], v164 offset:2048
	ds_read_b128 v[164:167], v164 offset:3072
	ds_read_b128 v[168:171], v180
	ds_read_b128 v[172:175], v180 offset:1024
	ds_read_b128 v[176:179], v180 offset:2048
	ds_read_b128 v[180:183], v180 offset:3072
	s_add_u32 s42, s42, 0x100000
	s_addc_u32 s43, s43, 0
	s_mov_b32 m0, s57
	ds_read_b128 v[188:191], v154 offset:32768
	ds_read_b128 v[192:195], v154 offset:33792
	ds_read_b128 v[196:199], v154 offset:34816
	ds_read_b128 v[200:203], v154 offset:35840
	ds_read_b128 v[204:207], v154 offset:36864
	ds_read_b128 v[208:211], v154 offset:37888
	ds_read_b128 v[212:215], v154 offset:38912
	ds_read_b128 v[216:219], v154 offset:39936
	global_load_lds_dwordx4 v130, s[42:43]
	s_mov_b32 m0, s60
	s_nop 0
	global_load_lds_dwordx4 v134, s[42:43]
	s_waitcnt vmcnt(8)
	s_waitcnt lgkmcnt(0)
	s_setprio 1
	s_barrier
	v_mfma_f32_16x16x32_bf16 v[126:129], v[146:149], v[188:191], v[126:129]
	v_mfma_f32_16x16x32_bf16 v[122:125], v[160:163], v[188:191], v[122:125]
	v_mfma_f32_16x16x32_bf16 v[110:113], v[146:149], v[196:199], v[110:113]
	v_mfma_f32_16x16x32_bf16 v[106:109], v[160:163], v[196:199], v[106:109]
	v_mfma_f32_16x16x32_bf16 v[94:97], v[146:149], v[204:207], v[94:97]
	v_mfma_f32_16x16x32_bf16 v[90:93], v[160:163], v[204:207], v[90:93]
	v_mfma_f32_16x16x32_bf16 v[78:81], v[146:149], v[212:215], v[78:81]
	v_mfma_f32_16x16x32_bf16 v[74:77], v[160:163], v[212:215], v[74:77]
	v_mfma_f32_16x16x32_bf16 v[126:129], v[156:159], v[192:195], v[126:129]
	v_mfma_f32_16x16x32_bf16 v[122:125], v[164:167], v[192:195], v[122:125]
	v_mfma_f32_16x16x32_bf16 v[110:113], v[156:159], v[200:203], v[110:113]
	v_mfma_f32_16x16x32_bf16 v[106:109], v[164:167], v[200:203], v[106:109]
	v_mfma_f32_16x16x32_bf16 v[94:97], v[156:159], v[208:211], v[94:97]
	v_mfma_f32_16x16x32_bf16 v[90:93], v[164:167], v[208:211], v[90:93]
	v_mfma_f32_16x16x32_bf16 v[78:81], v[156:159], v[216:219], v[78:81]
	v_mfma_f32_16x16x32_bf16 v[74:77], v[164:167], v[216:219], v[74:77]
	v_mfma_f32_16x16x32_bf16 v[118:121], v[168:171], v[188:191], v[118:121]
	v_mfma_f32_16x16x32_bf16 v[114:117], v[176:179], v[188:191], v[114:117]
	v_mfma_f32_16x16x32_bf16 v[102:105], v[168:171], v[196:199], v[102:105]
	v_mfma_f32_16x16x32_bf16 v[98:101], v[176:179], v[196:199], v[98:101]
	v_mfma_f32_16x16x32_bf16 v[86:89], v[168:171], v[204:207], v[86:89]
	v_mfma_f32_16x16x32_bf16 v[82:85], v[176:179], v[204:207], v[82:85]
	v_mfma_f32_16x16x32_bf16 v[70:73], v[168:171], v[212:215], v[70:73]
	v_mfma_f32_16x16x32_bf16 v[66:69], v[176:179], v[212:215], v[66:69]
	v_mfma_f32_16x16x32_bf16 v[118:121], v[172:175], v[192:195], v[118:121]
	v_mfma_f32_16x16x32_bf16 v[114:117], v[180:183], v[192:195], v[114:117]
	v_mfma_f32_16x16x32_bf16 v[102:105], v[172:175], v[200:203], v[102:105]
	v_mfma_f32_16x16x32_bf16 v[98:101], v[180:183], v[200:203], v[98:101]
	v_mfma_f32_16x16x32_bf16 v[86:89], v[172:175], v[208:211], v[86:89]
	v_mfma_f32_16x16x32_bf16 v[82:85], v[180:183], v[208:211], v[82:85]
	v_mfma_f32_16x16x32_bf16 v[70:73], v[172:175], v[216:219], v[70:73]
	v_mfma_f32_16x16x32_bf16 v[66:69], v[180:183], v[216:219], v[66:69]
	s_barrier
	s_setprio 0
	s_add_i32 s42, s73, s47
	v_lshl_add_u64 v[184:185], v[184:185], 0, s[22:23]
	s_mov_b32 m0, s42
	ds_read_b128 v[188:191], v154 offset:49152
	ds_read_b128 v[192:195], v154 offset:50176
	ds_read_b128 v[196:199], v154 offset:51200
	ds_read_b128 v[200:203], v154 offset:52224
	ds_read_b128 v[204:207], v154 offset:53248
	ds_read_b128 v[208:211], v154 offset:54272
	ds_read_b128 v[212:215], v154 offset:55296
	ds_read_b128 v[216:219], v154 offset:56320
	global_load_lds_dwordx4 v[184:185], off
	s_add_i32 m0, s42, 0x2000
	s_add_u32 s40, s40, 0x100080
	v_lshl_add_u64 v[184:185], v[220:221], 0, s[22:23]
	s_addc_u32 s41, s41, 0
	s_add_i32 s42, s74, s47
	global_load_lds_dwordx4 v[184:185], off
	s_mov_b32 m0, s42
	s_nop 0
	global_load_lds_dwordx4 v132, s[40:41]
	s_add_i32 m0, s42, 0x2000
	s_nop 0
	global_load_lds_dwordx4 v136, s[40:41]
	v_lshl_add_u64 v[184:185], v[222:223], 0, s[22:23]
	s_mov_b32 m0, s63
	s_nop 0
	global_load_lds_dwordx4 v[184:185], off
	v_lshl_add_u64 v[184:185], v[224:225], 0, s[22:23]
	s_mov_b32 m0, s64
	s_nop 0
	global_load_lds_dwordx4 v[184:185], off
	s_add_i32 s72, s72, 2
	s_add_u32 s70, s70, 0x100
	s_addc_u32 s71, s71, 0
	s_add_u32 s38, s38, 0x100
	s_addc_u32 s39, s39, 0
	s_cmp_gt_u32 s72, 61
	s_waitcnt vmcnt(8)
	s_waitcnt lgkmcnt(0)
	s_setprio 1
	s_barrier
	v_mfma_f32_16x16x32_bf16 v[62:65], v[146:149], v[188:191], v[62:65]
	v_mfma_f32_16x16x32_bf16 v[58:61], v[160:163], v[188:191], v[58:61]
	v_mfma_f32_16x16x32_bf16 v[46:49], v[146:149], v[196:199], v[46:49]
	v_mfma_f32_16x16x32_bf16 v[42:45], v[160:163], v[196:199], v[42:45]
	v_mfma_f32_16x16x32_bf16 v[30:33], v[146:149], v[204:207], v[30:33]
	v_mfma_f32_16x16x32_bf16 v[26:29], v[160:163], v[204:207], v[26:29]
	v_mfma_f32_16x16x32_bf16 v[14:17], v[146:149], v[212:215], v[14:17]
	v_mfma_f32_16x16x32_bf16 v[10:13], v[160:163], v[212:215], v[10:13]
	v_mfma_f32_16x16x32_bf16 v[62:65], v[156:159], v[192:195], v[62:65]
	v_mfma_f32_16x16x32_bf16 v[58:61], v[164:167], v[192:195], v[58:61]
	v_mfma_f32_16x16x32_bf16 v[46:49], v[156:159], v[200:203], v[46:49]
	v_mfma_f32_16x16x32_bf16 v[42:45], v[164:167], v[200:203], v[42:45]
	v_mfma_f32_16x16x32_bf16 v[30:33], v[156:159], v[208:211], v[30:33]
	v_mfma_f32_16x16x32_bf16 v[26:29], v[164:167], v[208:211], v[26:29]
	v_mfma_f32_16x16x32_bf16 v[14:17], v[156:159], v[216:219], v[14:17]
	v_mfma_f32_16x16x32_bf16 v[10:13], v[164:167], v[216:219], v[10:13]
	v_mfma_f32_16x16x32_bf16 v[54:57], v[168:171], v[188:191], v[54:57]
	v_mfma_f32_16x16x32_bf16 v[50:53], v[176:179], v[188:191], v[50:53]
	v_mfma_f32_16x16x32_bf16 v[38:41], v[168:171], v[196:199], v[38:41]
	v_mfma_f32_16x16x32_bf16 v[34:37], v[176:179], v[196:199], v[34:37]
	v_mfma_f32_16x16x32_bf16 v[22:25], v[168:171], v[204:207], v[22:25]
	v_mfma_f32_16x16x32_bf16 v[18:21], v[176:179], v[204:207], v[18:21]
	v_mfma_f32_16x16x32_bf16 v[6:9], v[168:171], v[212:215], v[6:9]
	v_mfma_f32_16x16x32_bf16 v[2:5], v[176:179], v[212:215], v[2:5]
	v_mfma_f32_16x16x32_bf16 v[54:57], v[172:175], v[192:195], v[54:57]
	v_mfma_f32_16x16x32_bf16 v[50:53], v[180:183], v[192:195], v[50:53]
	v_mfma_f32_16x16x32_bf16 v[38:41], v[172:175], v[200:203], v[38:41]
	v_mfma_f32_16x16x32_bf16 v[34:37], v[180:183], v[200:203], v[34:37]
	v_mfma_f32_16x16x32_bf16 v[22:25], v[172:175], v[208:211], v[22:25]
	v_mfma_f32_16x16x32_bf16 v[18:21], v[180:183], v[208:211], v[18:21]
	v_mfma_f32_16x16x32_bf16 v[6:9], v[172:175], v[216:219], v[6:9]
	v_mfma_f32_16x16x32_bf16 v[2:5], v[180:183], v[216:219], v[2:5]
	s_cbranch_scc1 .Ltb4_e
	s_barrier
	s_setprio 0
	s_branch .LBB0_1281
.Ltb4_e:
	s_setprio 0
	s_and_b64 vcc, exec, s[24:25]
	s_cbranch_vccz .LBB0_1284
	s_barrier

.LBB0_1483:
	ds_read_b128 v[146:149], v152
	ds_read_b128 v[156:159], v152 offset:1024
	ds_read_b128 v[160:163], v152 offset:2048
	ds_read_b128 v[164:167], v152 offset:3072
	ds_read_b128 v[168:171], v153
	ds_read_b128 v[172:175], v153 offset:1024
	ds_read_b128 v[176:179], v153 offset:2048
	ds_read_b128 v[180:183], v153 offset:3072
	s_add_u32 s38, s10, 0xfffc0080
	s_addc_u32 s39, s11, -1
	s_cmp_eq_u32 s66, 12
	s_cselect_b32 s41, s25, s39
	s_cselect_b32 s40, s27, s38
	s_cselect_b32 s39, s29, s65
	s_cselect_b32 s38, s28, s64
	s_add_i32 m0, s35, 0xc000
	ds_read_b128 v[188:191], v154
	ds_read_b128 v[192:195], v154 offset:1024
	ds_read_b128 v[196:199], v154 offset:2048
	ds_read_b128 v[200:203], v154 offset:3072
	ds_read_b128 v[204:207], v154 offset:4096
	ds_read_b128 v[208:211], v154 offset:5120
	ds_read_b128 v[212:215], v154 offset:6144
	ds_read_b128 v[216:219], v154 offset:7168
	global_load_lds_dwordx4 v140, s[10:11]
	s_add_i32 m0, s35, 0xe000
	s_nop 0
	global_load_lds_dwordx4 v138, s[10:11]
	s_waitcnt vmcnt(8)
	s_waitcnt lgkmcnt(0)
	s_setprio 1
	s_barrier
	v_mfma_f32_16x16x32_bf16 v[126:129], v[146:149], v[188:191], v[126:129]
	v_mfma_f32_16x16x32_bf16 v[122:125], v[160:163], v[188:191], v[122:125]
	v_mfma_f32_16x16x32_bf16 v[110:113], v[146:149], v[196:199], v[110:113]
	v_mfma_f32_16x16x32_bf16 v[106:109], v[160:163], v[196:199], v[106:109]
	v_mfma_f32_16x16x32_bf16 v[94:97], v[146:149], v[204:207], v[94:97]
	v_mfma_f32_16x16x32_bf16 v[90:93], v[160:163], v[204:207], v[90:93]
	v_mfma_f32_16x16x32_bf16 v[78:81], v[146:149], v[212:215], v[78:81]
	v_mfma_f32_16x16x32_bf16 v[74:77], v[160:163], v[212:215], v[74:77]
	v_mfma_f32_16x16x32_bf16 v[126:129], v[156:159], v[192:195], v[126:129]
	v_mfma_f32_16x16x32_bf16 v[122:125], v[164:167], v[192:195], v[122:125]
	v_mfma_f32_16x16x32_bf16 v[110:113], v[156:159], v[200:203], v[110:113]
	v_mfma_f32_16x16x32_bf16 v[106:109], v[164:167], v[200:203], v[106:109]
	v_mfma_f32_16x16x32_bf16 v[94:97], v[156:159], v[208:211], v[94:97]
	v_mfma_f32_16x16x32_bf16 v[90:93], v[164:167], v[208:211], v[90:93]
	v_mfma_f32_16x16x32_bf16 v[78:81], v[156:159], v[216:219], v[78:81]
	v_mfma_f32_16x16x32_bf16 v[74:77], v[164:167], v[216:219], v[74:77]
	v_mfma_f32_16x16x32_bf16 v[118:121], v[168:171], v[188:191], v[118:121]
	v_mfma_f32_16x16x32_bf16 v[114:117], v[176:179], v[188:191], v[114:117]
	v_mfma_f32_16x16x32_bf16 v[102:105], v[168:171], v[196:199], v[102:105]
	v_mfma_f32_16x16x32_bf16 v[98:101], v[176:179], v[196:199], v[98:101]
	v_mfma_f32_16x16x32_bf16 v[86:89], v[168:171], v[204:207], v[86:89]
	v_mfma_f32_16x16x32_bf16 v[82:85], v[176:179], v[204:207], v[82:85]
	v_mfma_f32_16x16x32_bf16 v[70:73], v[168:171], v[212:215], v[70:73]
	v_mfma_f32_16x16x32_bf16 v[66:69], v[176:179], v[212:215], v[66:69]
	v_mfma_f32_16x16x32_bf16 v[118:121], v[172:175], v[192:195], v[118:121]
	v_mfma_f32_16x16x32_bf16 v[114:117], v[180:183], v[192:195], v[114:117]
	v_mfma_f32_16x16x32_bf16 v[102:105], v[172:175], v[200:203], v[102:105]
	v_mfma_f32_16x16x32_bf16 v[98:101], v[180:183], v[200:203], v[98:101]
	v_mfma_f32_16x16x32_bf16 v[86:89], v[172:175], v[208:211], v[86:89]
	v_mfma_f32_16x16x32_bf16 v[82:85], v[180:183], v[208:211], v[82:85]
	v_mfma_f32_16x16x32_bf16 v[70:73], v[172:175], v[216:219], v[70:73]
	v_mfma_f32_16x16x32_bf16 v[66:69], v[180:183], v[216:219], v[66:69]
	s_barrier
	s_setprio 0
	s_add_i32 s67, s62, s45
	v_lshl_add_u64 v[184:185], s[38:39], 0, v[132:133]
	s_mov_b32 m0, s67
	ds_read_b128 v[188:191], v154 offset:16384
	ds_read_b128 v[192:195], v154 offset:17408
	ds_read_b128 v[196:199], v154 offset:18432
	ds_read_b128 v[200:203], v154 offset:19456
	ds_read_b128 v[204:207], v154 offset:20480
	ds_read_b128 v[208:211], v154 offset:21504
	ds_read_b128 v[212:215], v154 offset:22528
	ds_read_b128 v[216:219], v154 offset:23552
	global_load_lds_dwordx4 v[184:185], off
	s_add_i32 m0, s67, 0x2000
	s_add_u32 s68, s38, 0x40000
	v_lshl_add_u64 v[220:221], s[38:39], 0, v[136:137]
	s_addc_u32 s69, s39, 0
	s_add_i32 s67, s63, s45
	global_load_lds_dwordx4 v[220:221], off
	s_mov_b32 m0, s67
	v_lshl_add_u64 v[224:225], s[40:41], 0, v[134:135]
	global_load_lds_dwordx4 v132, s[68:69]
	s_add_i32 m0, s67, 0x2000
	s_nop 0
	global_load_lds_dwordx4 v136, s[68:69]
	v_lshl_add_u64 v[222:223], s[40:41], 0, v[130:131]
	s_mov_b32 m0, s35
	s_nop 0
	global_load_lds_dwordx4 v[222:223], off
	s_mov_b32 m0, s37
	s_nop 0
	global_load_lds_dwordx4 v[224:225], off
	s_waitcnt vmcnt(8)
	s_waitcnt lgkmcnt(0)
	s_setprio 1
	s_barrier
	v_mfma_f32_16x16x32_bf16 v[62:65], v[146:149], v[188:191], v[62:65]
	v_mfma_f32_16x16x32_bf16 v[58:61], v[160:163], v[188:191], v[58:61]
	v_mfma_f32_16x16x32_bf16 v[46:49], v[146:149], v[196:199], v[46:49]
	v_mfma_f32_16x16x32_bf16 v[42:45], v[160:163], v[196:199], v[42:45]
	v_mfma_f32_16x16x32_bf16 v[30:33], v[146:149], v[204:207], v[30:33]
	v_mfma_f32_16x16x32_bf16 v[26:29], v[160:163], v[204:207], v[26:29]
	v_mfma_f32_16x16x32_bf16 v[14:17], v[146:149], v[212:215], v[14:17]
	v_mfma_f32_16x16x32_bf16 v[10:13], v[160:163], v[212:215], v[10:13]
	v_mfma_f32_16x16x32_bf16 v[62:65], v[156:159], v[192:195], v[62:65]
	v_mfma_f32_16x16x32_bf16 v[58:61], v[164:167], v[192:195], v[58:61]
	v_mfma_f32_16x16x32_bf16 v[46:49], v[156:159], v[200:203], v[46:49]
	v_mfma_f32_16x16x32_bf16 v[42:45], v[164:167], v[200:203], v[42:45]
	v_mfma_f32_16x16x32_bf16 v[30:33], v[156:159], v[208:211], v[30:33]
	v_mfma_f32_16x16x32_bf16 v[26:29], v[164:167], v[208:211], v[26:29]
	v_mfma_f32_16x16x32_bf16 v[14:17], v[156:159], v[216:219], v[14:17]
	v_mfma_f32_16x16x32_bf16 v[10:13], v[164:167], v[216:219], v[10:13]
	v_mfma_f32_16x16x32_bf16 v[54:57], v[168:171], v[188:191], v[54:57]
	v_mfma_f32_16x16x32_bf16 v[50:53], v[176:179], v[188:191], v[50:53]
	v_mfma_f32_16x16x32_bf16 v[38:41], v[168:171], v[196:199], v[38:41]
	v_mfma_f32_16x16x32_bf16 v[34:37], v[176:179], v[196:199], v[34:37]
	v_mfma_f32_16x16x32_bf16 v[22:25], v[168:171], v[204:207], v[22:25]
	v_mfma_f32_16x16x32_bf16 v[18:21], v[176:179], v[204:207], v[18:21]
	v_mfma_f32_16x16x32_bf16 v[6:9], v[168:171], v[212:215], v[6:9]
	v_mfma_f32_16x16x32_bf16 v[2:5], v[176:179], v[212:215], v[2:5]
	v_mfma_f32_16x16x32_bf16 v[54:57], v[172:175], v[192:195], v[54:57]
	v_mfma_f32_16x16x32_bf16 v[50:53], v[180:183], v[192:195], v[50:53]
	v_mfma_f32_16x16x32_bf16 v[38:41], v[172:175], v[200:203], v[38:41]
	v_mfma_f32_16x16x32_bf16 v[34:37], v[180:183], v[200:203], v[34:37]
	v_mfma_f32_16x16x32_bf16 v[22:25], v[172:175], v[208:211], v[22:25]
	v_mfma_f32_16x16x32_bf16 v[18:21], v[180:183], v[208:211], v[18:21]
	v_mfma_f32_16x16x32_bf16 v[6:9], v[172:175], v[216:219], v[6:9]
	v_mfma_f32_16x16x32_bf16 v[2:5], v[180:183], v[216:219], v[2:5]
	s_barrier
	s_setprio 0
	s_add_i32 s67, 0, 0x18000
	s_add_i32 s68, 0, 0x1c000
	v_add_u32_e32 v164, s67, v150
	v_add_u32_e32 v180, s68, v150
	ds_read_b128 v[146:149], v164
	ds_read_b128 v[156:159], v164 offset:1024
	ds_read_b128 v[160:163], v164 offset:2048
	ds_read_b128 v[164:167], v164 offset:3072
	ds_read_b128 v[168:171], v180
	ds_read_b128 v[172:175], v180 offset:1024
	ds_read_b128 v[176:179], v180 offset:2048
	ds_read_b128 v[180:183], v180 offset:3072
	s_add_u32 s40, s40, 0x40000
	s_addc_u32 s41, s41, 0
	s_mov_b32 m0, s46
	ds_read_b128 v[188:191], v154 offset:32768
	ds_read_b128 v[192:195], v154 offset:33792
	ds_read_b128 v[196:199], v154 offset:34816
	ds_read_b128 v[200:203], v154 offset:35840
	ds_read_b128 v[204:207], v154 offset:36864
	ds_read_b128 v[208:211], v154 offset:37888
	ds_read_b128 v[212:215], v154 offset:38912
	ds_read_b128 v[216:219], v154 offset:39936
	global_load_lds_dwordx4 v130, s[40:41]
	s_mov_b32 m0, s47
	s_nop 0
	global_load_lds_dwordx4 v134, s[40:41]
	s_waitcnt vmcnt(8)
	s_waitcnt lgkmcnt(0)
	s_setprio 1
	s_barrier
	v_mfma_f32_16x16x32_bf16 v[126:129], v[146:149], v[188:191], v[126:129]
	v_mfma_f32_16x16x32_bf16 v[122:125], v[160:163], v[188:191], v[122:125]
	v_mfma_f32_16x16x32_bf16 v[110:113], v[146:149], v[196:199], v[110:113]
	v_mfma_f32_16x16x32_bf16 v[106:109], v[160:163], v[196:199], v[106:109]
	v_mfma_f32_16x16x32_bf16 v[94:97], v[146:149], v[204:207], v[94:97]
	v_mfma_f32_16x16x32_bf16 v[90:93], v[160:163], v[204:207], v[90:93]
	v_mfma_f32_16x16x32_bf16 v[78:81], v[146:149], v[212:215], v[78:81]
	v_mfma_f32_16x16x32_bf16 v[74:77], v[160:163], v[212:215], v[74:77]
	v_mfma_f32_16x16x32_bf16 v[126:129], v[156:159], v[192:195], v[126:129]
	v_mfma_f32_16x16x32_bf16 v[122:125], v[164:167], v[192:195], v[122:125]
	v_mfma_f32_16x16x32_bf16 v[110:113], v[156:159], v[200:203], v[110:113]
	v_mfma_f32_16x16x32_bf16 v[106:109], v[164:167], v[200:203], v[106:109]
	v_mfma_f32_16x16x32_bf16 v[94:97], v[156:159], v[208:211], v[94:97]
	v_mfma_f32_16x16x32_bf16 v[90:93], v[164:167], v[208:211], v[90:93]
	v_mfma_f32_16x16x32_bf16 v[78:81], v[156:159], v[216:219], v[78:81]
	v_mfma_f32_16x16x32_bf16 v[74:77], v[164:167], v[216:219], v[74:77]
	v_mfma_f32_16x16x32_bf16 v[118:121], v[168:171], v[188:191], v[118:121]
	v_mfma_f32_16x16x32_bf16 v[114:117], v[176:179], v[188:191], v[114:117]
	v_mfma_f32_16x16x32_bf16 v[102:105], v[168:171], v[196:199], v[102:105]
	v_mfma_f32_16x16x32_bf16 v[98:101], v[176:179], v[196:199], v[98:101]
	v_mfma_f32_16x16x32_bf16 v[86:89], v[168:171], v[204:207], v[86:89]
	v_mfma_f32_16x16x32_bf16 v[82:85], v[176:179], v[204:207], v[82:85]
	v_mfma_f32_16x16x32_bf16 v[70:73], v[168:171], v[212:215], v[70:73]
	v_mfma_f32_16x16x32_bf16 v[66:69], v[176:179], v[212:215], v[66:69]
	v_mfma_f32_16x16x32_bf16 v[118:121], v[172:175], v[192:195], v[118:121]
	v_mfma_f32_16x16x32_bf16 v[114:117], v[180:183], v[192:195], v[114:117]
	v_mfma_f32_16x16x32_bf16 v[102:105], v[172:175], v[200:203], v[102:105]
	v_mfma_f32_16x16x32_bf16 v[98:101], v[180:183], v[200:203], v[98:101]
	v_mfma_f32_16x16x32_bf16 v[86:89], v[172:175], v[208:211], v[86:89]
	v_mfma_f32_16x16x32_bf16 v[82:85], v[180:183], v[208:211], v[82:85]
	v_mfma_f32_16x16x32_bf16 v[70:73], v[172:175], v[216:219], v[70:73]
	v_mfma_f32_16x16x32_bf16 v[66:69], v[180:183], v[216:219], v[66:69]
	s_barrier
	s_setprio 0
	s_add_i32 s40, s67, s45
	v_lshl_add_u64 v[184:185], v[184:185], 0, s[20:21]
	s_mov_b32 m0, s40
	ds_read_b128 v[188:191], v154 offset:49152
	ds_read_b128 v[192:195], v154 offset:50176
	ds_read_b128 v[196:199], v154 offset:51200
	ds_read_b128 v[200:203], v154 offset:52224
	ds_read_b128 v[204:207], v154 offset:53248
	ds_read_b128 v[208:211], v154 offset:54272
	ds_read_b128 v[212:215], v154 offset:55296
	ds_read_b128 v[216:219], v154 offset:56320
	global_load_lds_dwordx4 v[184:185], off
	s_add_i32 m0, s40, 0x2000
	s_add_u32 s38, s38, 0x40080
	v_lshl_add_u64 v[184:185], v[220:221], 0, s[20:21]
	s_addc_u32 s39, s39, 0
	s_add_i32 s40, s68, s45
	global_load_lds_dwordx4 v[184:185], off
	s_mov_b32 m0, s40
	s_nop 0
	global_load_lds_dwordx4 v132, s[38:39]
	s_add_i32 m0, s40, 0x2000
	s_nop 0
	global_load_lds_dwordx4 v136, s[38:39]
	v_lshl_add_u64 v[184:185], v[222:223], 0, s[20:21]
	s_mov_b32 m0, s57
	s_nop 0
	global_load_lds_dwordx4 v[184:185], off
	v_lshl_add_u64 v[184:185], v[224:225], 0, s[20:21]
	s_mov_b32 m0, s60
	s_nop 0
	global_load_lds_dwordx4 v[184:185], off
	s_add_i32 s66, s66, 2
	s_add_u32 s64, s64, 0x100
	s_addc_u32 s65, s65, 0
	s_add_u32 s10, s10, 0x100
	s_addc_u32 s11, s11, 0
	s_cmp_gt_u32 s66, 13
	s_waitcnt vmcnt(8)
	s_waitcnt lgkmcnt(0)
	s_setprio 1
	s_barrier
	v_mfma_f32_16x16x32_bf16 v[62:65], v[146:149], v[188:191], v[62:65]
	v_mfma_f32_16x16x32_bf16 v[58:61], v[160:163], v[188:191], v[58:61]
	v_mfma_f32_16x16x32_bf16 v[46:49], v[146:149], v[196:199], v[46:49]
	v_mfma_f32_16x16x32_bf16 v[42:45], v[160:163], v[196:199], v[42:45]
	v_mfma_f32_16x16x32_bf16 v[30:33], v[146:149], v[204:207], v[30:33]
	v_mfma_f32_16x16x32_bf16 v[26:29], v[160:163], v[204:207], v[26:29]
	v_mfma_f32_16x16x32_bf16 v[14:17], v[146:149], v[212:215], v[14:17]
	v_mfma_f32_16x16x32_bf16 v[10:13], v[160:163], v[212:215], v[10:13]
	v_mfma_f32_16x16x32_bf16 v[62:65], v[156:159], v[192:195], v[62:65]
	v_mfma_f32_16x16x32_bf16 v[58:61], v[164:167], v[192:195], v[58:61]
	v_mfma_f32_16x16x32_bf16 v[46:49], v[156:159], v[200:203], v[46:49]
	v_mfma_f32_16x16x32_bf16 v[42:45], v[164:167], v[200:203], v[42:45]
	v_mfma_f32_16x16x32_bf16 v[30:33], v[156:159], v[208:211], v[30:33]
	v_mfma_f32_16x16x32_bf16 v[26:29], v[164:167], v[208:211], v[26:29]
	v_mfma_f32_16x16x32_bf16 v[14:17], v[156:159], v[216:219], v[14:17]
	v_mfma_f32_16x16x32_bf16 v[10:13], v[164:167], v[216:219], v[10:13]
	v_mfma_f32_16x16x32_bf16 v[54:57], v[168:171], v[188:191], v[54:57]
	v_mfma_f32_16x16x32_bf16 v[50:53], v[176:179], v[188:191], v[50:53]
	v_mfma_f32_16x16x32_bf16 v[38:41], v[168:171], v[196:199], v[38:41]
	v_mfma_f32_16x16x32_bf16 v[34:37], v[176:179], v[196:199], v[34:37]
	v_mfma_f32_16x16x32_bf16 v[22:25], v[168:171], v[204:207], v[22:25]
	v_mfma_f32_16x16x32_bf16 v[18:21], v[176:179], v[204:207], v[18:21]
	v_mfma_f32_16x16x32_bf16 v[6:9], v[168:171], v[212:215], v[6:9]
	v_mfma_f32_16x16x32_bf16 v[2:5], v[176:179], v[212:215], v[2:5]
	v_mfma_f32_16x16x32_bf16 v[54:57], v[172:175], v[192:195], v[54:57]
	v_mfma_f32_16x16x32_bf16 v[50:53], v[180:183], v[192:195], v[50:53]
	v_mfma_f32_16x16x32_bf16 v[38:41], v[172:175], v[200:203], v[38:41]
	v_mfma_f32_16x16x32_bf16 v[34:37], v[180:183], v[200:203], v[34:37]
	v_mfma_f32_16x16x32_bf16 v[22:25], v[172:175], v[208:211], v[22:25]
	v_mfma_f32_16x16x32_bf16 v[18:21], v[180:183], v[208:211], v[18:21]
	v_mfma_f32_16x16x32_bf16 v[6:9], v[172:175], v[216:219], v[6:9]
	v_mfma_f32_16x16x32_bf16 v[2:5], v[180:183], v[216:219], v[2:5]
	s_cbranch_scc1 .Ltb6_e
	s_barrier
	s_setprio 0
	s_branch .LBB0_1483
.Ltb6_e:
	s_setprio 0
	v_lshl_add_u32 v245, s34, 8, v1
	v_lshl_or_b32 v246, s36, 8, v151
	v_lshlrev_b32_e32 v245, 13, v245
	v_lshl_add_u32 v245, v246, 1, v245
	global_load_dwordx4 v[146:149], v245, s[16:17]
	global_load_dwordx4 v[156:159], v245, s[16:17] offset:256
	s_add_u32 s10, s16, 0x20000
	s_addc_u32 s11, s17, 0
	global_load_dwordx4 v[160:163], v245, s[10:11]
	global_load_dwordx4 v[164:167], v245, s[10:11] offset:256
	s_add_u32 s10, s16, 0x40000
	s_addc_u32 s11, s17, 0
	global_load_dwordx4 v[168:171], v245, s[10:11]
	global_load_dwordx4 v[172:175], v245, s[10:11] offset:256
	s_add_u32 s10, s16, 0x60000
	s_addc_u32 s11, s17, 0
	global_load_dwordx4 v[176:179], v245, s[10:11]
	global_load_dwordx4 v[180:183], v245, s[10:11] offset:256
	s_add_u32 s10, s16, 0x100000
	s_addc_u32 s11, s17, 0
	global_load_dwordx4 v[188:191], v245, s[10:11]
	global_load_dwordx4 v[192:195], v245, s[10:11] offset:256
	s_add_u32 s10, s16, 0x120000
	s_addc_u32 s11, s17, 0
	global_load_dwordx4 v[196:199], v245, s[10:11]
	global_load_dwordx4 v[200:203], v245, s[10:11] offset:256
	s_add_u32 s10, s16, 0x140000
	s_addc_u32 s11, s17, 0
	global_load_dwordx4 v[204:207], v245, s[10:11]
	global_load_dwordx4 v[208:211], v245, s[10:11] offset:256
	s_add_u32 s10, s16, 0x160000
	s_addc_u32 s11, s17, 0
	global_load_dwordx4 v[212:215], v245, s[10:11]
	global_load_dwordx4 v[216:219], v245, s[10:11] offset:256
	s_and_b64 vcc, exec, s[22:23]
	s_cbranch_vccz .LBB0_1486
	s_barrier

.LBB0_1689:
	ds_read_b128 v[142:145], v148
	ds_read_b128 v[152:155], v148 offset:1024
	ds_read_b128 v[156:159], v148 offset:2048
	ds_read_b128 v[160:163], v148 offset:3072
	ds_read_b128 v[166:169], v149
	ds_read_b128 v[170:173], v149 offset:1024
	ds_read_b128 v[174:177], v149 offset:2048
	ds_read_b128 v[178:181], v149 offset:3072
	s_add_u32 s6, s70, 0xfff00080
	s_addc_u32 s7, s71, -1
	s_cmp_eq_u32 s86, 60
	s_cselect_b32 s75, s61, s7
	s_cselect_b32 s74, s67, s6
	s_cselect_b32 s73, s47, s85
	s_cselect_b32 s72, s69, s84
	s_add_i32 m0, s28, 0xc000
	ds_read_b128 v[182:185], v150
	ds_read_b128 v[188:191], v150 offset:1024
	ds_read_b128 v[192:195], v150 offset:2048
	ds_read_b128 v[196:199], v150 offset:3072
	ds_read_b128 v[200:203], v150 offset:4096
	ds_read_b128 v[204:207], v150 offset:5120
	ds_read_b128 v[208:211], v150 offset:6144
	ds_read_b128 v[212:215], v150 offset:7168
	global_load_lds_dwordx4 v140, s[70:71]
	s_add_i32 m0, s28, 0xe000
	s_nop 0
	global_load_lds_dwordx4 v138, s[70:71]
	s_waitcnt vmcnt(8)
	s_waitcnt lgkmcnt(0)
	s_setprio 1
	s_barrier
	v_mfma_f32_16x16x32_bf16 v[126:129], v[142:145], v[182:185], v[126:129]
	v_mfma_f32_16x16x32_bf16 v[122:125], v[156:159], v[182:185], v[122:125]
	v_mfma_f32_16x16x32_bf16 v[110:113], v[142:145], v[192:195], v[110:113]
	v_mfma_f32_16x16x32_bf16 v[106:109], v[156:159], v[192:195], v[106:109]
	v_mfma_f32_16x16x32_bf16 v[94:97], v[142:145], v[200:203], v[94:97]
	v_mfma_f32_16x16x32_bf16 v[90:93], v[156:159], v[200:203], v[90:93]
	v_mfma_f32_16x16x32_bf16 v[78:81], v[142:145], v[208:211], v[78:81]
	v_mfma_f32_16x16x32_bf16 v[74:77], v[156:159], v[208:211], v[74:77]
	v_mfma_f32_16x16x32_bf16 v[126:129], v[152:155], v[188:191], v[126:129]
	v_mfma_f32_16x16x32_bf16 v[122:125], v[160:163], v[188:191], v[122:125]
	v_mfma_f32_16x16x32_bf16 v[110:113], v[152:155], v[196:199], v[110:113]
	v_mfma_f32_16x16x32_bf16 v[106:109], v[160:163], v[196:199], v[106:109]
	v_mfma_f32_16x16x32_bf16 v[94:97], v[152:155], v[204:207], v[94:97]
	v_mfma_f32_16x16x32_bf16 v[90:93], v[160:163], v[204:207], v[90:93]
	v_mfma_f32_16x16x32_bf16 v[78:81], v[152:155], v[212:215], v[78:81]
	v_mfma_f32_16x16x32_bf16 v[74:77], v[160:163], v[212:215], v[74:77]
	v_mfma_f32_16x16x32_bf16 v[118:121], v[166:169], v[182:185], v[118:121]
	v_mfma_f32_16x16x32_bf16 v[114:117], v[174:177], v[182:185], v[114:117]
	v_mfma_f32_16x16x32_bf16 v[102:105], v[166:169], v[192:195], v[102:105]
	v_mfma_f32_16x16x32_bf16 v[98:101], v[174:177], v[192:195], v[98:101]
	v_mfma_f32_16x16x32_bf16 v[86:89], v[166:169], v[200:203], v[86:89]
	v_mfma_f32_16x16x32_bf16 v[82:85], v[174:177], v[200:203], v[82:85]
	v_mfma_f32_16x16x32_bf16 v[70:73], v[166:169], v[208:211], v[70:73]
	v_mfma_f32_16x16x32_bf16 v[66:69], v[174:177], v[208:211], v[66:69]
	v_mfma_f32_16x16x32_bf16 v[118:121], v[170:173], v[188:191], v[118:121]
	v_mfma_f32_16x16x32_bf16 v[114:117], v[178:181], v[188:191], v[114:117]
	v_mfma_f32_16x16x32_bf16 v[102:105], v[170:173], v[196:199], v[102:105]
	v_mfma_f32_16x16x32_bf16 v[98:101], v[178:181], v[196:199], v[98:101]
	v_mfma_f32_16x16x32_bf16 v[86:89], v[170:173], v[204:207], v[86:89]
	v_mfma_f32_16x16x32_bf16 v[82:85], v[178:181], v[204:207], v[82:85]
	v_mfma_f32_16x16x32_bf16 v[70:73], v[170:173], v[212:215], v[70:73]
	v_mfma_f32_16x16x32_bf16 v[66:69], v[178:181], v[212:215], v[66:69]
	s_barrier
	s_setprio 0
	s_add_i32 s6, s82, s27
	v_lshl_add_u64 v[216:217], s[72:73], 0, v[132:133]
	s_mov_b32 m0, s6
	ds_read_b128 v[182:185], v150 offset:16384
	ds_read_b128 v[188:191], v150 offset:17408
	ds_read_b128 v[192:195], v150 offset:18432
	ds_read_b128 v[196:199], v150 offset:19456
	ds_read_b128 v[200:203], v150 offset:20480
	ds_read_b128 v[204:207], v150 offset:21504
	ds_read_b128 v[208:211], v150 offset:22528
	ds_read_b128 v[212:215], v150 offset:23552
	global_load_lds_dwordx4 v[216:217], off
	s_add_i32 m0, s6, 0x2000
	s_add_u32 s6, s72, 0x100000
	v_lshl_add_u64 v[218:219], s[72:73], 0, v[136:137]
	s_addc_u32 s7, s73, 0
	s_add_i32 s16, s83, s27
	global_load_lds_dwordx4 v[218:219], off
	s_mov_b32 m0, s16
	v_lshl_add_u64 v[222:223], s[74:75], 0, v[134:135]
	global_load_lds_dwordx4 v132, s[6:7]
	s_add_i32 m0, s16, 0x2000
	s_nop 0
	global_load_lds_dwordx4 v136, s[6:7]
	v_lshl_add_u64 v[220:221], s[74:75], 0, v[130:131]
	s_mov_b32 m0, s28
	s_nop 0
	global_load_lds_dwordx4 v[220:221], off
	s_mov_b32 m0, s29
	s_nop 0
	global_load_lds_dwordx4 v[222:223], off
	s_waitcnt vmcnt(8)
	s_waitcnt lgkmcnt(0)
	s_setprio 1
	s_barrier
	v_mfma_f32_16x16x32_bf16 v[62:65], v[142:145], v[182:185], v[62:65]
	v_mfma_f32_16x16x32_bf16 v[58:61], v[156:159], v[182:185], v[58:61]
	v_mfma_f32_16x16x32_bf16 v[46:49], v[142:145], v[192:195], v[46:49]
	v_mfma_f32_16x16x32_bf16 v[42:45], v[156:159], v[192:195], v[42:45]
	v_mfma_f32_16x16x32_bf16 v[30:33], v[142:145], v[200:203], v[30:33]
	v_mfma_f32_16x16x32_bf16 v[26:29], v[156:159], v[200:203], v[26:29]
	v_mfma_f32_16x16x32_bf16 v[14:17], v[142:145], v[208:211], v[14:17]
	v_mfma_f32_16x16x32_bf16 v[10:13], v[156:159], v[208:211], v[10:13]
	v_mfma_f32_16x16x32_bf16 v[62:65], v[152:155], v[188:191], v[62:65]
	v_mfma_f32_16x16x32_bf16 v[58:61], v[160:163], v[188:191], v[58:61]
	v_mfma_f32_16x16x32_bf16 v[46:49], v[152:155], v[196:199], v[46:49]
	v_mfma_f32_16x16x32_bf16 v[42:45], v[160:163], v[196:199], v[42:45]
	v_mfma_f32_16x16x32_bf16 v[30:33], v[152:155], v[204:207], v[30:33]
	v_mfma_f32_16x16x32_bf16 v[26:29], v[160:163], v[204:207], v[26:29]
	v_mfma_f32_16x16x32_bf16 v[14:17], v[152:155], v[212:215], v[14:17]
	v_mfma_f32_16x16x32_bf16 v[10:13], v[160:163], v[212:215], v[10:13]
	v_mfma_f32_16x16x32_bf16 v[54:57], v[166:169], v[182:185], v[54:57]
	v_mfma_f32_16x16x32_bf16 v[50:53], v[174:177], v[182:185], v[50:53]
	v_mfma_f32_16x16x32_bf16 v[38:41], v[166:169], v[192:195], v[38:41]
	v_mfma_f32_16x16x32_bf16 v[34:37], v[174:177], v[192:195], v[34:37]
	v_mfma_f32_16x16x32_bf16 v[22:25], v[166:169], v[200:203], v[22:25]
	v_mfma_f32_16x16x32_bf16 v[18:21], v[174:177], v[200:203], v[18:21]
	v_mfma_f32_16x16x32_bf16 v[6:9], v[166:169], v[208:211], v[6:9]
	v_mfma_f32_16x16x32_bf16 v[2:5], v[174:177], v[208:211], v[2:5]
	v_mfma_f32_16x16x32_bf16 v[54:57], v[170:173], v[188:191], v[54:57]
	v_mfma_f32_16x16x32_bf16 v[50:53], v[178:181], v[188:191], v[50:53]
	v_mfma_f32_16x16x32_bf16 v[38:41], v[170:173], v[196:199], v[38:41]
	v_mfma_f32_16x16x32_bf16 v[34:37], v[178:181], v[196:199], v[34:37]
	v_mfma_f32_16x16x32_bf16 v[22:25], v[170:173], v[204:207], v[22:25]
	v_mfma_f32_16x16x32_bf16 v[18:21], v[178:181], v[204:207], v[18:21]
	v_mfma_f32_16x16x32_bf16 v[6:9], v[170:173], v[212:215], v[6:9]
	v_mfma_f32_16x16x32_bf16 v[2:5], v[178:181], v[212:215], v[2:5]
	s_barrier
	s_setprio 0
	s_add_i32 s16, 0, 0x18000
	s_add_i32 s17, 0, 0x1c000
	v_add_u32_e32 v160, s16, v146
	v_add_u32_e32 v165, s17, v146
	ds_read_b128 v[142:145], v160
	ds_read_b128 v[152:155], v160 offset:1024
	ds_read_b128 v[156:159], v160 offset:2048
	ds_read_b128 v[160:163], v160 offset:3072
	ds_read_b128 v[166:169], v165
	ds_read_b128 v[170:173], v165 offset:1024
	ds_read_b128 v[174:177], v165 offset:2048
	ds_read_b128 v[178:181], v165 offset:3072
	s_add_u32 s6, s74, 0x100000
	s_addc_u32 s7, s75, 0
	s_mov_b32 m0, s56
	ds_read_b128 v[182:185], v150 offset:32768
	ds_read_b128 v[188:191], v150 offset:33792
	ds_read_b128 v[192:195], v150 offset:34816
	ds_read_b128 v[196:199], v150 offset:35840
	ds_read_b128 v[200:203], v150 offset:36864
	ds_read_b128 v[204:207], v150 offset:37888
	ds_read_b128 v[208:211], v150 offset:38912
	ds_read_b128 v[212:215], v150 offset:39936
	global_load_lds_dwordx4 v130, s[6:7]
	s_mov_b32 m0, s57
	s_nop 0
	global_load_lds_dwordx4 v134, s[6:7]
	s_waitcnt vmcnt(8)
	s_waitcnt lgkmcnt(0)
	s_setprio 1
	s_barrier
	v_mfma_f32_16x16x32_bf16 v[126:129], v[142:145], v[182:185], v[126:129]
	v_mfma_f32_16x16x32_bf16 v[122:125], v[156:159], v[182:185], v[122:125]
	v_mfma_f32_16x16x32_bf16 v[110:113], v[142:145], v[192:195], v[110:113]
	v_mfma_f32_16x16x32_bf16 v[106:109], v[156:159], v[192:195], v[106:109]
	v_mfma_f32_16x16x32_bf16 v[94:97], v[142:145], v[200:203], v[94:97]
	v_mfma_f32_16x16x32_bf16 v[90:93], v[156:159], v[200:203], v[90:93]
	v_mfma_f32_16x16x32_bf16 v[78:81], v[142:145], v[208:211], v[78:81]
	v_mfma_f32_16x16x32_bf16 v[74:77], v[156:159], v[208:211], v[74:77]
	v_mfma_f32_16x16x32_bf16 v[126:129], v[152:155], v[188:191], v[126:129]
	v_mfma_f32_16x16x32_bf16 v[122:125], v[160:163], v[188:191], v[122:125]
	v_mfma_f32_16x16x32_bf16 v[110:113], v[152:155], v[196:199], v[110:113]
	v_mfma_f32_16x16x32_bf16 v[106:109], v[160:163], v[196:199], v[106:109]
	v_mfma_f32_16x16x32_bf16 v[94:97], v[152:155], v[204:207], v[94:97]
	v_mfma_f32_16x16x32_bf16 v[90:93], v[160:163], v[204:207], v[90:93]
	v_mfma_f32_16x16x32_bf16 v[78:81], v[152:155], v[212:215], v[78:81]
	v_mfma_f32_16x16x32_bf16 v[74:77], v[160:163], v[212:215], v[74:77]
	v_mfma_f32_16x16x32_bf16 v[118:121], v[166:169], v[182:185], v[118:121]
	v_mfma_f32_16x16x32_bf16 v[114:117], v[174:177], v[182:185], v[114:117]
	v_mfma_f32_16x16x32_bf16 v[102:105], v[166:169], v[192:195], v[102:105]
	v_mfma_f32_16x16x32_bf16 v[98:101], v[174:177], v[192:195], v[98:101]
	v_mfma_f32_16x16x32_bf16 v[86:89], v[166:169], v[200:203], v[86:89]
	v_mfma_f32_16x16x32_bf16 v[82:85], v[174:177], v[200:203], v[82:85]
	v_mfma_f32_16x16x32_bf16 v[70:73], v[166:169], v[208:211], v[70:73]
	v_mfma_f32_16x16x32_bf16 v[66:69], v[174:177], v[208:211], v[66:69]
	v_mfma_f32_16x16x32_bf16 v[118:121], v[170:173], v[188:191], v[118:121]
	v_mfma_f32_16x16x32_bf16 v[114:117], v[178:181], v[188:191], v[114:117]
	v_mfma_f32_16x16x32_bf16 v[102:105], v[170:173], v[196:199], v[102:105]
	v_mfma_f32_16x16x32_bf16 v[98:101], v[178:181], v[196:199], v[98:101]
	v_mfma_f32_16x16x32_bf16 v[86:89], v[170:173], v[204:207], v[86:89]
	v_mfma_f32_16x16x32_bf16 v[82:85], v[178:181], v[204:207], v[82:85]
	v_mfma_f32_16x16x32_bf16 v[70:73], v[170:173], v[212:215], v[70:73]
	v_mfma_f32_16x16x32_bf16 v[66:69], v[178:181], v[212:215], v[66:69]
	s_barrier
	s_setprio 0
	s_add_i32 s6, s16, s27
	v_lshl_add_u64 v[216:217], v[216:217], 0, s[40:41]
	s_mov_b32 m0, s6
	ds_read_b128 v[182:185], v150 offset:49152
	ds_read_b128 v[188:191], v150 offset:50176
	ds_read_b128 v[192:195], v150 offset:51200
	ds_read_b128 v[196:199], v150 offset:52224
	ds_read_b128 v[200:203], v150 offset:53248
	ds_read_b128 v[204:207], v150 offset:54272
	ds_read_b128 v[208:211], v150 offset:55296
	ds_read_b128 v[212:215], v150 offset:56320
	global_load_lds_dwordx4 v[216:217], off
	s_add_i32 m0, s6, 0x2000
	s_add_u32 s6, s72, 0x100080
	v_lshl_add_u64 v[216:217], v[218:219], 0, s[40:41]
	s_addc_u32 s7, s73, 0
	s_add_i32 s16, s17, s27
	global_load_lds_dwordx4 v[216:217], off
	s_mov_b32 m0, s16
	s_nop 0
	global_load_lds_dwordx4 v132, s[6:7]
	s_add_i32 m0, s16, 0x2000
	s_nop 0
	global_load_lds_dwordx4 v136, s[6:7]
	v_lshl_add_u64 v[216:217], v[220:221], 0, s[40:41]
	s_mov_b32 m0, s77
	s_nop 0
	global_load_lds_dwordx4 v[216:217], off
	v_lshl_add_u64 v[216:217], v[222:223], 0, s[40:41]
	s_mov_b32 m0, s78
	s_nop 0
	global_load_lds_dwordx4 v[216:217], off
	s_add_i32 s86, s86, 2
	s_add_u32 s84, s84, 0x100
	s_addc_u32 s85, s85, 0
	s_add_u32 s70, s70, 0x100
	s_addc_u32 s71, s71, 0
	s_cmp_gt_u32 s86, 61
	s_waitcnt vmcnt(8)
	s_waitcnt lgkmcnt(0)
	s_setprio 1
	s_barrier
	v_mfma_f32_16x16x32_bf16 v[62:65], v[142:145], v[182:185], v[62:65]
	v_mfma_f32_16x16x32_bf16 v[58:61], v[156:159], v[182:185], v[58:61]
	v_mfma_f32_16x16x32_bf16 v[46:49], v[142:145], v[192:195], v[46:49]
	v_mfma_f32_16x16x32_bf16 v[42:45], v[156:159], v[192:195], v[42:45]
	v_mfma_f32_16x16x32_bf16 v[30:33], v[142:145], v[200:203], v[30:33]
	v_mfma_f32_16x16x32_bf16 v[26:29], v[156:159], v[200:203], v[26:29]
	v_mfma_f32_16x16x32_bf16 v[14:17], v[142:145], v[208:211], v[14:17]
	v_mfma_f32_16x16x32_bf16 v[10:13], v[156:159], v[208:211], v[10:13]
	v_mfma_f32_16x16x32_bf16 v[62:65], v[152:155], v[188:191], v[62:65]
	v_mfma_f32_16x16x32_bf16 v[58:61], v[160:163], v[188:191], v[58:61]
	v_mfma_f32_16x16x32_bf16 v[46:49], v[152:155], v[196:199], v[46:49]
	v_mfma_f32_16x16x32_bf16 v[42:45], v[160:163], v[196:199], v[42:45]
	v_mfma_f32_16x16x32_bf16 v[30:33], v[152:155], v[204:207], v[30:33]
	v_mfma_f32_16x16x32_bf16 v[26:29], v[160:163], v[204:207], v[26:29]
	v_mfma_f32_16x16x32_bf16 v[14:17], v[152:155], v[212:215], v[14:17]
	v_mfma_f32_16x16x32_bf16 v[10:13], v[160:163], v[212:215], v[10:13]
	v_mfma_f32_16x16x32_bf16 v[54:57], v[166:169], v[182:185], v[54:57]
	v_mfma_f32_16x16x32_bf16 v[50:53], v[174:177], v[182:185], v[50:53]
	v_mfma_f32_16x16x32_bf16 v[38:41], v[166:169], v[192:195], v[38:41]
	v_mfma_f32_16x16x32_bf16 v[34:37], v[174:177], v[192:195], v[34:37]
	v_mfma_f32_16x16x32_bf16 v[22:25], v[166:169], v[200:203], v[22:25]
	v_mfma_f32_16x16x32_bf16 v[18:21], v[174:177], v[200:203], v[18:21]
	v_mfma_f32_16x16x32_bf16 v[6:9], v[166:169], v[208:211], v[6:9]
	v_mfma_f32_16x16x32_bf16 v[2:5], v[174:177], v[208:211], v[2:5]
	v_mfma_f32_16x16x32_bf16 v[54:57], v[170:173], v[188:191], v[54:57]
	v_mfma_f32_16x16x32_bf16 v[50:53], v[178:181], v[188:191], v[50:53]
	v_mfma_f32_16x16x32_bf16 v[38:41], v[170:173], v[196:199], v[38:41]
	v_mfma_f32_16x16x32_bf16 v[34:37], v[178:181], v[196:199], v[34:37]
	v_mfma_f32_16x16x32_bf16 v[22:25], v[170:173], v[204:207], v[22:25]
	v_mfma_f32_16x16x32_bf16 v[18:21], v[178:181], v[204:207], v[18:21]
	v_mfma_f32_16x16x32_bf16 v[6:9], v[170:173], v[212:215], v[6:9]
	v_mfma_f32_16x16x32_bf16 v[2:5], v[178:181], v[212:215], v[2:5]
	s_cbranch_scc1 .Ltb8_e
	s_barrier
	s_setprio 0
	s_branch .LBB0_1689
.Ltb8_e:
	s_setprio 0
	s_and_b64 vcc, exec, s[44:45]
	s_cbranch_vccz .LBB0_1692
	s_barrier

.LBB0_1771:
	ds_read_b128 v[130:133], v185
	ds_read_b128 v[134:137], v185 offset:1024
	ds_read_b128 v[138:141], v185 offset:2048
	ds_read_b128 v[142:145], v185 offset:3072
	ds_read_b128 v[146:149], v188
	ds_read_b128 v[150:153], v188 offset:1024
	ds_read_b128 v[168:171], v188 offset:2048
	ds_read_b128 v[172:175], v188 offset:3072
	s_add_u32 s6, s8, 0xfff80080
	s_addc_u32 s7, s9, -1
	s_cmp_eq_u32 s71, 28
	s_cselect_b32 s81, s26, s7
	s_cselect_b32 s80, s27, s6
	s_cselect_b32 s79, s28, s41
	s_cselect_b32 s78, s29, s40
	s_add_i32 m0, s11, 0xc000
	ds_read_b128 v[192:195], v189
	ds_read_b128 v[196:199], v189 offset:1024
	ds_read_b128 v[200:203], v189 offset:2048
	ds_read_b128 v[204:207], v189 offset:3072
	ds_read_b128 v[208:211], v189 offset:4096
	ds_read_b128 v[212:215], v189 offset:5120
	ds_read_b128 v[216:219], v189 offset:6144
	ds_read_b128 v[220:223], v189 offset:7168
	global_load_lds_dwordx4 v162, s[8:9]
	s_add_i32 m0, s11, 0xe000
	s_nop 0
	global_load_lds_dwordx4 v166, s[8:9]
	s_waitcnt vmcnt(8)
	s_waitcnt lgkmcnt(0)
	s_setprio 1
	s_barrier
	v_mfma_i32_16x16x64_i8 v[126:129], v[130:133], v[192:195], v[126:129]
	v_mfma_i32_16x16x64_i8 v[122:125], v[138:141], v[192:195], v[122:125]
	v_mfma_i32_16x16x64_i8 v[110:113], v[130:133], v[200:203], v[110:113]
	v_mfma_i32_16x16x64_i8 v[106:109], v[138:141], v[200:203], v[106:109]
	v_mfma_i32_16x16x64_i8 v[94:97], v[130:133], v[208:211], v[94:97]
	v_mfma_i32_16x16x64_i8 v[90:93], v[138:141], v[208:211], v[90:93]
	v_mfma_i32_16x16x64_i8 v[78:81], v[130:133], v[216:219], v[78:81]
	v_mfma_i32_16x16x64_i8 v[74:77], v[138:141], v[216:219], v[74:77]
	v_mfma_i32_16x16x64_i8 v[126:129], v[134:137], v[196:199], v[126:129]
	v_mfma_i32_16x16x64_i8 v[122:125], v[142:145], v[196:199], v[122:125]
	v_mfma_i32_16x16x64_i8 v[110:113], v[134:137], v[204:207], v[110:113]
	v_mfma_i32_16x16x64_i8 v[106:109], v[142:145], v[204:207], v[106:109]
	v_mfma_i32_16x16x64_i8 v[94:97], v[134:137], v[212:215], v[94:97]
	v_mfma_i32_16x16x64_i8 v[90:93], v[142:145], v[212:215], v[90:93]
	v_mfma_i32_16x16x64_i8 v[78:81], v[134:137], v[220:223], v[78:81]
	v_mfma_i32_16x16x64_i8 v[74:77], v[142:145], v[220:223], v[74:77]
	v_mfma_i32_16x16x64_i8 v[118:121], v[146:149], v[192:195], v[118:121]
	v_mfma_i32_16x16x64_i8 v[114:117], v[168:171], v[192:195], v[114:117]
	v_mfma_i32_16x16x64_i8 v[102:105], v[146:149], v[200:203], v[102:105]
	v_mfma_i32_16x16x64_i8 v[98:101], v[168:171], v[200:203], v[98:101]
	v_mfma_i32_16x16x64_i8 v[86:89], v[146:149], v[208:211], v[86:89]
	v_mfma_i32_16x16x64_i8 v[82:85], v[168:171], v[208:211], v[82:85]
	v_mfma_i32_16x16x64_i8 v[70:73], v[146:149], v[216:219], v[70:73]
	v_mfma_i32_16x16x64_i8 v[66:69], v[168:171], v[216:219], v[66:69]
	v_mfma_i32_16x16x64_i8 v[118:121], v[150:153], v[196:199], v[118:121]
	v_mfma_i32_16x16x64_i8 v[114:117], v[172:175], v[196:199], v[114:117]
	v_mfma_i32_16x16x64_i8 v[102:105], v[150:153], v[204:207], v[102:105]
	v_mfma_i32_16x16x64_i8 v[98:101], v[172:175], v[204:207], v[98:101]
	v_mfma_i32_16x16x64_i8 v[86:89], v[150:153], v[212:215], v[86:89]
	v_mfma_i32_16x16x64_i8 v[82:85], v[172:175], v[212:215], v[82:85]
	v_mfma_i32_16x16x64_i8 v[70:73], v[150:153], v[220:223], v[70:73]
	v_mfma_i32_16x16x64_i8 v[66:69], v[172:175], v[220:223], v[66:69]
	s_barrier
	s_setprio 0
	s_add_i32 s6, s87, s67
	v_lshl_add_u64 v[176:177], s[78:79], 0, v[156:157]
	s_mov_b32 m0, s6
	ds_read_b128 v[192:195], v189 offset:16384
	ds_read_b128 v[196:199], v189 offset:17408
	ds_read_b128 v[200:203], v189 offset:18432
	ds_read_b128 v[204:207], v189 offset:19456
	ds_read_b128 v[208:211], v189 offset:20480
	ds_read_b128 v[212:215], v189 offset:21504
	ds_read_b128 v[216:219], v189 offset:22528
	ds_read_b128 v[220:223], v189 offset:23552
	global_load_lds_dwordx4 v[176:177], off
	s_add_i32 m0, s6, 0x2000
	s_add_u32 s6, s78, 0x80000
	v_lshl_add_u64 v[182:183], s[78:79], 0, v[160:161]
	s_addc_u32 s7, s79, 0
	s_add_i32 s16, s88, s67
	global_load_lds_dwordx4 v[182:183], off
	s_mov_b32 m0, s16
	v_lshl_add_u64 v[226:227], s[80:81], 0, v[158:159]
	global_load_lds_dwordx4 v156, s[6:7]
	s_add_i32 m0, s16, 0x2000
	s_nop 0
	global_load_lds_dwordx4 v160, s[6:7]
	v_lshl_add_u64 v[224:225], s[80:81], 0, v[154:155]
	s_mov_b32 m0, s11
	s_nop 0
	global_load_lds_dwordx4 v[224:225], off
	s_mov_b32 m0, s56
	s_nop 0
	global_load_lds_dwordx4 v[226:227], off
	s_waitcnt vmcnt(8)
	s_waitcnt lgkmcnt(0)
	s_setprio 1
	s_barrier
	v_mfma_i32_16x16x64_i8 v[62:65], v[130:133], v[192:195], v[62:65]
	v_mfma_i32_16x16x64_i8 v[58:61], v[138:141], v[192:195], v[58:61]
	v_mfma_i32_16x16x64_i8 v[46:49], v[130:133], v[200:203], v[46:49]
	v_mfma_i32_16x16x64_i8 v[42:45], v[138:141], v[200:203], v[42:45]
	v_mfma_i32_16x16x64_i8 v[30:33], v[130:133], v[208:211], v[30:33]
	v_mfma_i32_16x16x64_i8 v[26:29], v[138:141], v[208:211], v[26:29]
	v_mfma_i32_16x16x64_i8 v[14:17], v[130:133], v[216:219], v[14:17]
	v_mfma_i32_16x16x64_i8 v[10:13], v[138:141], v[216:219], v[10:13]
	v_mfma_i32_16x16x64_i8 v[62:65], v[134:137], v[196:199], v[62:65]
	v_mfma_i32_16x16x64_i8 v[58:61], v[142:145], v[196:199], v[58:61]
	v_mfma_i32_16x16x64_i8 v[46:49], v[134:137], v[204:207], v[46:49]
	v_mfma_i32_16x16x64_i8 v[42:45], v[142:145], v[204:207], v[42:45]
	v_mfma_i32_16x16x64_i8 v[30:33], v[134:137], v[212:215], v[30:33]
	v_mfma_i32_16x16x64_i8 v[26:29], v[142:145], v[212:215], v[26:29]
	v_mfma_i32_16x16x64_i8 v[14:17], v[134:137], v[220:223], v[14:17]
	v_mfma_i32_16x16x64_i8 v[10:13], v[142:145], v[220:223], v[10:13]
	v_mfma_i32_16x16x64_i8 v[54:57], v[146:149], v[192:195], v[54:57]
	v_mfma_i32_16x16x64_i8 v[50:53], v[168:171], v[192:195], v[50:53]
	v_mfma_i32_16x16x64_i8 v[38:41], v[146:149], v[200:203], v[38:41]
	v_mfma_i32_16x16x64_i8 v[34:37], v[168:171], v[200:203], v[34:37]
	v_mfma_i32_16x16x64_i8 v[22:25], v[146:149], v[208:211], v[22:25]
	v_mfma_i32_16x16x64_i8 v[18:21], v[168:171], v[208:211], v[18:21]
	v_mfma_i32_16x16x64_i8 v[6:9], v[146:149], v[216:219], v[6:9]
	v_mfma_i32_16x16x64_i8 v[2:5], v[168:171], v[216:219], v[2:5]
	v_mfma_i32_16x16x64_i8 v[54:57], v[150:153], v[196:199], v[54:57]
	v_mfma_i32_16x16x64_i8 v[50:53], v[172:175], v[196:199], v[50:53]
	v_mfma_i32_16x16x64_i8 v[38:41], v[150:153], v[204:207], v[38:41]
	v_mfma_i32_16x16x64_i8 v[34:37], v[172:175], v[204:207], v[34:37]
	v_mfma_i32_16x16x64_i8 v[22:25], v[150:153], v[212:215], v[22:25]
	v_mfma_i32_16x16x64_i8 v[18:21], v[172:175], v[212:215], v[18:21]
	v_mfma_i32_16x16x64_i8 v[6:9], v[150:153], v[220:223], v[6:9]
	v_mfma_i32_16x16x64_i8 v[2:5], v[172:175], v[220:223], v[2:5]
	s_barrier
	s_setprio 0
	s_add_i32 s16, 0, 0x18000
	s_add_i32 s17, 0, 0x1c000
	v_add_u32_e32 v142, s16, v179
	v_add_u32_e32 v172, s17, v179
	ds_read_b128 v[130:133], v142
	ds_read_b128 v[134:137], v142 offset:1024
	ds_read_b128 v[138:141], v142 offset:2048
	ds_read_b128 v[142:145], v142 offset:3072
	ds_read_b128 v[146:149], v172
	ds_read_b128 v[150:153], v172 offset:1024
	ds_read_b128 v[168:171], v172 offset:2048
	ds_read_b128 v[172:175], v172 offset:3072
	s_add_u32 s6, s80, 0x80000
	s_addc_u32 s7, s81, 0
	s_mov_b32 m0, s57
	ds_read_b128 v[192:195], v189 offset:32768
	ds_read_b128 v[196:199], v189 offset:33792
	ds_read_b128 v[200:203], v189 offset:34816
	ds_read_b128 v[204:207], v189 offset:35840
	ds_read_b128 v[208:211], v189 offset:36864
	ds_read_b128 v[212:215], v189 offset:37888
	ds_read_b128 v[216:219], v189 offset:38912
	ds_read_b128 v[220:223], v189 offset:39936
	global_load_lds_dwordx4 v154, s[6:7]
	s_mov_b32 m0, s82
	s_nop 0
	global_load_lds_dwordx4 v158, s[6:7]
	s_waitcnt vmcnt(8)
	s_waitcnt lgkmcnt(0)
	s_setprio 1
	s_barrier
	v_mfma_i32_16x16x64_i8 v[126:129], v[130:133], v[192:195], v[126:129]
	v_mfma_i32_16x16x64_i8 v[122:125], v[138:141], v[192:195], v[122:125]
	v_mfma_i32_16x16x64_i8 v[110:113], v[130:133], v[200:203], v[110:113]
	v_mfma_i32_16x16x64_i8 v[106:109], v[138:141], v[200:203], v[106:109]
	v_mfma_i32_16x16x64_i8 v[94:97], v[130:133], v[208:211], v[94:97]
	v_mfma_i32_16x16x64_i8 v[90:93], v[138:141], v[208:211], v[90:93]
	v_mfma_i32_16x16x64_i8 v[78:81], v[130:133], v[216:219], v[78:81]
	v_mfma_i32_16x16x64_i8 v[74:77], v[138:141], v[216:219], v[74:77]
	v_mfma_i32_16x16x64_i8 v[126:129], v[134:137], v[196:199], v[126:129]
	v_mfma_i32_16x16x64_i8 v[122:125], v[142:145], v[196:199], v[122:125]
	v_mfma_i32_16x16x64_i8 v[110:113], v[134:137], v[204:207], v[110:113]
	v_mfma_i32_16x16x64_i8 v[106:109], v[142:145], v[204:207], v[106:109]
	v_mfma_i32_16x16x64_i8 v[94:97], v[134:137], v[212:215], v[94:97]
	v_mfma_i32_16x16x64_i8 v[90:93], v[142:145], v[212:215], v[90:93]
	v_mfma_i32_16x16x64_i8 v[78:81], v[134:137], v[220:223], v[78:81]
	v_mfma_i32_16x16x64_i8 v[74:77], v[142:145], v[220:223], v[74:77]
	v_mfma_i32_16x16x64_i8 v[118:121], v[146:149], v[192:195], v[118:121]
	v_mfma_i32_16x16x64_i8 v[114:117], v[168:171], v[192:195], v[114:117]
	v_mfma_i32_16x16x64_i8 v[102:105], v[146:149], v[200:203], v[102:105]
	v_mfma_i32_16x16x64_i8 v[98:101], v[168:171], v[200:203], v[98:101]
	v_mfma_i32_16x16x64_i8 v[86:89], v[146:149], v[208:211], v[86:89]
	v_mfma_i32_16x16x64_i8 v[82:85], v[168:171], v[208:211], v[82:85]
	v_mfma_i32_16x16x64_i8 v[70:73], v[146:149], v[216:219], v[70:73]
	v_mfma_i32_16x16x64_i8 v[66:69], v[168:171], v[216:219], v[66:69]
	v_mfma_i32_16x16x64_i8 v[118:121], v[150:153], v[196:199], v[118:121]
	v_mfma_i32_16x16x64_i8 v[114:117], v[172:175], v[196:199], v[114:117]
	v_mfma_i32_16x16x64_i8 v[102:105], v[150:153], v[204:207], v[102:105]
	v_mfma_i32_16x16x64_i8 v[98:101], v[172:175], v[204:207], v[98:101]
	v_mfma_i32_16x16x64_i8 v[86:89], v[150:153], v[212:215], v[86:89]
	v_mfma_i32_16x16x64_i8 v[82:85], v[172:175], v[212:215], v[82:85]
	v_mfma_i32_16x16x64_i8 v[70:73], v[150:153], v[220:223], v[70:73]
	v_mfma_i32_16x16x64_i8 v[66:69], v[172:175], v[220:223], v[66:69]
	s_barrier
	s_setprio 0
	s_add_i32 s6, s16, s67
	v_lshl_add_u64 v[176:177], v[176:177], 0, s[62:63]
	s_mov_b32 m0, s6
	ds_read_b128 v[192:195], v189 offset:49152
	ds_read_b128 v[196:199], v189 offset:50176
	ds_read_b128 v[200:203], v189 offset:51200
	ds_read_b128 v[204:207], v189 offset:52224
	ds_read_b128 v[208:211], v189 offset:53248
	ds_read_b128 v[212:215], v189 offset:54272
	ds_read_b128 v[216:219], v189 offset:55296
	ds_read_b128 v[220:223], v189 offset:56320
	global_load_lds_dwordx4 v[176:177], off
	s_add_i32 m0, s6, 0x2000
	s_add_u32 s6, s78, 0x80080
	v_lshl_add_u64 v[176:177], v[182:183], 0, s[62:63]
	s_addc_u32 s7, s79, 0
	s_add_i32 s16, s17, s67
	global_load_lds_dwordx4 v[176:177], off
	s_mov_b32 m0, s16
	s_nop 0
	global_load_lds_dwordx4 v156, s[6:7]
	s_add_i32 m0, s16, 0x2000
	s_nop 0
	global_load_lds_dwordx4 v160, s[6:7]
	v_lshl_add_u64 v[176:177], v[224:225], 0, s[62:63]
	s_mov_b32 m0, s84
	s_nop 0
	global_load_lds_dwordx4 v[176:177], off
	v_lshl_add_u64 v[176:177], v[226:227], 0, s[62:63]
	s_mov_b32 m0, s85
	s_nop 0
	global_load_lds_dwordx4 v[176:177], off
	s_add_i32 s71, s71, 2
	s_add_u32 s8, s8, 0x100
	s_addc_u32 s9, s9, 0
	s_add_u32 s40, s40, 0x100
	s_addc_u32 s41, s41, 0
	s_cmp_gt_u32 s71, 29
	s_waitcnt vmcnt(8)
	s_waitcnt lgkmcnt(0)
	s_setprio 1
	s_barrier
	v_mfma_i32_16x16x64_i8 v[62:65], v[130:133], v[192:195], v[62:65]
	v_mfma_i32_16x16x64_i8 v[58:61], v[138:141], v[192:195], v[58:61]
	v_mfma_i32_16x16x64_i8 v[46:49], v[130:133], v[200:203], v[46:49]
	v_mfma_i32_16x16x64_i8 v[42:45], v[138:141], v[200:203], v[42:45]
	v_mfma_i32_16x16x64_i8 v[30:33], v[130:133], v[208:211], v[30:33]
	v_mfma_i32_16x16x64_i8 v[26:29], v[138:141], v[208:211], v[26:29]
	v_mfma_i32_16x16x64_i8 v[14:17], v[130:133], v[216:219], v[14:17]
	v_mfma_i32_16x16x64_i8 v[10:13], v[138:141], v[216:219], v[10:13]
	v_mfma_i32_16x16x64_i8 v[62:65], v[134:137], v[196:199], v[62:65]
	v_mfma_i32_16x16x64_i8 v[58:61], v[142:145], v[196:199], v[58:61]
	v_mfma_i32_16x16x64_i8 v[46:49], v[134:137], v[204:207], v[46:49]
	v_mfma_i32_16x16x64_i8 v[42:45], v[142:145], v[204:207], v[42:45]
	v_mfma_i32_16x16x64_i8 v[30:33], v[134:137], v[212:215], v[30:33]
	v_mfma_i32_16x16x64_i8 v[26:29], v[142:145], v[212:215], v[26:29]
	v_mfma_i32_16x16x64_i8 v[14:17], v[134:137], v[220:223], v[14:17]
	v_mfma_i32_16x16x64_i8 v[10:13], v[142:145], v[220:223], v[10:13]
	v_mfma_i32_16x16x64_i8 v[54:57], v[146:149], v[192:195], v[54:57]
	v_mfma_i32_16x16x64_i8 v[50:53], v[168:171], v[192:195], v[50:53]
	v_mfma_i32_16x16x64_i8 v[38:41], v[146:149], v[200:203], v[38:41]
	v_mfma_i32_16x16x64_i8 v[34:37], v[168:171], v[200:203], v[34:37]
	v_mfma_i32_16x16x64_i8 v[22:25], v[146:149], v[208:211], v[22:25]
	v_mfma_i32_16x16x64_i8 v[18:21], v[168:171], v[208:211], v[18:21]
	v_mfma_i32_16x16x64_i8 v[6:9], v[146:149], v[216:219], v[6:9]
	v_mfma_i32_16x16x64_i8 v[2:5], v[168:171], v[216:219], v[2:5]
	v_mfma_i32_16x16x64_i8 v[54:57], v[150:153], v[196:199], v[54:57]
	v_mfma_i32_16x16x64_i8 v[50:53], v[172:175], v[196:199], v[50:53]
	v_mfma_i32_16x16x64_i8 v[38:41], v[150:153], v[204:207], v[38:41]
	v_mfma_i32_16x16x64_i8 v[34:37], v[172:175], v[204:207], v[34:37]
	v_mfma_i32_16x16x64_i8 v[22:25], v[150:153], v[212:215], v[22:25]
	v_mfma_i32_16x16x64_i8 v[18:21], v[172:175], v[212:215], v[18:21]
	v_mfma_i32_16x16x64_i8 v[6:9], v[150:153], v[220:223], v[6:9]
	v_mfma_i32_16x16x64_i8 v[2:5], v[172:175], v[220:223], v[2:5]
	s_cbranch_scc1 .Ltb9_e
	s_barrier
	s_setprio 0
	s_branch .LBB0_1771
.Ltb9_e:
	s_setprio 0
	s_and_b64 vcc, exec, s[64:65]
	s_cbranch_vccz .LBB0_1774
	s_barrier

.LBB0_1984:
	ds_read_b128 v[142:145], v149
	ds_read_b128 v[154:157], v149 offset:1024
	ds_read_b128 v[158:161], v149 offset:2048
	ds_read_b128 v[166:169], v149 offset:3072
	ds_read_b128 v[170:173], v150
	ds_read_b128 v[174:177], v150 offset:1024
	ds_read_b128 v[178:181], v150 offset:2048
	ds_read_b128 v[182:185], v150 offset:3072
	s_add_u32 s6, s72, 0xfff00080
	s_addc_u32 s7, s73, -1
	s_cmp_eq_u32 s83, 60
	s_cselect_b32 s77, s63, s7
	s_cselect_b32 s76, s69, s6
	s_cselect_b32 s75, s61, s82
	s_cselect_b32 s74, s80, s81
	s_add_i32 m0, s27, 0xc000
	ds_read_b128 v[188:191], v151
	ds_read_b128 v[192:195], v151 offset:1024
	ds_read_b128 v[196:199], v151 offset:2048
	ds_read_b128 v[200:203], v151 offset:3072
	ds_read_b128 v[204:207], v151 offset:4096
	ds_read_b128 v[208:211], v151 offset:5120
	ds_read_b128 v[212:215], v151 offset:6144
	ds_read_b128 v[216:219], v151 offset:7168
	global_load_lds_dwordx4 v140, s[72:73]
	s_add_i32 m0, s27, 0xe000
	s_nop 0
	global_load_lds_dwordx4 v138, s[72:73]
	s_waitcnt vmcnt(8)
	s_waitcnt lgkmcnt(0)
	s_setprio 1
	s_barrier
	v_mfma_f32_16x16x32_bf16 v[126:129], v[142:145], v[188:191], v[126:129]
	v_mfma_f32_16x16x32_bf16 v[122:125], v[158:161], v[188:191], v[122:125]
	v_mfma_f32_16x16x32_bf16 v[110:113], v[142:145], v[196:199], v[110:113]
	v_mfma_f32_16x16x32_bf16 v[106:109], v[158:161], v[196:199], v[106:109]
	v_mfma_f32_16x16x32_bf16 v[94:97], v[142:145], v[204:207], v[94:97]
	v_mfma_f32_16x16x32_bf16 v[90:93], v[158:161], v[204:207], v[90:93]
	v_mfma_f32_16x16x32_bf16 v[78:81], v[142:145], v[212:215], v[78:81]
	v_mfma_f32_16x16x32_bf16 v[74:77], v[158:161], v[212:215], v[74:77]
	v_mfma_f32_16x16x32_bf16 v[126:129], v[154:157], v[192:195], v[126:129]
	v_mfma_f32_16x16x32_bf16 v[122:125], v[166:169], v[192:195], v[122:125]
	v_mfma_f32_16x16x32_bf16 v[110:113], v[154:157], v[200:203], v[110:113]
	v_mfma_f32_16x16x32_bf16 v[106:109], v[166:169], v[200:203], v[106:109]
	v_mfma_f32_16x16x32_bf16 v[94:97], v[154:157], v[208:211], v[94:97]
	v_mfma_f32_16x16x32_bf16 v[90:93], v[166:169], v[208:211], v[90:93]
	v_mfma_f32_16x16x32_bf16 v[78:81], v[154:157], v[216:219], v[78:81]
	v_mfma_f32_16x16x32_bf16 v[74:77], v[166:169], v[216:219], v[74:77]
	v_mfma_f32_16x16x32_bf16 v[118:121], v[170:173], v[188:191], v[118:121]
	v_mfma_f32_16x16x32_bf16 v[114:117], v[178:181], v[188:191], v[114:117]
	v_mfma_f32_16x16x32_bf16 v[102:105], v[170:173], v[196:199], v[102:105]
	v_mfma_f32_16x16x32_bf16 v[98:101], v[178:181], v[196:199], v[98:101]
	v_mfma_f32_16x16x32_bf16 v[86:89], v[170:173], v[204:207], v[86:89]
	v_mfma_f32_16x16x32_bf16 v[82:85], v[178:181], v[204:207], v[82:85]
	v_mfma_f32_16x16x32_bf16 v[70:73], v[170:173], v[212:215], v[70:73]
	v_mfma_f32_16x16x32_bf16 v[66:69], v[178:181], v[212:215], v[66:69]
	v_mfma_f32_16x16x32_bf16 v[118:121], v[174:177], v[192:195], v[118:121]
	v_mfma_f32_16x16x32_bf16 v[114:117], v[182:185], v[192:195], v[114:117]
	v_mfma_f32_16x16x32_bf16 v[102:105], v[174:177], v[200:203], v[102:105]
	v_mfma_f32_16x16x32_bf16 v[98:101], v[182:185], v[200:203], v[98:101]
	v_mfma_f32_16x16x32_bf16 v[86:89], v[174:177], v[208:211], v[86:89]
	v_mfma_f32_16x16x32_bf16 v[82:85], v[182:185], v[208:211], v[82:85]
	v_mfma_f32_16x16x32_bf16 v[70:73], v[174:177], v[216:219], v[70:73]
	v_mfma_f32_16x16x32_bf16 v[66:69], v[182:185], v[216:219], v[66:69]
	s_barrier
	s_setprio 0
	s_add_i32 s6, s78, s26
	v_lshl_add_u64 v[162:163], s[74:75], 0, v[132:133]
	s_mov_b32 m0, s6
	ds_read_b128 v[188:191], v151 offset:16384
	ds_read_b128 v[192:195], v151 offset:17408
	ds_read_b128 v[196:199], v151 offset:18432
	ds_read_b128 v[200:203], v151 offset:19456
	ds_read_b128 v[204:207], v151 offset:20480
	ds_read_b128 v[208:211], v151 offset:21504
	ds_read_b128 v[212:215], v151 offset:22528
	ds_read_b128 v[216:219], v151 offset:23552
	global_load_lds_dwordx4 v[162:163], off
	s_add_i32 m0, s6, 0x2000
	s_add_u32 s6, s74, 0x100000
	v_lshl_add_u64 v[220:221], s[74:75], 0, v[136:137]
	s_addc_u32 s7, s75, 0
	s_add_i32 s16, s79, s26
	global_load_lds_dwordx4 v[220:221], off
	s_mov_b32 m0, s16
	v_lshl_add_u64 v[224:225], s[76:77], 0, v[134:135]
	global_load_lds_dwordx4 v132, s[6:7]
	s_add_i32 m0, s16, 0x2000
	s_nop 0
	global_load_lds_dwordx4 v136, s[6:7]
	v_lshl_add_u64 v[222:223], s[76:77], 0, v[130:131]
	s_mov_b32 m0, s27
	s_nop 0
	global_load_lds_dwordx4 v[222:223], off
	s_mov_b32 m0, s28
	s_nop 0
	global_load_lds_dwordx4 v[224:225], off
	s_waitcnt vmcnt(8)
	s_waitcnt lgkmcnt(0)
	s_setprio 1
	s_barrier
	v_mfma_f32_16x16x32_bf16 v[62:65], v[142:145], v[188:191], v[62:65]
	v_mfma_f32_16x16x32_bf16 v[58:61], v[158:161], v[188:191], v[58:61]
	v_mfma_f32_16x16x32_bf16 v[46:49], v[142:145], v[196:199], v[46:49]
	v_mfma_f32_16x16x32_bf16 v[42:45], v[158:161], v[196:199], v[42:45]
	v_mfma_f32_16x16x32_bf16 v[30:33], v[142:145], v[204:207], v[30:33]
	v_mfma_f32_16x16x32_bf16 v[26:29], v[158:161], v[204:207], v[26:29]
	v_mfma_f32_16x16x32_bf16 v[14:17], v[142:145], v[212:215], v[14:17]
	v_mfma_f32_16x16x32_bf16 v[10:13], v[158:161], v[212:215], v[10:13]
	v_mfma_f32_16x16x32_bf16 v[62:65], v[154:157], v[192:195], v[62:65]
	v_mfma_f32_16x16x32_bf16 v[58:61], v[166:169], v[192:195], v[58:61]
	v_mfma_f32_16x16x32_bf16 v[46:49], v[154:157], v[200:203], v[46:49]
	v_mfma_f32_16x16x32_bf16 v[42:45], v[166:169], v[200:203], v[42:45]
	v_mfma_f32_16x16x32_bf16 v[30:33], v[154:157], v[208:211], v[30:33]
	v_mfma_f32_16x16x32_bf16 v[26:29], v[166:169], v[208:211], v[26:29]
	v_mfma_f32_16x16x32_bf16 v[14:17], v[154:157], v[216:219], v[14:17]
	v_mfma_f32_16x16x32_bf16 v[10:13], v[166:169], v[216:219], v[10:13]
	v_mfma_f32_16x16x32_bf16 v[54:57], v[170:173], v[188:191], v[54:57]
	v_mfma_f32_16x16x32_bf16 v[50:53], v[178:181], v[188:191], v[50:53]
	v_mfma_f32_16x16x32_bf16 v[38:41], v[170:173], v[196:199], v[38:41]
	v_mfma_f32_16x16x32_bf16 v[34:37], v[178:181], v[196:199], v[34:37]
	v_mfma_f32_16x16x32_bf16 v[22:25], v[170:173], v[204:207], v[22:25]
	v_mfma_f32_16x16x32_bf16 v[18:21], v[178:181], v[204:207], v[18:21]
	v_mfma_f32_16x16x32_bf16 v[6:9], v[170:173], v[212:215], v[6:9]
	v_mfma_f32_16x16x32_bf16 v[2:5], v[178:181], v[212:215], v[2:5]
	v_mfma_f32_16x16x32_bf16 v[54:57], v[174:177], v[192:195], v[54:57]
	v_mfma_f32_16x16x32_bf16 v[50:53], v[182:185], v[192:195], v[50:53]
	v_mfma_f32_16x16x32_bf16 v[38:41], v[174:177], v[200:203], v[38:41]
	v_mfma_f32_16x16x32_bf16 v[34:37], v[182:185], v[200:203], v[34:37]
	v_mfma_f32_16x16x32_bf16 v[22:25], v[174:177], v[208:211], v[22:25]
	v_mfma_f32_16x16x32_bf16 v[18:21], v[182:185], v[208:211], v[18:21]
	v_mfma_f32_16x16x32_bf16 v[6:9], v[174:177], v[216:219], v[6:9]
	v_mfma_f32_16x16x32_bf16 v[2:5], v[182:185], v[216:219], v[2:5]
	s_barrier
	s_setprio 0
	s_add_i32 s16, 0, 0x18000
	v_add_u32_e32 v153, s16, v147
	s_add_i32 s17, 0, 0x1c000
	ds_read_b128 v[142:145], v153
	ds_read_b128 v[154:157], v153 offset:1024
	ds_read_b128 v[158:161], v153 offset:2048
	ds_read_b128 v[166:169], v153 offset:3072
	v_add_u32_e32 v153, s17, v147
	ds_read_b128 v[170:173], v153
	ds_read_b128 v[174:177], v153 offset:1024
	ds_read_b128 v[178:181], v153 offset:2048
	ds_read_b128 v[182:185], v153 offset:3072
	s_add_u32 s6, s76, 0x100000
	s_addc_u32 s7, s77, 0
	s_mov_b32 m0, s29
	ds_read_b128 v[188:191], v151 offset:32768
	ds_read_b128 v[192:195], v151 offset:33792
	ds_read_b128 v[196:199], v151 offset:34816
	ds_read_b128 v[200:203], v151 offset:35840
	ds_read_b128 v[204:207], v151 offset:36864
	ds_read_b128 v[208:211], v151 offset:37888
	ds_read_b128 v[212:215], v151 offset:38912
	ds_read_b128 v[216:219], v151 offset:39936
	global_load_lds_dwordx4 v130, s[6:7]
	s_mov_b32 m0, s40
	s_nop 0
	global_load_lds_dwordx4 v134, s[6:7]
	s_waitcnt vmcnt(8)
	s_waitcnt lgkmcnt(0)
	s_setprio 1
	s_barrier
	v_mfma_f32_16x16x32_bf16 v[126:129], v[142:145], v[188:191], v[126:129]
	v_mfma_f32_16x16x32_bf16 v[122:125], v[158:161], v[188:191], v[122:125]
	v_mfma_f32_16x16x32_bf16 v[110:113], v[142:145], v[196:199], v[110:113]
	v_mfma_f32_16x16x32_bf16 v[106:109], v[158:161], v[196:199], v[106:109]
	v_mfma_f32_16x16x32_bf16 v[94:97], v[142:145], v[204:207], v[94:97]
	v_mfma_f32_16x16x32_bf16 v[90:93], v[158:161], v[204:207], v[90:93]
	v_mfma_f32_16x16x32_bf16 v[78:81], v[142:145], v[212:215], v[78:81]
	v_mfma_f32_16x16x32_bf16 v[74:77], v[158:161], v[212:215], v[74:77]
	v_mfma_f32_16x16x32_bf16 v[126:129], v[154:157], v[192:195], v[126:129]
	v_mfma_f32_16x16x32_bf16 v[122:125], v[166:169], v[192:195], v[122:125]
	v_mfma_f32_16x16x32_bf16 v[110:113], v[154:157], v[200:203], v[110:113]
	v_mfma_f32_16x16x32_bf16 v[106:109], v[166:169], v[200:203], v[106:109]
	v_mfma_f32_16x16x32_bf16 v[94:97], v[154:157], v[208:211], v[94:97]
	v_mfma_f32_16x16x32_bf16 v[90:93], v[166:169], v[208:211], v[90:93]
	v_mfma_f32_16x16x32_bf16 v[78:81], v[154:157], v[216:219], v[78:81]
	v_mfma_f32_16x16x32_bf16 v[74:77], v[166:169], v[216:219], v[74:77]
	v_mfma_f32_16x16x32_bf16 v[118:121], v[170:173], v[188:191], v[118:121]
	v_mfma_f32_16x16x32_bf16 v[114:117], v[178:181], v[188:191], v[114:117]
	v_mfma_f32_16x16x32_bf16 v[102:105], v[170:173], v[196:199], v[102:105]
	v_mfma_f32_16x16x32_bf16 v[98:101], v[178:181], v[196:199], v[98:101]
	v_mfma_f32_16x16x32_bf16 v[86:89], v[170:173], v[204:207], v[86:89]
	v_mfma_f32_16x16x32_bf16 v[82:85], v[178:181], v[204:207], v[82:85]
	v_mfma_f32_16x16x32_bf16 v[70:73], v[170:173], v[212:215], v[70:73]
	v_mfma_f32_16x16x32_bf16 v[66:69], v[178:181], v[212:215], v[66:69]
	v_mfma_f32_16x16x32_bf16 v[118:121], v[174:177], v[192:195], v[118:121]
	v_mfma_f32_16x16x32_bf16 v[114:117], v[182:185], v[192:195], v[114:117]
	v_mfma_f32_16x16x32_bf16 v[102:105], v[174:177], v[200:203], v[102:105]
	v_mfma_f32_16x16x32_bf16 v[98:101], v[182:185], v[200:203], v[98:101]
	v_mfma_f32_16x16x32_bf16 v[86:89], v[174:177], v[208:211], v[86:89]
	v_mfma_f32_16x16x32_bf16 v[82:85], v[182:185], v[208:211], v[82:85]
	v_mfma_f32_16x16x32_bf16 v[70:73], v[174:177], v[216:219], v[70:73]
	v_mfma_f32_16x16x32_bf16 v[66:69], v[182:185], v[216:219], v[66:69]
	s_barrier
	s_setprio 0
	s_add_i32 s6, s16, s26
	v_lshl_add_u64 v[162:163], v[162:163], 0, s[12:13]
	s_mov_b32 m0, s6
	ds_read_b128 v[188:191], v151 offset:49152
	ds_read_b128 v[192:195], v151 offset:50176
	ds_read_b128 v[196:199], v151 offset:51200
	ds_read_b128 v[200:203], v151 offset:52224
	ds_read_b128 v[204:207], v151 offset:53248
	ds_read_b128 v[208:211], v151 offset:54272
	ds_read_b128 v[212:215], v151 offset:55296
	ds_read_b128 v[216:219], v151 offset:56320
	global_load_lds_dwordx4 v[162:163], off
	s_add_i32 m0, s6, 0x2000
	s_add_u32 s6, s74, 0x100080
	v_lshl_add_u64 v[162:163], v[220:221], 0, s[12:13]
	s_addc_u32 s7, s75, 0
	s_add_i32 s16, s17, s26
	global_load_lds_dwordx4 v[162:163], off
	s_mov_b32 m0, s16
	s_nop 0
	global_load_lds_dwordx4 v132, s[6:7]
	s_add_i32 m0, s16, 0x2000
	s_nop 0
	global_load_lds_dwordx4 v136, s[6:7]
	v_lshl_add_u64 v[162:163], v[222:223], 0, s[12:13]
	s_mov_b32 m0, s56
	s_nop 0
	global_load_lds_dwordx4 v[162:163], off
	v_lshl_add_u64 v[162:163], v[224:225], 0, s[12:13]
	s_mov_b32 m0, s57
	s_nop 0
	global_load_lds_dwordx4 v[162:163], off
	s_add_i32 s83, s83, 2
	s_add_u32 s81, s81, 0x100
	s_addc_u32 s82, s82, 0
	s_add_u32 s72, s72, 0x100
	s_addc_u32 s73, s73, 0
	s_cmp_gt_u32 s83, 61
	s_waitcnt vmcnt(8)
	s_waitcnt lgkmcnt(0)
	s_setprio 1
	s_barrier
	v_mfma_f32_16x16x32_bf16 v[62:65], v[142:145], v[188:191], v[62:65]
	v_mfma_f32_16x16x32_bf16 v[58:61], v[158:161], v[188:191], v[58:61]
	v_mfma_f32_16x16x32_bf16 v[46:49], v[142:145], v[196:199], v[46:49]
	v_mfma_f32_16x16x32_bf16 v[42:45], v[158:161], v[196:199], v[42:45]
	v_mfma_f32_16x16x32_bf16 v[30:33], v[142:145], v[204:207], v[30:33]
	v_mfma_f32_16x16x32_bf16 v[26:29], v[158:161], v[204:207], v[26:29]
	v_mfma_f32_16x16x32_bf16 v[14:17], v[142:145], v[212:215], v[14:17]
	v_mfma_f32_16x16x32_bf16 v[10:13], v[158:161], v[212:215], v[10:13]
	v_mfma_f32_16x16x32_bf16 v[62:65], v[154:157], v[192:195], v[62:65]
	v_mfma_f32_16x16x32_bf16 v[58:61], v[166:169], v[192:195], v[58:61]
	v_mfma_f32_16x16x32_bf16 v[46:49], v[154:157], v[200:203], v[46:49]
	v_mfma_f32_16x16x32_bf16 v[42:45], v[166:169], v[200:203], v[42:45]
	v_mfma_f32_16x16x32_bf16 v[30:33], v[154:157], v[208:211], v[30:33]
	v_mfma_f32_16x16x32_bf16 v[26:29], v[166:169], v[208:211], v[26:29]
	v_mfma_f32_16x16x32_bf16 v[14:17], v[154:157], v[216:219], v[14:17]
	v_mfma_f32_16x16x32_bf16 v[10:13], v[166:169], v[216:219], v[10:13]
	v_mfma_f32_16x16x32_bf16 v[54:57], v[170:173], v[188:191], v[54:57]
	v_mfma_f32_16x16x32_bf16 v[50:53], v[178:181], v[188:191], v[50:53]
	v_mfma_f32_16x16x32_bf16 v[38:41], v[170:173], v[196:199], v[38:41]
	v_mfma_f32_16x16x32_bf16 v[34:37], v[178:181], v[196:199], v[34:37]
	v_mfma_f32_16x16x32_bf16 v[22:25], v[170:173], v[204:207], v[22:25]
	v_mfma_f32_16x16x32_bf16 v[18:21], v[178:181], v[204:207], v[18:21]
	v_mfma_f32_16x16x32_bf16 v[6:9], v[170:173], v[212:215], v[6:9]
	v_mfma_f32_16x16x32_bf16 v[2:5], v[178:181], v[212:215], v[2:5]
	v_mfma_f32_16x16x32_bf16 v[54:57], v[174:177], v[192:195], v[54:57]
	v_mfma_f32_16x16x32_bf16 v[50:53], v[182:185], v[192:195], v[50:53]
	v_mfma_f32_16x16x32_bf16 v[38:41], v[174:177], v[200:203], v[38:41]
	v_mfma_f32_16x16x32_bf16 v[34:37], v[182:185], v[200:203], v[34:37]
	v_mfma_f32_16x16x32_bf16 v[22:25], v[174:177], v[208:211], v[22:25]
	v_mfma_f32_16x16x32_bf16 v[18:21], v[182:185], v[208:211], v[18:21]
	v_mfma_f32_16x16x32_bf16 v[6:9], v[174:177], v[216:219], v[6:9]
	v_mfma_f32_16x16x32_bf16 v[2:5], v[182:185], v[216:219], v[2:5]
	s_cbranch_scc1 .Ltb12_e
	s_barrier
	s_setprio 0
	s_branch .LBB0_1984
.Ltb12_e:
	s_setprio 0
	v_lshl_add_u32 v245, s70, 8, v146
	v_lshl_or_b32 v246, s68, 8, v148
	v_lshlrev_b32_e32 v245, 13, v245
	v_lshl_add_u32 v245, v246, 1, v245
	global_load_dwordx4 v[142:145], v245, s[24:25]
	global_load_dwordx4 v[154:157], v245, s[24:25] offset:256
	s_add_u32 s68, s24, 0x20000
	s_addc_u32 s69, s25, 0
	global_load_dwordx4 v[158:161], v245, s[68:69]
	global_load_dwordx4 v[166:169], v245, s[68:69] offset:256
	s_add_u32 s68, s24, 0x40000
	s_addc_u32 s69, s25, 0
	global_load_dwordx4 v[170:173], v245, s[68:69]
	global_load_dwordx4 v[174:177], v245, s[68:69] offset:256
	s_add_u32 s68, s24, 0x60000
	s_addc_u32 s69, s25, 0
	global_load_dwordx4 v[178:181], v245, s[68:69]
	global_load_dwordx4 v[182:185], v245, s[68:69] offset:256
	s_add_u32 s68, s24, 0x100000
	s_addc_u32 s69, s25, 0
	global_load_dwordx4 v[188:191], v245, s[68:69]
	global_load_dwordx4 v[192:195], v245, s[68:69] offset:256
	s_add_u32 s68, s24, 0x120000
	s_addc_u32 s69, s25, 0
	global_load_dwordx4 v[196:199], v245, s[68:69]
	global_load_dwordx4 v[200:203], v245, s[68:69] offset:256
	s_add_u32 s68, s24, 0x140000
	s_addc_u32 s69, s25, 0
	global_load_dwordx4 v[204:207], v245, s[68:69]
	global_load_dwordx4 v[208:211], v245, s[68:69] offset:256
	s_add_u32 s68, s24, 0x160000
	s_addc_u32 s69, s25, 0
	global_load_dwordx4 v[212:215], v245, s[68:69]
	global_load_dwordx4 v[216:219], v245, s[68:69] offset:256
	s_and_b64 vcc, exec, s[44:45]
	s_cbranch_vccz .LBB0_1987
	s_barrier

.LBB0_2067:
	ds_read_b128 v[2:5], v185
	ds_read_b128 v[6:9], v185 offset:1024
	ds_read_b128 v[138:141], v185 offset:2048
	ds_read_b128 v[142:145], v185 offset:3072
	ds_read_b128 v[146:149], v186
	ds_read_b128 v[150:153], v186 offset:1024
	ds_read_b128 v[170:173], v186 offset:2048
	ds_read_b128 v[174:177], v186 offset:3072
	s_add_u32 s6, s10, 0xfff80080
	s_addc_u32 s7, s11, -1
	s_cmp_eq_u32 s85, 28
	s_cselect_b32 s15, s28, s7
	s_cselect_b32 s14, s29, s6
	s_cselect_b32 s13, s65, s84
	s_cselect_b32 s12, s67, s83
	s_add_i32 m0, s39, 0xc000
	ds_read_b128 v[178:181], v187
	ds_read_b128 v[190:193], v187 offset:1024
	ds_read_b128 v[194:197], v187 offset:2048
	ds_read_b128 v[198:201], v187 offset:3072
	ds_read_b128 v[202:205], v187 offset:4096
	ds_read_b128 v[206:209], v187 offset:5120
	ds_read_b128 v[210:213], v187 offset:6144
	ds_read_b128 v[214:217], v187 offset:7168
	global_load_lds_dwordx4 v164, s[10:11]
	s_add_i32 m0, s39, 0xe000
	s_nop 0
	global_load_lds_dwordx4 v162, s[10:11]
	s_waitcnt vmcnt(8)
	s_waitcnt lgkmcnt(0)
	s_setprio 1
	s_barrier
	v_mfma_i32_16x16x64_i8 v[134:137], v[2:5], v[178:181], v[134:137]
	v_mfma_i32_16x16x64_i8 v[126:129], v[138:141], v[178:181], v[126:129]
	v_mfma_i32_16x16x64_i8 v[118:121], v[2:5], v[194:197], v[118:121]
	v_mfma_i32_16x16x64_i8 v[110:113], v[138:141], v[194:197], v[110:113]
	v_mfma_i32_16x16x64_i8 v[102:105], v[2:5], v[202:205], v[102:105]
	v_mfma_i32_16x16x64_i8 v[94:97], v[138:141], v[202:205], v[94:97]
	v_mfma_i32_16x16x64_i8 v[86:89], v[2:5], v[210:213], v[86:89]
	v_mfma_i32_16x16x64_i8 v[78:81], v[138:141], v[210:213], v[78:81]
	v_mfma_i32_16x16x64_i8 v[134:137], v[6:9], v[190:193], v[134:137]
	v_mfma_i32_16x16x64_i8 v[126:129], v[142:145], v[190:193], v[126:129]
	v_mfma_i32_16x16x64_i8 v[118:121], v[6:9], v[198:201], v[118:121]
	v_mfma_i32_16x16x64_i8 v[110:113], v[142:145], v[198:201], v[110:113]
	v_mfma_i32_16x16x64_i8 v[102:105], v[6:9], v[206:209], v[102:105]
	v_mfma_i32_16x16x64_i8 v[94:97], v[142:145], v[206:209], v[94:97]
	v_mfma_i32_16x16x64_i8 v[86:89], v[6:9], v[214:217], v[86:89]
	v_mfma_i32_16x16x64_i8 v[78:81], v[142:145], v[214:217], v[78:81]
	v_mfma_i32_16x16x64_i8 v[130:133], v[146:149], v[178:181], v[130:133]
	v_mfma_i32_16x16x64_i8 v[122:125], v[170:173], v[178:181], v[122:125]
	v_mfma_i32_16x16x64_i8 v[114:117], v[146:149], v[194:197], v[114:117]
	v_mfma_i32_16x16x64_i8 v[106:109], v[170:173], v[194:197], v[106:109]
	v_mfma_i32_16x16x64_i8 v[98:101], v[146:149], v[202:205], v[98:101]
	v_mfma_i32_16x16x64_i8 v[90:93], v[170:173], v[202:205], v[90:93]
	v_mfma_i32_16x16x64_i8 v[82:85], v[146:149], v[210:213], v[82:85]
	v_mfma_i32_16x16x64_i8 v[74:77], v[170:173], v[210:213], v[74:77]
	v_mfma_i32_16x16x64_i8 v[130:133], v[150:153], v[190:193], v[130:133]
	v_mfma_i32_16x16x64_i8 v[122:125], v[174:177], v[190:193], v[122:125]
	v_mfma_i32_16x16x64_i8 v[114:117], v[150:153], v[198:201], v[114:117]
	v_mfma_i32_16x16x64_i8 v[106:109], v[174:177], v[198:201], v[106:109]
	v_mfma_i32_16x16x64_i8 v[98:101], v[150:153], v[206:209], v[98:101]
	v_mfma_i32_16x16x64_i8 v[90:93], v[174:177], v[206:209], v[90:93]
	v_mfma_i32_16x16x64_i8 v[82:85], v[150:153], v[214:217], v[82:85]
	v_mfma_i32_16x16x64_i8 v[74:77], v[174:177], v[214:217], v[74:77]
	s_barrier
	s_setprio 0
	s_add_i32 s6, s79, s63
	v_lshl_add_u64 v[218:219], s[12:13], 0, v[156:157]
	s_mov_b32 m0, s6
	ds_read_b128 v[178:181], v187 offset:16384
	ds_read_b128 v[190:193], v187 offset:17408
	ds_read_b128 v[194:197], v187 offset:18432
	ds_read_b128 v[198:201], v187 offset:19456
	ds_read_b128 v[202:205], v187 offset:20480
	ds_read_b128 v[206:209], v187 offset:21504
	ds_read_b128 v[210:213], v187 offset:22528
	ds_read_b128 v[214:217], v187 offset:23552
	global_load_lds_dwordx4 v[218:219], off
	s_add_i32 m0, s6, 0x2000
	s_add_u32 s6, s12, 0x80000
	v_lshl_add_u64 v[220:221], s[12:13], 0, v[160:161]
	s_addc_u32 s7, s13, 0
	s_add_i32 s16, s80, s63
	global_load_lds_dwordx4 v[220:221], off
	s_mov_b32 m0, s16
	v_lshl_add_u64 v[224:225], s[14:15], 0, v[158:159]
	global_load_lds_dwordx4 v156, s[6:7]
	s_add_i32 m0, s16, 0x2000
	s_nop 0
	global_load_lds_dwordx4 v160, s[6:7]
	v_lshl_add_u64 v[222:223], s[14:15], 0, v[154:155]
	s_mov_b32 m0, s39
	s_nop 0
	global_load_lds_dwordx4 v[222:223], off
	s_mov_b32 m0, s72
	s_nop 0
	global_load_lds_dwordx4 v[224:225], off
	s_waitcnt vmcnt(8)
	s_waitcnt lgkmcnt(0)
	s_setprio 1
	s_barrier
	v_mfma_i32_16x16x64_i8 v[70:73], v[2:5], v[178:181], v[70:73]
	v_mfma_i32_16x16x64_i8 v[62:65], v[138:141], v[178:181], v[62:65]
	v_mfma_i32_16x16x64_i8 v[54:57], v[2:5], v[194:197], v[54:57]
	v_mfma_i32_16x16x64_i8 v[46:49], v[138:141], v[194:197], v[46:49]
	v_mfma_i32_16x16x64_i8 v[38:41], v[2:5], v[202:205], v[38:41]
	v_mfma_i32_16x16x64_i8 v[30:33], v[138:141], v[202:205], v[30:33]
	v_mfma_i32_16x16x64_i8 v[2:5], v[2:5], v[210:213], v[22:25]
	v_mfma_i32_16x16x64_i8 v[70:73], v[6:9], v[190:193], v[70:73]
	v_mfma_i32_16x16x64_i8 v[62:65], v[142:145], v[190:193], v[62:65]
	v_mfma_i32_16x16x64_i8 v[54:57], v[6:9], v[198:201], v[54:57]
	v_mfma_i32_16x16x64_i8 v[46:49], v[142:145], v[198:201], v[46:49]
	v_mfma_i32_16x16x64_i8 v[38:41], v[6:9], v[206:209], v[38:41]
	v_mfma_i32_16x16x64_i8 v[30:33], v[142:145], v[206:209], v[30:33]
	v_mfma_i32_16x16x64_i8 v[2:5], v[6:9], v[214:217], v[2:5]
	v_mfma_i32_16x16x64_i8 v[6:9], v[138:141], v[210:213], v[14:17]
	v_mfma_i32_16x16x64_i8 v[6:9], v[142:145], v[214:217], v[6:9]
	v_mfma_i32_16x16x64_i8 v[14:17], v[146:149], v[178:181], v[66:69]
	v_mfma_i32_16x16x64_i8 v[66:69], v[150:153], v[190:193], v[14:17]
	v_mfma_i32_16x16x64_i8 v[14:17], v[170:173], v[178:181], v[58:61]
	v_mfma_i32_16x16x64_i8 v[58:61], v[174:177], v[190:193], v[14:17]
	v_mfma_i32_16x16x64_i8 v[14:17], v[146:149], v[194:197], v[50:53]
	v_mfma_i32_16x16x64_i8 v[50:53], v[150:153], v[198:201], v[14:17]
	v_mfma_i32_16x16x64_i8 v[14:17], v[170:173], v[194:197], v[42:45]
	v_mfma_i32_16x16x64_i8 v[42:45], v[174:177], v[198:201], v[14:17]
	v_mfma_i32_16x16x64_i8 v[14:17], v[146:149], v[202:205], v[34:37]
	v_mfma_i32_16x16x64_i8 v[34:37], v[150:153], v[206:209], v[14:17]
	v_mfma_i32_16x16x64_i8 v[14:17], v[170:173], v[202:205], v[26:29]
	v_mfma_i32_16x16x64_i8 v[26:29], v[174:177], v[206:209], v[14:17]
	v_mfma_i32_16x16x64_i8 v[14:17], v[146:149], v[210:213], v[18:21]
	v_mfma_i32_16x16x64_i8 v[10:13], v[170:173], v[210:213], v[10:13]
	v_mfma_i32_16x16x64_i8 v[18:21], v[150:153], v[214:217], v[14:17]
	v_mfma_i32_16x16x64_i8 v[10:13], v[174:177], v[214:217], v[10:13]
	s_barrier
	s_setprio 0
	s_add_i32 s16, 0, 0x18000
	s_add_i32 s17, 0, 0x1c000
	v_add_u32_e32 v142, s16, v183
	v_add_u32_e32 v174, s17, v183
	ds_read_b128 v[14:17], v142
	ds_read_b128 v[22:25], v142 offset:1024
	ds_read_b128 v[138:141], v142 offset:2048
	ds_read_b128 v[142:145], v142 offset:3072
	ds_read_b128 v[146:149], v174
	ds_read_b128 v[150:153], v174 offset:1024
	ds_read_b128 v[170:173], v174 offset:2048
	ds_read_b128 v[174:177], v174 offset:3072
	s_add_u32 s6, s14, 0x80000
	s_addc_u32 s7, s15, 0
	s_mov_b32 m0, s73
	ds_read_b128 v[178:181], v187 offset:32768
	ds_read_b128 v[190:193], v187 offset:33792
	ds_read_b128 v[194:197], v187 offset:34816
	ds_read_b128 v[198:201], v187 offset:35840
	ds_read_b128 v[202:205], v187 offset:36864
	ds_read_b128 v[206:209], v187 offset:37888
	ds_read_b128 v[210:213], v187 offset:38912
	ds_read_b128 v[214:217], v187 offset:39936
	global_load_lds_dwordx4 v154, s[6:7]
	s_mov_b32 m0, s74
	s_nop 0
	global_load_lds_dwordx4 v158, s[6:7]
	s_waitcnt vmcnt(8)
	s_waitcnt lgkmcnt(0)
	s_setprio 1
	s_barrier
	v_mfma_i32_16x16x64_i8 v[134:137], v[14:17], v[178:181], v[134:137]
	v_mfma_i32_16x16x64_i8 v[126:129], v[138:141], v[178:181], v[126:129]
	v_mfma_i32_16x16x64_i8 v[118:121], v[14:17], v[194:197], v[118:121]
	v_mfma_i32_16x16x64_i8 v[110:113], v[138:141], v[194:197], v[110:113]
	v_mfma_i32_16x16x64_i8 v[102:105], v[14:17], v[202:205], v[102:105]
	v_mfma_i32_16x16x64_i8 v[94:97], v[138:141], v[202:205], v[94:97]
	v_mfma_i32_16x16x64_i8 v[86:89], v[14:17], v[210:213], v[86:89]
	v_mfma_i32_16x16x64_i8 v[78:81], v[138:141], v[210:213], v[78:81]
	v_mfma_i32_16x16x64_i8 v[134:137], v[22:25], v[190:193], v[134:137]
	v_mfma_i32_16x16x64_i8 v[126:129], v[142:145], v[190:193], v[126:129]
	v_mfma_i32_16x16x64_i8 v[118:121], v[22:25], v[198:201], v[118:121]
	v_mfma_i32_16x16x64_i8 v[110:113], v[142:145], v[198:201], v[110:113]
	v_mfma_i32_16x16x64_i8 v[102:105], v[22:25], v[206:209], v[102:105]
	v_mfma_i32_16x16x64_i8 v[94:97], v[142:145], v[206:209], v[94:97]
	v_mfma_i32_16x16x64_i8 v[86:89], v[22:25], v[214:217], v[86:89]
	v_mfma_i32_16x16x64_i8 v[78:81], v[142:145], v[214:217], v[78:81]
	v_mfma_i32_16x16x64_i8 v[130:133], v[146:149], v[178:181], v[130:133]
	v_mfma_i32_16x16x64_i8 v[122:125], v[170:173], v[178:181], v[122:125]
	v_mfma_i32_16x16x64_i8 v[114:117], v[146:149], v[194:197], v[114:117]
	v_mfma_i32_16x16x64_i8 v[106:109], v[170:173], v[194:197], v[106:109]
	v_mfma_i32_16x16x64_i8 v[98:101], v[146:149], v[202:205], v[98:101]
	v_mfma_i32_16x16x64_i8 v[90:93], v[170:173], v[202:205], v[90:93]
	v_mfma_i32_16x16x64_i8 v[82:85], v[146:149], v[210:213], v[82:85]
	v_mfma_i32_16x16x64_i8 v[74:77], v[170:173], v[210:213], v[74:77]
	v_mfma_i32_16x16x64_i8 v[130:133], v[150:153], v[190:193], v[130:133]
	v_mfma_i32_16x16x64_i8 v[122:125], v[174:177], v[190:193], v[122:125]
	v_mfma_i32_16x16x64_i8 v[114:117], v[150:153], v[198:201], v[114:117]
	v_mfma_i32_16x16x64_i8 v[106:109], v[174:177], v[198:201], v[106:109]
	v_mfma_i32_16x16x64_i8 v[98:101], v[150:153], v[206:209], v[98:101]
	v_mfma_i32_16x16x64_i8 v[90:93], v[174:177], v[206:209], v[90:93]
	v_mfma_i32_16x16x64_i8 v[82:85], v[150:153], v[214:217], v[82:85]
	v_mfma_i32_16x16x64_i8 v[74:77], v[174:177], v[214:217], v[74:77]
	s_barrier
	s_setprio 0
	s_add_i32 s6, s16, s63
	v_lshl_add_u64 v[218:219], v[218:219], 0, s[46:47]
	s_mov_b32 m0, s6
	ds_read_b128 v[178:181], v187 offset:49152
	ds_read_b128 v[190:193], v187 offset:50176
	ds_read_b128 v[194:197], v187 offset:51200
	ds_read_b128 v[198:201], v187 offset:52224
	ds_read_b128 v[202:205], v187 offset:53248
	ds_read_b128 v[206:209], v187 offset:54272
	ds_read_b128 v[210:213], v187 offset:55296
	ds_read_b128 v[214:217], v187 offset:56320
	global_load_lds_dwordx4 v[218:219], off
	s_add_i32 m0, s6, 0x2000
	s_add_u32 s6, s12, 0x80080
	v_lshl_add_u64 v[218:219], v[220:221], 0, s[46:47]
	s_addc_u32 s7, s13, 0
	s_add_i32 s12, s17, s63
	global_load_lds_dwordx4 v[218:219], off
	s_mov_b32 m0, s12
	s_nop 0
	global_load_lds_dwordx4 v156, s[6:7]
	s_add_i32 m0, s12, 0x2000
	s_nop 0
	global_load_lds_dwordx4 v160, s[6:7]
	v_lshl_add_u64 v[218:219], v[222:223], 0, s[46:47]
	s_mov_b32 m0, s76
	s_nop 0
	global_load_lds_dwordx4 v[218:219], off
	v_lshl_add_u64 v[218:219], v[224:225], 0, s[46:47]
	s_mov_b32 m0, s77
	s_nop 0
	global_load_lds_dwordx4 v[218:219], off
	s_add_i32 s85, s85, 2
	s_add_u32 s83, s83, 0x100
	s_addc_u32 s84, s84, 0
	s_add_u32 s10, s10, 0x100
	s_addc_u32 s11, s11, 0
	s_cmp_gt_u32 s85, 29
	s_waitcnt vmcnt(8)
	s_waitcnt lgkmcnt(0)
	s_setprio 1
	s_barrier
	v_mfma_i32_16x16x64_i8 v[70:73], v[14:17], v[178:181], v[70:73]
	v_mfma_i32_16x16x64_i8 v[54:57], v[14:17], v[194:197], v[54:57]
	v_mfma_i32_16x16x64_i8 v[38:41], v[14:17], v[202:205], v[38:41]
	v_mfma_i32_16x16x64_i8 v[2:5], v[14:17], v[210:213], v[2:5]
	v_mfma_i32_16x16x64_i8 v[70:73], v[22:25], v[190:193], v[70:73]
	v_mfma_i32_16x16x64_i8 v[62:65], v[138:141], v[178:181], v[62:65]
	v_mfma_i32_16x16x64_i8 v[54:57], v[22:25], v[198:201], v[54:57]
	v_mfma_i32_16x16x64_i8 v[46:49], v[138:141], v[194:197], v[46:49]
	v_mfma_i32_16x16x64_i8 v[38:41], v[22:25], v[206:209], v[38:41]
	v_mfma_i32_16x16x64_i8 v[30:33], v[138:141], v[202:205], v[30:33]
	v_mfma_i32_16x16x64_i8 v[22:25], v[22:25], v[214:217], v[2:5]
	v_mfma_i32_16x16x64_i8 v[2:5], v[138:141], v[210:213], v[6:9]
	v_mfma_i32_16x16x64_i8 v[62:65], v[142:145], v[190:193], v[62:65]
	v_mfma_i32_16x16x64_i8 v[46:49], v[142:145], v[198:201], v[46:49]
	v_mfma_i32_16x16x64_i8 v[30:33], v[142:145], v[206:209], v[30:33]
	v_mfma_i32_16x16x64_i8 v[14:17], v[142:145], v[214:217], v[2:5]
	v_mfma_i32_16x16x64_i8 v[2:5], v[146:149], v[178:181], v[66:69]
	v_mfma_i32_16x16x64_i8 v[66:69], v[150:153], v[190:193], v[2:5]
	v_mfma_i32_16x16x64_i8 v[2:5], v[170:173], v[178:181], v[58:61]
	v_mfma_i32_16x16x64_i8 v[58:61], v[174:177], v[190:193], v[2:5]
	v_mfma_i32_16x16x64_i8 v[2:5], v[146:149], v[194:197], v[50:53]
	v_mfma_i32_16x16x64_i8 v[50:53], v[150:153], v[198:201], v[2:5]
	v_mfma_i32_16x16x64_i8 v[2:5], v[170:173], v[194:197], v[42:45]
	v_mfma_i32_16x16x64_i8 v[42:45], v[174:177], v[198:201], v[2:5]
	v_mfma_i32_16x16x64_i8 v[2:5], v[146:149], v[202:205], v[34:37]
	v_mfma_i32_16x16x64_i8 v[34:37], v[150:153], v[206:209], v[2:5]
	v_mfma_i32_16x16x64_i8 v[2:5], v[170:173], v[202:205], v[26:29]
	v_mfma_i32_16x16x64_i8 v[26:29], v[174:177], v[206:209], v[2:5]
	v_mfma_i32_16x16x64_i8 v[2:5], v[146:149], v[210:213], v[18:21]
	v_mfma_i32_16x16x64_i8 v[18:21], v[150:153], v[214:217], v[2:5]
	v_mfma_i32_16x16x64_i8 v[2:5], v[170:173], v[210:213], v[10:13]
	v_mfma_i32_16x16x64_i8 v[10:13], v[174:177], v[214:217], v[2:5]
	s_cbranch_scc1 .Ltb13_e
	s_barrier
	s_setprio 0
	s_branch .LBB0_2067
.Ltb13_e:
	s_setprio 0
	s_and_b64 vcc, exec, s[60:61]
	s_cbranch_vccz .LBB0_2070
	s_barrier

.LBB0_2118:
	ds_read_b128 v[142:145], v149
	ds_read_b128 v[154:157], v149 offset:1024
	ds_read_b128 v[158:161], v149 offset:2048
	ds_read_b128 v[162:165], v149 offset:3072
	ds_read_b128 v[166:169], v150
	ds_read_b128 v[170:173], v150 offset:1024
	ds_read_b128 v[174:177], v150 offset:2048
	ds_read_b128 v[178:181], v150 offset:3072
	s_add_u32 s16, s40, 0xffd50080
	s_addc_u32 s17, s41, -1
	s_cmpk_eq_i32 s71, 0xa8
	s_cselect_b32 s45, s37, s17
	s_cselect_b32 s44, s36, s16
	s_cselect_b32 s43, s39, s70
	s_cselect_b32 s42, s38, s69
	s_add_i32 m0, s27, 0xc000
	ds_read_b128 v[182:185], v151
	ds_read_b128 v[186:189], v151 offset:1024
	ds_read_b128 v[190:193], v151 offset:2048
	ds_read_b128 v[194:197], v151 offset:3072
	ds_read_b128 v[198:201], v151 offset:4096
	ds_read_b128 v[202:205], v151 offset:5120
	ds_read_b128 v[206:209], v151 offset:6144
	ds_read_b128 v[210:213], v151 offset:7168
	global_load_lds_dwordx4 v140, s[40:41]
	s_add_i32 m0, s27, 0xe000
	s_nop 0
	global_load_lds_dwordx4 v138, s[40:41]
	s_waitcnt vmcnt(8)
	s_waitcnt lgkmcnt(0)
	s_setprio 1
	s_barrier
	v_mfma_f32_16x16x32_bf16 v[126:129], v[142:145], v[182:185], v[126:129]
	v_mfma_f32_16x16x32_bf16 v[122:125], v[158:161], v[182:185], v[122:125]
	v_mfma_f32_16x16x32_bf16 v[110:113], v[142:145], v[190:193], v[110:113]
	v_mfma_f32_16x16x32_bf16 v[106:109], v[158:161], v[190:193], v[106:109]
	v_mfma_f32_16x16x32_bf16 v[94:97], v[142:145], v[198:201], v[94:97]
	v_mfma_f32_16x16x32_bf16 v[90:93], v[158:161], v[198:201], v[90:93]
	v_mfma_f32_16x16x32_bf16 v[78:81], v[142:145], v[206:209], v[78:81]
	v_mfma_f32_16x16x32_bf16 v[74:77], v[158:161], v[206:209], v[74:77]
	v_mfma_f32_16x16x32_bf16 v[126:129], v[154:157], v[186:189], v[126:129]
	v_mfma_f32_16x16x32_bf16 v[122:125], v[162:165], v[186:189], v[122:125]
	v_mfma_f32_16x16x32_bf16 v[110:113], v[154:157], v[194:197], v[110:113]
	v_mfma_f32_16x16x32_bf16 v[106:109], v[162:165], v[194:197], v[106:109]
	v_mfma_f32_16x16x32_bf16 v[94:97], v[154:157], v[202:205], v[94:97]
	v_mfma_f32_16x16x32_bf16 v[90:93], v[162:165], v[202:205], v[90:93]
	v_mfma_f32_16x16x32_bf16 v[78:81], v[154:157], v[210:213], v[78:81]
	v_mfma_f32_16x16x32_bf16 v[74:77], v[162:165], v[210:213], v[74:77]
	v_mfma_f32_16x16x32_bf16 v[118:121], v[166:169], v[182:185], v[118:121]
	v_mfma_f32_16x16x32_bf16 v[114:117], v[174:177], v[182:185], v[114:117]
	v_mfma_f32_16x16x32_bf16 v[102:105], v[166:169], v[190:193], v[102:105]
	v_mfma_f32_16x16x32_bf16 v[98:101], v[174:177], v[190:193], v[98:101]
	v_mfma_f32_16x16x32_bf16 v[86:89], v[166:169], v[198:201], v[86:89]
	v_mfma_f32_16x16x32_bf16 v[82:85], v[174:177], v[198:201], v[82:85]
	v_mfma_f32_16x16x32_bf16 v[70:73], v[166:169], v[206:209], v[70:73]
	v_mfma_f32_16x16x32_bf16 v[66:69], v[174:177], v[206:209], v[66:69]
	v_mfma_f32_16x16x32_bf16 v[118:121], v[170:173], v[186:189], v[118:121]
	v_mfma_f32_16x16x32_bf16 v[114:117], v[178:181], v[186:189], v[114:117]
	v_mfma_f32_16x16x32_bf16 v[102:105], v[170:173], v[194:197], v[102:105]
	v_mfma_f32_16x16x32_bf16 v[98:101], v[178:181], v[194:197], v[98:101]
	v_mfma_f32_16x16x32_bf16 v[86:89], v[170:173], v[202:205], v[86:89]
	v_mfma_f32_16x16x32_bf16 v[82:85], v[178:181], v[202:205], v[82:85]
	v_mfma_f32_16x16x32_bf16 v[70:73], v[170:173], v[210:213], v[70:73]
	v_mfma_f32_16x16x32_bf16 v[66:69], v[178:181], v[210:213], v[66:69]
	s_barrier
	s_setprio 0
	s_add_i32 s16, s63, s26
	v_lshl_add_u64 v[214:215], s[42:43], 0, v[132:133]
	s_mov_b32 m0, s16
	ds_read_b128 v[182:185], v151 offset:16384
	ds_read_b128 v[186:189], v151 offset:17408
	ds_read_b128 v[190:193], v151 offset:18432
	ds_read_b128 v[194:197], v151 offset:19456
	ds_read_b128 v[198:201], v151 offset:20480
	ds_read_b128 v[202:205], v151 offset:21504
	ds_read_b128 v[206:209], v151 offset:22528
	ds_read_b128 v[210:213], v151 offset:23552
	global_load_lds_dwordx4 v[214:215], off
	s_add_i32 m0, s16, 0x2000
	s_add_u32 s16, s42, 0x2b0000
	v_lshl_add_u64 v[216:217], s[42:43], 0, v[136:137]
	s_addc_u32 s17, s43, 0
	s_add_i32 s72, s64, s26
	global_load_lds_dwordx4 v[216:217], off
	s_mov_b32 m0, s72
	v_lshl_add_u64 v[220:221], s[44:45], 0, v[134:135]
	global_load_lds_dwordx4 v132, s[16:17]
	s_add_i32 m0, s72, 0x2000
	s_nop 0
	global_load_lds_dwordx4 v136, s[16:17]
	v_lshl_add_u64 v[218:219], s[44:45], 0, v[130:131]
	s_mov_b32 m0, s27
	s_nop 0
	global_load_lds_dwordx4 v[218:219], off
	s_mov_b32 m0, s28
	s_nop 0
	global_load_lds_dwordx4 v[220:221], off
	s_waitcnt vmcnt(8)
	s_waitcnt lgkmcnt(0)
	s_setprio 1
	s_barrier
	v_mfma_f32_16x16x32_bf16 v[62:65], v[142:145], v[182:185], v[62:65]
	v_mfma_f32_16x16x32_bf16 v[58:61], v[158:161], v[182:185], v[58:61]
	v_mfma_f32_16x16x32_bf16 v[46:49], v[142:145], v[190:193], v[46:49]
	v_mfma_f32_16x16x32_bf16 v[42:45], v[158:161], v[190:193], v[42:45]
	v_mfma_f32_16x16x32_bf16 v[30:33], v[142:145], v[198:201], v[30:33]
	v_mfma_f32_16x16x32_bf16 v[26:29], v[158:161], v[198:201], v[26:29]
	v_mfma_f32_16x16x32_bf16 v[14:17], v[142:145], v[206:209], v[14:17]
	v_mfma_f32_16x16x32_bf16 v[10:13], v[158:161], v[206:209], v[10:13]
	v_mfma_f32_16x16x32_bf16 v[62:65], v[154:157], v[186:189], v[62:65]
	v_mfma_f32_16x16x32_bf16 v[58:61], v[162:165], v[186:189], v[58:61]
	v_mfma_f32_16x16x32_bf16 v[46:49], v[154:157], v[194:197], v[46:49]
	v_mfma_f32_16x16x32_bf16 v[42:45], v[162:165], v[194:197], v[42:45]
	v_mfma_f32_16x16x32_bf16 v[30:33], v[154:157], v[202:205], v[30:33]
	v_mfma_f32_16x16x32_bf16 v[26:29], v[162:165], v[202:205], v[26:29]
	v_mfma_f32_16x16x32_bf16 v[14:17], v[154:157], v[210:213], v[14:17]
	v_mfma_f32_16x16x32_bf16 v[10:13], v[162:165], v[210:213], v[10:13]
	v_mfma_f32_16x16x32_bf16 v[54:57], v[166:169], v[182:185], v[54:57]
	v_mfma_f32_16x16x32_bf16 v[50:53], v[174:177], v[182:185], v[50:53]
	v_mfma_f32_16x16x32_bf16 v[38:41], v[166:169], v[190:193], v[38:41]
	v_mfma_f32_16x16x32_bf16 v[34:37], v[174:177], v[190:193], v[34:37]
	v_mfma_f32_16x16x32_bf16 v[22:25], v[166:169], v[198:201], v[22:25]
	v_mfma_f32_16x16x32_bf16 v[18:21], v[174:177], v[198:201], v[18:21]
	v_mfma_f32_16x16x32_bf16 v[6:9], v[166:169], v[206:209], v[6:9]
	v_mfma_f32_16x16x32_bf16 v[2:5], v[174:177], v[206:209], v[2:5]
	v_mfma_f32_16x16x32_bf16 v[54:57], v[170:173], v[186:189], v[54:57]
	v_mfma_f32_16x16x32_bf16 v[50:53], v[178:181], v[186:189], v[50:53]
	v_mfma_f32_16x16x32_bf16 v[38:41], v[170:173], v[194:197], v[38:41]
	v_mfma_f32_16x16x32_bf16 v[34:37], v[178:181], v[194:197], v[34:37]
	v_mfma_f32_16x16x32_bf16 v[22:25], v[170:173], v[202:205], v[22:25]
	v_mfma_f32_16x16x32_bf16 v[18:21], v[178:181], v[202:205], v[18:21]
	v_mfma_f32_16x16x32_bf16 v[6:9], v[170:173], v[210:213], v[6:9]
	v_mfma_f32_16x16x32_bf16 v[2:5], v[178:181], v[210:213], v[2:5]
	s_barrier
	s_setprio 0
	s_add_i32 s72, 0, 0x18000
	v_add_u32_e32 v153, s72, v147
	s_add_i32 s73, 0, 0x1c000
	ds_read_b128 v[142:145], v153
	ds_read_b128 v[154:157], v153 offset:1024
	ds_read_b128 v[158:161], v153 offset:2048
	ds_read_b128 v[162:165], v153 offset:3072
	v_add_u32_e32 v153, s73, v147
	ds_read_b128 v[166:169], v153
	ds_read_b128 v[170:173], v153 offset:1024
	ds_read_b128 v[174:177], v153 offset:2048
	ds_read_b128 v[178:181], v153 offset:3072
	s_add_u32 s16, s44, 0x2b0000
	s_addc_u32 s17, s45, 0
	s_mov_b32 m0, s29
	ds_read_b128 v[182:185], v151 offset:32768
	ds_read_b128 v[186:189], v151 offset:33792
	ds_read_b128 v[190:193], v151 offset:34816
	ds_read_b128 v[194:197], v151 offset:35840
	ds_read_b128 v[198:201], v151 offset:36864
	ds_read_b128 v[202:205], v151 offset:37888
	ds_read_b128 v[206:209], v151 offset:38912
	ds_read_b128 v[210:213], v151 offset:39936
	global_load_lds_dwordx4 v130, s[16:17]
	s_mov_b32 m0, s56
	s_nop 0
	global_load_lds_dwordx4 v134, s[16:17]
	s_waitcnt vmcnt(8)
	s_waitcnt lgkmcnt(0)
	s_setprio 1
	s_barrier
	v_mfma_f32_16x16x32_bf16 v[126:129], v[142:145], v[182:185], v[126:129]
	v_mfma_f32_16x16x32_bf16 v[122:125], v[158:161], v[182:185], v[122:125]
	v_mfma_f32_16x16x32_bf16 v[110:113], v[142:145], v[190:193], v[110:113]
	v_mfma_f32_16x16x32_bf16 v[106:109], v[158:161], v[190:193], v[106:109]
	v_mfma_f32_16x16x32_bf16 v[94:97], v[142:145], v[198:201], v[94:97]
	v_mfma_f32_16x16x32_bf16 v[90:93], v[158:161], v[198:201], v[90:93]
	v_mfma_f32_16x16x32_bf16 v[78:81], v[142:145], v[206:209], v[78:81]
	v_mfma_f32_16x16x32_bf16 v[74:77], v[158:161], v[206:209], v[74:77]
	v_mfma_f32_16x16x32_bf16 v[126:129], v[154:157], v[186:189], v[126:129]
	v_mfma_f32_16x16x32_bf16 v[122:125], v[162:165], v[186:189], v[122:125]
	v_mfma_f32_16x16x32_bf16 v[110:113], v[154:157], v[194:197], v[110:113]
	v_mfma_f32_16x16x32_bf16 v[106:109], v[162:165], v[194:197], v[106:109]
	v_mfma_f32_16x16x32_bf16 v[94:97], v[154:157], v[202:205], v[94:97]
	v_mfma_f32_16x16x32_bf16 v[90:93], v[162:165], v[202:205], v[90:93]
	v_mfma_f32_16x16x32_bf16 v[78:81], v[154:157], v[210:213], v[78:81]
	v_mfma_f32_16x16x32_bf16 v[74:77], v[162:165], v[210:213], v[74:77]
	v_mfma_f32_16x16x32_bf16 v[118:121], v[166:169], v[182:185], v[118:121]
	v_mfma_f32_16x16x32_bf16 v[114:117], v[174:177], v[182:185], v[114:117]
	v_mfma_f32_16x16x32_bf16 v[102:105], v[166:169], v[190:193], v[102:105]
	v_mfma_f32_16x16x32_bf16 v[98:101], v[174:177], v[190:193], v[98:101]
	v_mfma_f32_16x16x32_bf16 v[86:89], v[166:169], v[198:201], v[86:89]
	v_mfma_f32_16x16x32_bf16 v[82:85], v[174:177], v[198:201], v[82:85]
	v_mfma_f32_16x16x32_bf16 v[70:73], v[166:169], v[206:209], v[70:73]
	v_mfma_f32_16x16x32_bf16 v[66:69], v[174:177], v[206:209], v[66:69]
	v_mfma_f32_16x16x32_bf16 v[118:121], v[170:173], v[186:189], v[118:121]
	v_mfma_f32_16x16x32_bf16 v[114:117], v[178:181], v[186:189], v[114:117]
	v_mfma_f32_16x16x32_bf16 v[102:105], v[170:173], v[194:197], v[102:105]
	v_mfma_f32_16x16x32_bf16 v[98:101], v[178:181], v[194:197], v[98:101]
	v_mfma_f32_16x16x32_bf16 v[86:89], v[170:173], v[202:205], v[86:89]
	v_mfma_f32_16x16x32_bf16 v[82:85], v[178:181], v[202:205], v[82:85]
	v_mfma_f32_16x16x32_bf16 v[70:73], v[170:173], v[210:213], v[70:73]
	v_mfma_f32_16x16x32_bf16 v[66:69], v[178:181], v[210:213], v[66:69]
	s_barrier
	s_setprio 0
	s_add_i32 s16, s72, s26
	v_lshl_add_u64 v[214:215], v[214:215], 0, s[14:15]
	s_mov_b32 m0, s16
	ds_read_b128 v[182:185], v151 offset:49152
	ds_read_b128 v[186:189], v151 offset:50176
	ds_read_b128 v[190:193], v151 offset:51200
	ds_read_b128 v[194:197], v151 offset:52224
	ds_read_b128 v[198:201], v151 offset:53248
	ds_read_b128 v[202:205], v151 offset:54272
	ds_read_b128 v[206:209], v151 offset:55296
	ds_read_b128 v[210:213], v151 offset:56320
	global_load_lds_dwordx4 v[214:215], off
	s_add_i32 m0, s16, 0x2000
	s_add_u32 s16, s42, 0x2b0080
	v_lshl_add_u64 v[214:215], v[216:217], 0, s[14:15]
	s_addc_u32 s17, s43, 0
	s_add_i32 s42, s73, s26
	global_load_lds_dwordx4 v[214:215], off
	s_mov_b32 m0, s42
	s_nop 0
	global_load_lds_dwordx4 v132, s[16:17]
	s_add_i32 m0, s42, 0x2000
	s_nop 0
	global_load_lds_dwordx4 v136, s[16:17]
	v_lshl_add_u64 v[214:215], v[218:219], 0, s[14:15]
	s_mov_b32 m0, s60
	s_nop 0
	global_load_lds_dwordx4 v[214:215], off
	v_lshl_add_u64 v[214:215], v[220:221], 0, s[14:15]
	s_mov_b32 m0, s61
	s_nop 0
	global_load_lds_dwordx4 v[214:215], off
	s_add_i32 s71, s71, 2
	s_add_u32 s69, s69, 0x100
	s_addc_u32 s70, s70, 0
	s_add_u32 s40, s40, 0x100
	s_addc_u32 s41, s41, 0
	s_cmpk_gt_u32 s71, 0xa9
	s_waitcnt vmcnt(8)
	s_waitcnt lgkmcnt(0)
	s_setprio 1
	s_barrier
	v_mfma_f32_16x16x32_bf16 v[62:65], v[142:145], v[182:185], v[62:65]
	v_mfma_f32_16x16x32_bf16 v[58:61], v[158:161], v[182:185], v[58:61]
	v_mfma_f32_16x16x32_bf16 v[46:49], v[142:145], v[190:193], v[46:49]
	v_mfma_f32_16x16x32_bf16 v[42:45], v[158:161], v[190:193], v[42:45]
	v_mfma_f32_16x16x32_bf16 v[30:33], v[142:145], v[198:201], v[30:33]
	v_mfma_f32_16x16x32_bf16 v[26:29], v[158:161], v[198:201], v[26:29]
	v_mfma_f32_16x16x32_bf16 v[14:17], v[142:145], v[206:209], v[14:17]
	v_mfma_f32_16x16x32_bf16 v[10:13], v[158:161], v[206:209], v[10:13]
	v_mfma_f32_16x16x32_bf16 v[62:65], v[154:157], v[186:189], v[62:65]
	v_mfma_f32_16x16x32_bf16 v[58:61], v[162:165], v[186:189], v[58:61]
	v_mfma_f32_16x16x32_bf16 v[46:49], v[154:157], v[194:197], v[46:49]
	v_mfma_f32_16x16x32_bf16 v[42:45], v[162:165], v[194:197], v[42:45]
	v_mfma_f32_16x16x32_bf16 v[30:33], v[154:157], v[202:205], v[30:33]
	v_mfma_f32_16x16x32_bf16 v[26:29], v[162:165], v[202:205], v[26:29]
	v_mfma_f32_16x16x32_bf16 v[14:17], v[154:157], v[210:213], v[14:17]
	v_mfma_f32_16x16x32_bf16 v[10:13], v[162:165], v[210:213], v[10:13]
	v_mfma_f32_16x16x32_bf16 v[54:57], v[166:169], v[182:185], v[54:57]
	v_mfma_f32_16x16x32_bf16 v[50:53], v[174:177], v[182:185], v[50:53]
	v_mfma_f32_16x16x32_bf16 v[38:41], v[166:169], v[190:193], v[38:41]
	v_mfma_f32_16x16x32_bf16 v[34:37], v[174:177], v[190:193], v[34:37]
	v_mfma_f32_16x16x32_bf16 v[22:25], v[166:169], v[198:201], v[22:25]
	v_mfma_f32_16x16x32_bf16 v[18:21], v[174:177], v[198:201], v[18:21]
	v_mfma_f32_16x16x32_bf16 v[6:9], v[166:169], v[206:209], v[6:9]
	v_mfma_f32_16x16x32_bf16 v[2:5], v[174:177], v[206:209], v[2:5]
	v_mfma_f32_16x16x32_bf16 v[54:57], v[170:173], v[186:189], v[54:57]
	v_mfma_f32_16x16x32_bf16 v[50:53], v[178:181], v[186:189], v[50:53]
	v_mfma_f32_16x16x32_bf16 v[38:41], v[170:173], v[194:197], v[38:41]
	v_mfma_f32_16x16x32_bf16 v[34:37], v[178:181], v[194:197], v[34:37]
	v_mfma_f32_16x16x32_bf16 v[22:25], v[170:173], v[202:205], v[22:25]
	v_mfma_f32_16x16x32_bf16 v[18:21], v[178:181], v[202:205], v[18:21]
	v_mfma_f32_16x16x32_bf16 v[6:9], v[170:173], v[210:213], v[6:9]
	v_mfma_f32_16x16x32_bf16 v[2:5], v[178:181], v[210:213], v[2:5]
	s_cbranch_scc1 .Ltb14_e
	s_barrier
	s_setprio 0
	s_branch .LBB0_2118
.Ltb14_e:
	s_setprio 0
	v_lshl_add_u32 v245, s68, 8, v146
	v_lshl_or_b32 v246, s67, 8, v148
	v_lshlrev_b32_e32 v245, 13, v245
	v_lshl_add_u32 v245, v246, 1, v245
	global_load_dwordx4 v[142:145], v245, s[24:25]
	global_load_dwordx4 v[154:157], v245, s[24:25] offset:256
	s_add_u32 s40, s24, 0x20000
	s_addc_u32 s41, s25, 0
	global_load_dwordx4 v[158:161], v245, s[40:41]
	global_load_dwordx4 v[162:165], v245, s[40:41] offset:256
	s_add_u32 s40, s24, 0x40000
	s_addc_u32 s41, s25, 0
	global_load_dwordx4 v[166:169], v245, s[40:41]
	global_load_dwordx4 v[170:173], v245, s[40:41] offset:256
	s_add_u32 s40, s24, 0x60000
	s_addc_u32 s41, s25, 0
	global_load_dwordx4 v[174:177], v245, s[40:41]
	global_load_dwordx4 v[178:181], v245, s[40:41] offset:256
	s_add_u32 s40, s24, 0x100000
	s_addc_u32 s41, s25, 0
	global_load_dwordx4 v[182:185], v245, s[40:41]
	global_load_dwordx4 v[186:189], v245, s[40:41] offset:256
	s_add_u32 s40, s24, 0x120000
	s_addc_u32 s41, s25, 0
	global_load_dwordx4 v[190:193], v245, s[40:41]
	global_load_dwordx4 v[194:197], v245, s[40:41] offset:256
	s_add_u32 s40, s24, 0x140000
	s_addc_u32 s41, s25, 0
	global_load_dwordx4 v[198:201], v245, s[40:41]
	global_load_dwordx4 v[202:205], v245, s[40:41] offset:256
	s_add_u32 s40, s24, 0x160000
	s_addc_u32 s41, s25, 0
	global_load_dwordx4 v[206:209], v245, s[40:41]
	global_load_dwordx4 v[210:213], v245, s[40:41] offset:256
	s_and_b64 vcc, exec, s[34:35]
	s_cbranch_vccz .LBB0_2121
	s_barrier

.LBB0_2159:
	ds_read_b128 v[2:5], v183
	ds_read_b128 v[6:9], v183 offset:1024
	ds_read_b128 v[138:141], v183 offset:2048
	ds_read_b128 v[142:145], v183 offset:3072
	ds_read_b128 v[146:149], v184
	ds_read_b128 v[150:153], v184 offset:1024
	ds_read_b128 v[168:171], v184 offset:2048
	ds_read_b128 v[172:175], v184 offset:3072
	s_add_u32 s10, s8, 0xfff80080
	s_addc_u32 s11, s9, -1
	s_cmp_eq_u32 s79, 28
	s_cselect_b32 s13, s41, s11
	s_cselect_b32 s12, s75, s10
	s_cselect_b32 s11, s39, s78
	s_cselect_b32 s10, s76, s77
	s_add_i32 m0, s15, 0xc000
	ds_read_b128 v[176:179], v185
	ds_read_b128 v[188:191], v185 offset:1024
	ds_read_b128 v[192:195], v185 offset:2048
	ds_read_b128 v[196:199], v185 offset:3072
	ds_read_b128 v[200:203], v185 offset:4096
	ds_read_b128 v[204:207], v185 offset:5120
	ds_read_b128 v[208:211], v185 offset:6144
	ds_read_b128 v[212:215], v185 offset:7168
	global_load_lds_dwordx4 v164, s[8:9]
	s_add_i32 m0, s15, 0xe000
	s_nop 0
	global_load_lds_dwordx4 v162, s[8:9]
	s_waitcnt vmcnt(8)
	s_waitcnt lgkmcnt(0)
	s_setprio 1
	s_barrier
	v_mfma_i32_16x16x64_i8 v[134:137], v[2:5], v[176:179], v[134:137]
	v_mfma_i32_16x16x64_i8 v[126:129], v[138:141], v[176:179], v[126:129]
	v_mfma_i32_16x16x64_i8 v[118:121], v[2:5], v[192:195], v[118:121]
	v_mfma_i32_16x16x64_i8 v[110:113], v[138:141], v[192:195], v[110:113]
	v_mfma_i32_16x16x64_i8 v[102:105], v[2:5], v[200:203], v[102:105]
	v_mfma_i32_16x16x64_i8 v[94:97], v[138:141], v[200:203], v[94:97]
	v_mfma_i32_16x16x64_i8 v[86:89], v[2:5], v[208:211], v[86:89]
	v_mfma_i32_16x16x64_i8 v[78:81], v[138:141], v[208:211], v[78:81]
	v_mfma_i32_16x16x64_i8 v[134:137], v[6:9], v[188:191], v[134:137]
	v_mfma_i32_16x16x64_i8 v[126:129], v[142:145], v[188:191], v[126:129]
	v_mfma_i32_16x16x64_i8 v[118:121], v[6:9], v[196:199], v[118:121]
	v_mfma_i32_16x16x64_i8 v[110:113], v[142:145], v[196:199], v[110:113]
	v_mfma_i32_16x16x64_i8 v[102:105], v[6:9], v[204:207], v[102:105]
	v_mfma_i32_16x16x64_i8 v[94:97], v[142:145], v[204:207], v[94:97]
	v_mfma_i32_16x16x64_i8 v[86:89], v[6:9], v[212:215], v[86:89]
	v_mfma_i32_16x16x64_i8 v[78:81], v[142:145], v[212:215], v[78:81]
	v_mfma_i32_16x16x64_i8 v[130:133], v[146:149], v[176:179], v[130:133]
	v_mfma_i32_16x16x64_i8 v[122:125], v[168:171], v[176:179], v[122:125]
	v_mfma_i32_16x16x64_i8 v[114:117], v[146:149], v[192:195], v[114:117]
	v_mfma_i32_16x16x64_i8 v[106:109], v[168:171], v[192:195], v[106:109]
	v_mfma_i32_16x16x64_i8 v[98:101], v[146:149], v[200:203], v[98:101]
	v_mfma_i32_16x16x64_i8 v[90:93], v[168:171], v[200:203], v[90:93]
	v_mfma_i32_16x16x64_i8 v[82:85], v[146:149], v[208:211], v[82:85]
	v_mfma_i32_16x16x64_i8 v[74:77], v[168:171], v[208:211], v[74:77]
	v_mfma_i32_16x16x64_i8 v[130:133], v[150:153], v[188:191], v[130:133]
	v_mfma_i32_16x16x64_i8 v[122:125], v[172:175], v[188:191], v[122:125]
	v_mfma_i32_16x16x64_i8 v[114:117], v[150:153], v[196:199], v[114:117]
	v_mfma_i32_16x16x64_i8 v[106:109], v[172:175], v[196:199], v[106:109]
	v_mfma_i32_16x16x64_i8 v[98:101], v[150:153], v[204:207], v[98:101]
	v_mfma_i32_16x16x64_i8 v[90:93], v[172:175], v[204:207], v[90:93]
	v_mfma_i32_16x16x64_i8 v[82:85], v[150:153], v[212:215], v[82:85]
	v_mfma_i32_16x16x64_i8 v[74:77], v[172:175], v[212:215], v[74:77]
	s_barrier
	s_setprio 0
	s_add_i32 s16, s69, s56
	v_lshl_add_u64 v[216:217], s[10:11], 0, v[156:157]
	s_mov_b32 m0, s16
	ds_read_b128 v[176:179], v185 offset:16384
	ds_read_b128 v[188:191], v185 offset:17408
	ds_read_b128 v[192:195], v185 offset:18432
	ds_read_b128 v[196:199], v185 offset:19456
	ds_read_b128 v[200:203], v185 offset:20480
	ds_read_b128 v[204:207], v185 offset:21504
	ds_read_b128 v[208:211], v185 offset:22528
	ds_read_b128 v[212:215], v185 offset:23552
	global_load_lds_dwordx4 v[216:217], off
	s_add_i32 m0, s16, 0x2000
	s_add_u32 s16, s10, 0x80000
	v_lshl_add_u64 v[218:219], s[10:11], 0, v[160:161]
	s_addc_u32 s17, s11, 0
	s_add_i32 s80, s70, s56
	global_load_lds_dwordx4 v[218:219], off
	s_mov_b32 m0, s80
	v_lshl_add_u64 v[222:223], s[12:13], 0, v[158:159]
	global_load_lds_dwordx4 v156, s[16:17]
	s_add_i32 m0, s80, 0x2000
	s_nop 0
	global_load_lds_dwordx4 v160, s[16:17]
	v_lshl_add_u64 v[220:221], s[12:13], 0, v[154:155]
	s_mov_b32 m0, s15
	s_nop 0
	global_load_lds_dwordx4 v[220:221], off
	s_mov_b32 m0, s60
	s_nop 0
	global_load_lds_dwordx4 v[222:223], off
	s_waitcnt vmcnt(8)
	s_waitcnt lgkmcnt(0)
	s_setprio 1
	s_barrier
	v_mfma_i32_16x16x64_i8 v[70:73], v[2:5], v[176:179], v[70:73]
	v_mfma_i32_16x16x64_i8 v[62:65], v[138:141], v[176:179], v[62:65]
	v_mfma_i32_16x16x64_i8 v[54:57], v[2:5], v[192:195], v[54:57]
	v_mfma_i32_16x16x64_i8 v[46:49], v[138:141], v[192:195], v[46:49]
	v_mfma_i32_16x16x64_i8 v[38:41], v[2:5], v[200:203], v[38:41]
	v_mfma_i32_16x16x64_i8 v[30:33], v[138:141], v[200:203], v[30:33]
	v_mfma_i32_16x16x64_i8 v[2:5], v[2:5], v[208:211], v[22:25]
	v_mfma_i32_16x16x64_i8 v[70:73], v[6:9], v[188:191], v[70:73]
	v_mfma_i32_16x16x64_i8 v[62:65], v[142:145], v[188:191], v[62:65]
	v_mfma_i32_16x16x64_i8 v[54:57], v[6:9], v[196:199], v[54:57]
	v_mfma_i32_16x16x64_i8 v[46:49], v[142:145], v[196:199], v[46:49]
	v_mfma_i32_16x16x64_i8 v[38:41], v[6:9], v[204:207], v[38:41]
	v_mfma_i32_16x16x64_i8 v[30:33], v[142:145], v[204:207], v[30:33]
	v_mfma_i32_16x16x64_i8 v[2:5], v[6:9], v[212:215], v[2:5]
	v_mfma_i32_16x16x64_i8 v[6:9], v[138:141], v[208:211], v[14:17]
	v_mfma_i32_16x16x64_i8 v[6:9], v[142:145], v[212:215], v[6:9]
	v_mfma_i32_16x16x64_i8 v[14:17], v[146:149], v[176:179], v[66:69]
	v_mfma_i32_16x16x64_i8 v[66:69], v[150:153], v[188:191], v[14:17]
	v_mfma_i32_16x16x64_i8 v[14:17], v[168:171], v[176:179], v[58:61]
	v_mfma_i32_16x16x64_i8 v[58:61], v[172:175], v[188:191], v[14:17]
	v_mfma_i32_16x16x64_i8 v[14:17], v[146:149], v[192:195], v[50:53]
	v_mfma_i32_16x16x64_i8 v[50:53], v[150:153], v[196:199], v[14:17]
	v_mfma_i32_16x16x64_i8 v[14:17], v[168:171], v[192:195], v[42:45]
	v_mfma_i32_16x16x64_i8 v[42:45], v[172:175], v[196:199], v[14:17]
	v_mfma_i32_16x16x64_i8 v[14:17], v[146:149], v[200:203], v[34:37]
	v_mfma_i32_16x16x64_i8 v[34:37], v[150:153], v[204:207], v[14:17]
	v_mfma_i32_16x16x64_i8 v[14:17], v[168:171], v[200:203], v[26:29]
	v_mfma_i32_16x16x64_i8 v[26:29], v[172:175], v[204:207], v[14:17]
	v_mfma_i32_16x16x64_i8 v[14:17], v[146:149], v[208:211], v[18:21]
	v_mfma_i32_16x16x64_i8 v[10:13], v[168:171], v[208:211], v[10:13]
	v_mfma_i32_16x16x64_i8 v[18:21], v[150:153], v[212:215], v[14:17]
	v_mfma_i32_16x16x64_i8 v[10:13], v[172:175], v[212:215], v[10:13]
	s_barrier
	s_setprio 0
	s_add_i32 s16, 0, 0x18000
	s_add_i32 s17, 0, 0x1c000
	v_add_u32_e32 v142, s16, v181
	v_add_u32_e32 v172, s17, v181
	ds_read_b128 v[14:17], v142
	ds_read_b128 v[22:25], v142 offset:1024
	ds_read_b128 v[138:141], v142 offset:2048
	ds_read_b128 v[142:145], v142 offset:3072
	ds_read_b128 v[146:149], v172
	ds_read_b128 v[150:153], v172 offset:1024
	ds_read_b128 v[168:171], v172 offset:2048
	ds_read_b128 v[172:175], v172 offset:3072
	s_add_u32 s12, s12, 0x80000
	s_addc_u32 s13, s13, 0
	s_mov_b32 m0, s61
	ds_read_b128 v[176:179], v185 offset:32768
	ds_read_b128 v[188:191], v185 offset:33792
	ds_read_b128 v[192:195], v185 offset:34816
	ds_read_b128 v[196:199], v185 offset:35840
	ds_read_b128 v[200:203], v185 offset:36864
	ds_read_b128 v[204:207], v185 offset:37888
	ds_read_b128 v[208:211], v185 offset:38912
	ds_read_b128 v[212:215], v185 offset:39936
	global_load_lds_dwordx4 v154, s[12:13]
	s_mov_b32 m0, s62
	s_nop 0
	global_load_lds_dwordx4 v158, s[12:13]
	s_waitcnt vmcnt(8)
	s_waitcnt lgkmcnt(0)
	s_setprio 1
	s_barrier
	v_mfma_i32_16x16x64_i8 v[134:137], v[14:17], v[176:179], v[134:137]
	v_mfma_i32_16x16x64_i8 v[126:129], v[138:141], v[176:179], v[126:129]
	v_mfma_i32_16x16x64_i8 v[118:121], v[14:17], v[192:195], v[118:121]
	v_mfma_i32_16x16x64_i8 v[110:113], v[138:141], v[192:195], v[110:113]
	v_mfma_i32_16x16x64_i8 v[102:105], v[14:17], v[200:203], v[102:105]
	v_mfma_i32_16x16x64_i8 v[94:97], v[138:141], v[200:203], v[94:97]
	v_mfma_i32_16x16x64_i8 v[86:89], v[14:17], v[208:211], v[86:89]
	v_mfma_i32_16x16x64_i8 v[78:81], v[138:141], v[208:211], v[78:81]
	v_mfma_i32_16x16x64_i8 v[134:137], v[22:25], v[188:191], v[134:137]
	v_mfma_i32_16x16x64_i8 v[126:129], v[142:145], v[188:191], v[126:129]
	v_mfma_i32_16x16x64_i8 v[118:121], v[22:25], v[196:199], v[118:121]
	v_mfma_i32_16x16x64_i8 v[110:113], v[142:145], v[196:199], v[110:113]
	v_mfma_i32_16x16x64_i8 v[102:105], v[22:25], v[204:207], v[102:105]
	v_mfma_i32_16x16x64_i8 v[94:97], v[142:145], v[204:207], v[94:97]
	v_mfma_i32_16x16x64_i8 v[86:89], v[22:25], v[212:215], v[86:89]
	v_mfma_i32_16x16x64_i8 v[78:81], v[142:145], v[212:215], v[78:81]
	v_mfma_i32_16x16x64_i8 v[130:133], v[146:149], v[176:179], v[130:133]
	v_mfma_i32_16x16x64_i8 v[122:125], v[168:171], v[176:179], v[122:125]
	v_mfma_i32_16x16x64_i8 v[114:117], v[146:149], v[192:195], v[114:117]
	v_mfma_i32_16x16x64_i8 v[106:109], v[168:171], v[192:195], v[106:109]
	v_mfma_i32_16x16x64_i8 v[98:101], v[146:149], v[200:203], v[98:101]
	v_mfma_i32_16x16x64_i8 v[90:93], v[168:171], v[200:203], v[90:93]
	v_mfma_i32_16x16x64_i8 v[82:85], v[146:149], v[208:211], v[82:85]
	v_mfma_i32_16x16x64_i8 v[74:77], v[168:171], v[208:211], v[74:77]
	v_mfma_i32_16x16x64_i8 v[130:133], v[150:153], v[188:191], v[130:133]
	v_mfma_i32_16x16x64_i8 v[122:125], v[172:175], v[188:191], v[122:125]
	v_mfma_i32_16x16x64_i8 v[114:117], v[150:153], v[196:199], v[114:117]
	v_mfma_i32_16x16x64_i8 v[106:109], v[172:175], v[196:199], v[106:109]
	v_mfma_i32_16x16x64_i8 v[98:101], v[150:153], v[204:207], v[98:101]
	v_mfma_i32_16x16x64_i8 v[90:93], v[172:175], v[204:207], v[90:93]
	v_mfma_i32_16x16x64_i8 v[82:85], v[150:153], v[212:215], v[82:85]
	v_mfma_i32_16x16x64_i8 v[74:77], v[172:175], v[212:215], v[74:77]
	s_barrier
	s_setprio 0
	s_add_i32 s12, s16, s56
	v_lshl_add_u64 v[216:217], v[216:217], 0, s[34:35]
	s_mov_b32 m0, s12
	ds_read_b128 v[176:179], v185 offset:49152
	ds_read_b128 v[188:191], v185 offset:50176
	ds_read_b128 v[192:195], v185 offset:51200
	ds_read_b128 v[196:199], v185 offset:52224
	ds_read_b128 v[200:203], v185 offset:53248
	ds_read_b128 v[204:207], v185 offset:54272
	ds_read_b128 v[208:211], v185 offset:55296
	ds_read_b128 v[212:215], v185 offset:56320
	global_load_lds_dwordx4 v[216:217], off
	s_add_i32 m0, s12, 0x2000
	s_add_u32 s10, s10, 0x80080
	v_lshl_add_u64 v[216:217], v[218:219], 0, s[34:35]
	s_addc_u32 s11, s11, 0
	s_add_i32 s12, s17, s56
	global_load_lds_dwordx4 v[216:217], off
	s_mov_b32 m0, s12
	s_nop 0
	global_load_lds_dwordx4 v156, s[10:11]
	s_add_i32 m0, s12, 0x2000
	s_nop 0
	global_load_lds_dwordx4 v160, s[10:11]
	v_lshl_add_u64 v[216:217], v[220:221], 0, s[34:35]
	s_mov_b32 m0, s64
	s_nop 0
	global_load_lds_dwordx4 v[216:217], off
	v_lshl_add_u64 v[216:217], v[222:223], 0, s[34:35]
	s_mov_b32 m0, s65
	s_nop 0
	global_load_lds_dwordx4 v[216:217], off
	s_add_i32 s79, s79, 2
	s_add_u32 s77, s77, 0x100
	s_addc_u32 s78, s78, 0
	s_add_u32 s8, s8, 0x100
	s_addc_u32 s9, s9, 0
	s_cmp_gt_u32 s79, 29
	s_waitcnt vmcnt(8)
	s_waitcnt lgkmcnt(0)
	s_setprio 1
	s_barrier
	v_mfma_i32_16x16x64_i8 v[70:73], v[14:17], v[176:179], v[70:73]
	v_mfma_i32_16x16x64_i8 v[54:57], v[14:17], v[192:195], v[54:57]
	v_mfma_i32_16x16x64_i8 v[38:41], v[14:17], v[200:203], v[38:41]
	v_mfma_i32_16x16x64_i8 v[2:5], v[14:17], v[208:211], v[2:5]
	v_mfma_i32_16x16x64_i8 v[70:73], v[22:25], v[188:191], v[70:73]
	v_mfma_i32_16x16x64_i8 v[62:65], v[138:141], v[176:179], v[62:65]
	v_mfma_i32_16x16x64_i8 v[54:57], v[22:25], v[196:199], v[54:57]
	v_mfma_i32_16x16x64_i8 v[46:49], v[138:141], v[192:195], v[46:49]
	v_mfma_i32_16x16x64_i8 v[38:41], v[22:25], v[204:207], v[38:41]
	v_mfma_i32_16x16x64_i8 v[30:33], v[138:141], v[200:203], v[30:33]
	v_mfma_i32_16x16x64_i8 v[22:25], v[22:25], v[212:215], v[2:5]
	v_mfma_i32_16x16x64_i8 v[2:5], v[138:141], v[208:211], v[6:9]
	v_mfma_i32_16x16x64_i8 v[62:65], v[142:145], v[188:191], v[62:65]
	v_mfma_i32_16x16x64_i8 v[46:49], v[142:145], v[196:199], v[46:49]
	v_mfma_i32_16x16x64_i8 v[30:33], v[142:145], v[204:207], v[30:33]
	v_mfma_i32_16x16x64_i8 v[14:17], v[142:145], v[212:215], v[2:5]
	v_mfma_i32_16x16x64_i8 v[2:5], v[146:149], v[176:179], v[66:69]
	v_mfma_i32_16x16x64_i8 v[66:69], v[150:153], v[188:191], v[2:5]
	v_mfma_i32_16x16x64_i8 v[2:5], v[168:171], v[176:179], v[58:61]
	v_mfma_i32_16x16x64_i8 v[58:61], v[172:175], v[188:191], v[2:5]
	v_mfma_i32_16x16x64_i8 v[2:5], v[146:149], v[192:195], v[50:53]
	v_mfma_i32_16x16x64_i8 v[50:53], v[150:153], v[196:199], v[2:5]
	v_mfma_i32_16x16x64_i8 v[2:5], v[168:171], v[192:195], v[42:45]
	v_mfma_i32_16x16x64_i8 v[42:45], v[172:175], v[196:199], v[2:5]
	v_mfma_i32_16x16x64_i8 v[2:5], v[146:149], v[200:203], v[34:37]
	v_mfma_i32_16x16x64_i8 v[34:37], v[150:153], v[204:207], v[2:5]
	v_mfma_i32_16x16x64_i8 v[2:5], v[168:171], v[200:203], v[26:29]
	v_mfma_i32_16x16x64_i8 v[26:29], v[172:175], v[204:207], v[2:5]
	v_mfma_i32_16x16x64_i8 v[2:5], v[146:149], v[208:211], v[18:21]
	v_mfma_i32_16x16x64_i8 v[18:21], v[150:153], v[212:215], v[2:5]
	v_mfma_i32_16x16x64_i8 v[2:5], v[168:171], v[208:211], v[10:13]
	v_mfma_i32_16x16x64_i8 v[10:13], v[172:175], v[212:215], v[2:5]
	s_cbranch_scc1 .Ltb15_e
	s_barrier
	s_setprio 0
	s_branch .LBB0_2159
.Ltb15_e:
	s_setprio 0
	s_and_b64 vcc, exec, s[36:37]
	s_cbranch_vccz .LBB0_2162
	s_barrier

.LBB0_2248:
	ds_read_b128 v[146:149], v152
	ds_read_b128 v[156:159], v152 offset:1024
	ds_read_b128 v[160:163], v152 offset:2048
	ds_read_b128 v[164:167], v152 offset:3072
	ds_read_b128 v[168:171], v153
	ds_read_b128 v[172:175], v153 offset:1024
	ds_read_b128 v[176:179], v153 offset:2048
	ds_read_b128 v[180:183], v153 offset:3072
	s_add_u32 s28, s26, 0xffd50080
	s_addc_u32 s29, s27, -1
	s_cmpk_eq_i32 s64, 0xa8
	s_cselect_b32 s31, s11, s29
	s_cselect_b32 s30, s10, s28
	s_cselect_b32 s29, s25, s63
	s_cselect_b32 s28, s24, s62
	s_add_i32 m0, s38, 0xc000
	ds_read_b128 v[184:187], v154
	ds_read_b128 v[188:191], v154 offset:1024
	ds_read_b128 v[192:195], v154 offset:2048
	ds_read_b128 v[196:199], v154 offset:3072
	ds_read_b128 v[200:203], v154 offset:4096
	ds_read_b128 v[204:207], v154 offset:5120
	ds_read_b128 v[208:211], v154 offset:6144
	ds_read_b128 v[212:215], v154 offset:7168
	global_load_lds_dwordx4 v140, s[26:27]
	s_add_i32 m0, s38, 0xe000
	s_nop 0
	global_load_lds_dwordx4 v138, s[26:27]
	s_waitcnt vmcnt(8)
	s_waitcnt lgkmcnt(0)
	s_setprio 1
	s_barrier
	v_mfma_f32_16x16x32_bf16 v[126:129], v[146:149], v[184:187], v[126:129]
	v_mfma_f32_16x16x32_bf16 v[122:125], v[160:163], v[184:187], v[122:125]
	v_mfma_f32_16x16x32_bf16 v[110:113], v[146:149], v[192:195], v[110:113]
	v_mfma_f32_16x16x32_bf16 v[106:109], v[160:163], v[192:195], v[106:109]
	v_mfma_f32_16x16x32_bf16 v[94:97], v[146:149], v[200:203], v[94:97]
	v_mfma_f32_16x16x32_bf16 v[90:93], v[160:163], v[200:203], v[90:93]
	v_mfma_f32_16x16x32_bf16 v[78:81], v[146:149], v[208:211], v[78:81]
	v_mfma_f32_16x16x32_bf16 v[74:77], v[160:163], v[208:211], v[74:77]
	v_mfma_f32_16x16x32_bf16 v[126:129], v[156:159], v[188:191], v[126:129]
	v_mfma_f32_16x16x32_bf16 v[122:125], v[164:167], v[188:191], v[122:125]
	v_mfma_f32_16x16x32_bf16 v[110:113], v[156:159], v[196:199], v[110:113]
	v_mfma_f32_16x16x32_bf16 v[106:109], v[164:167], v[196:199], v[106:109]
	v_mfma_f32_16x16x32_bf16 v[94:97], v[156:159], v[204:207], v[94:97]
	v_mfma_f32_16x16x32_bf16 v[90:93], v[164:167], v[204:207], v[90:93]
	v_mfma_f32_16x16x32_bf16 v[78:81], v[156:159], v[212:215], v[78:81]
	v_mfma_f32_16x16x32_bf16 v[74:77], v[164:167], v[212:215], v[74:77]
	v_mfma_f32_16x16x32_bf16 v[118:121], v[168:171], v[184:187], v[118:121]
	v_mfma_f32_16x16x32_bf16 v[114:117], v[176:179], v[184:187], v[114:117]
	v_mfma_f32_16x16x32_bf16 v[102:105], v[168:171], v[192:195], v[102:105]
	v_mfma_f32_16x16x32_bf16 v[98:101], v[176:179], v[192:195], v[98:101]
	v_mfma_f32_16x16x32_bf16 v[86:89], v[168:171], v[200:203], v[86:89]
	v_mfma_f32_16x16x32_bf16 v[82:85], v[176:179], v[200:203], v[82:85]
	v_mfma_f32_16x16x32_bf16 v[70:73], v[168:171], v[208:211], v[70:73]
	v_mfma_f32_16x16x32_bf16 v[66:69], v[176:179], v[208:211], v[66:69]
	v_mfma_f32_16x16x32_bf16 v[118:121], v[172:175], v[188:191], v[118:121]
	v_mfma_f32_16x16x32_bf16 v[114:117], v[180:183], v[188:191], v[114:117]
	v_mfma_f32_16x16x32_bf16 v[102:105], v[172:175], v[196:199], v[102:105]
	v_mfma_f32_16x16x32_bf16 v[98:101], v[180:183], v[196:199], v[98:101]
	v_mfma_f32_16x16x32_bf16 v[86:89], v[172:175], v[204:207], v[86:89]
	v_mfma_f32_16x16x32_bf16 v[82:85], v[180:183], v[204:207], v[82:85]
	v_mfma_f32_16x16x32_bf16 v[70:73], v[172:175], v[212:215], v[70:73]
	v_mfma_f32_16x16x32_bf16 v[66:69], v[180:183], v[212:215], v[66:69]
	s_barrier
	s_setprio 0
	s_add_i32 s65, s47, s37
	v_lshl_add_u64 v[216:217], s[28:29], 0, v[132:133]
	s_mov_b32 m0, s65
	ds_read_b128 v[184:187], v154 offset:16384
	ds_read_b128 v[188:191], v154 offset:17408
	ds_read_b128 v[192:195], v154 offset:18432
	ds_read_b128 v[196:199], v154 offset:19456
	ds_read_b128 v[200:203], v154 offset:20480
	ds_read_b128 v[204:207], v154 offset:21504
	ds_read_b128 v[208:211], v154 offset:22528
	ds_read_b128 v[212:215], v154 offset:23552
	global_load_lds_dwordx4 v[216:217], off
	s_add_i32 m0, s65, 0x2000
	s_add_u32 s66, s28, 0x2b0000
	v_lshl_add_u64 v[218:219], s[28:29], 0, v[136:137]
	s_addc_u32 s67, s29, 0
	s_add_i32 s65, s49, s37
	global_load_lds_dwordx4 v[218:219], off
	s_mov_b32 m0, s65
	v_lshl_add_u64 v[222:223], s[30:31], 0, v[134:135]
	global_load_lds_dwordx4 v132, s[66:67]
	s_add_i32 m0, s65, 0x2000
	s_nop 0
	global_load_lds_dwordx4 v136, s[66:67]
	v_lshl_add_u64 v[220:221], s[30:31], 0, v[130:131]
	s_mov_b32 m0, s38
	s_nop 0
	global_load_lds_dwordx4 v[220:221], off
	s_mov_b32 m0, s39
	s_nop 0
	global_load_lds_dwordx4 v[222:223], off
	s_waitcnt vmcnt(8)
	s_waitcnt lgkmcnt(0)
	s_setprio 1
	s_barrier
	v_mfma_f32_16x16x32_bf16 v[62:65], v[146:149], v[184:187], v[62:65]
	v_mfma_f32_16x16x32_bf16 v[58:61], v[160:163], v[184:187], v[58:61]
	v_mfma_f32_16x16x32_bf16 v[46:49], v[146:149], v[192:195], v[46:49]
	v_mfma_f32_16x16x32_bf16 v[42:45], v[160:163], v[192:195], v[42:45]
	v_mfma_f32_16x16x32_bf16 v[30:33], v[146:149], v[200:203], v[30:33]
	v_mfma_f32_16x16x32_bf16 v[26:29], v[160:163], v[200:203], v[26:29]
	v_mfma_f32_16x16x32_bf16 v[14:17], v[146:149], v[208:211], v[14:17]
	v_mfma_f32_16x16x32_bf16 v[10:13], v[160:163], v[208:211], v[10:13]
	v_mfma_f32_16x16x32_bf16 v[62:65], v[156:159], v[188:191], v[62:65]
	v_mfma_f32_16x16x32_bf16 v[58:61], v[164:167], v[188:191], v[58:61]
	v_mfma_f32_16x16x32_bf16 v[46:49], v[156:159], v[196:199], v[46:49]
	v_mfma_f32_16x16x32_bf16 v[42:45], v[164:167], v[196:199], v[42:45]
	v_mfma_f32_16x16x32_bf16 v[30:33], v[156:159], v[204:207], v[30:33]
	v_mfma_f32_16x16x32_bf16 v[26:29], v[164:167], v[204:207], v[26:29]
	v_mfma_f32_16x16x32_bf16 v[14:17], v[156:159], v[212:215], v[14:17]
	v_mfma_f32_16x16x32_bf16 v[10:13], v[164:167], v[212:215], v[10:13]
	v_mfma_f32_16x16x32_bf16 v[54:57], v[168:171], v[184:187], v[54:57]
	v_mfma_f32_16x16x32_bf16 v[50:53], v[176:179], v[184:187], v[50:53]
	v_mfma_f32_16x16x32_bf16 v[38:41], v[168:171], v[192:195], v[38:41]
	v_mfma_f32_16x16x32_bf16 v[34:37], v[176:179], v[192:195], v[34:37]
	v_mfma_f32_16x16x32_bf16 v[22:25], v[168:171], v[200:203], v[22:25]
	v_mfma_f32_16x16x32_bf16 v[18:21], v[176:179], v[200:203], v[18:21]
	v_mfma_f32_16x16x32_bf16 v[6:9], v[168:171], v[208:211], v[6:9]
	v_mfma_f32_16x16x32_bf16 v[2:5], v[176:179], v[208:211], v[2:5]
	v_mfma_f32_16x16x32_bf16 v[54:57], v[172:175], v[188:191], v[54:57]
	v_mfma_f32_16x16x32_bf16 v[50:53], v[180:183], v[188:191], v[50:53]
	v_mfma_f32_16x16x32_bf16 v[38:41], v[172:175], v[196:199], v[38:41]
	v_mfma_f32_16x16x32_bf16 v[34:37], v[180:183], v[196:199], v[34:37]
	v_mfma_f32_16x16x32_bf16 v[22:25], v[172:175], v[204:207], v[22:25]
	v_mfma_f32_16x16x32_bf16 v[18:21], v[180:183], v[204:207], v[18:21]
	v_mfma_f32_16x16x32_bf16 v[6:9], v[172:175], v[212:215], v[6:9]
	v_mfma_f32_16x16x32_bf16 v[2:5], v[180:183], v[212:215], v[2:5]
	s_barrier
	s_setprio 0
	s_add_i32 s65, 0, 0x18000
	s_add_i32 s66, 0, 0x1c000
	v_add_u32_e32 v164, s65, v150
	v_add_u32_e32 v180, s66, v150
	ds_read_b128 v[146:149], v164
	ds_read_b128 v[156:159], v164 offset:1024
	ds_read_b128 v[160:163], v164 offset:2048
	ds_read_b128 v[164:167], v164 offset:3072
	ds_read_b128 v[168:171], v180
	ds_read_b128 v[172:175], v180 offset:1024
	ds_read_b128 v[176:179], v180 offset:2048
	ds_read_b128 v[180:183], v180 offset:3072
	s_add_u32 s30, s30, 0x2b0000
	s_addc_u32 s31, s31, 0
	s_mov_b32 m0, s40
	ds_read_b128 v[184:187], v154 offset:32768
	ds_read_b128 v[188:191], v154 offset:33792
	ds_read_b128 v[192:195], v154 offset:34816
	ds_read_b128 v[196:199], v154 offset:35840
	ds_read_b128 v[200:203], v154 offset:36864
	ds_read_b128 v[204:207], v154 offset:37888
	ds_read_b128 v[208:211], v154 offset:38912
	ds_read_b128 v[212:215], v154 offset:39936
	global_load_lds_dwordx4 v130, s[30:31]
	s_mov_b32 m0, s41
	s_nop 0
	global_load_lds_dwordx4 v134, s[30:31]
	s_waitcnt vmcnt(8)
	s_waitcnt lgkmcnt(0)
	s_setprio 1
	s_barrier
	v_mfma_f32_16x16x32_bf16 v[126:129], v[146:149], v[184:187], v[126:129]
	v_mfma_f32_16x16x32_bf16 v[122:125], v[160:163], v[184:187], v[122:125]
	v_mfma_f32_16x16x32_bf16 v[110:113], v[146:149], v[192:195], v[110:113]
	v_mfma_f32_16x16x32_bf16 v[106:109], v[160:163], v[192:195], v[106:109]
	v_mfma_f32_16x16x32_bf16 v[94:97], v[146:149], v[200:203], v[94:97]
	v_mfma_f32_16x16x32_bf16 v[90:93], v[160:163], v[200:203], v[90:93]
	v_mfma_f32_16x16x32_bf16 v[78:81], v[146:149], v[208:211], v[78:81]
	v_mfma_f32_16x16x32_bf16 v[74:77], v[160:163], v[208:211], v[74:77]
	v_mfma_f32_16x16x32_bf16 v[126:129], v[156:159], v[188:191], v[126:129]
	v_mfma_f32_16x16x32_bf16 v[122:125], v[164:167], v[188:191], v[122:125]
	v_mfma_f32_16x16x32_bf16 v[110:113], v[156:159], v[196:199], v[110:113]
	v_mfma_f32_16x16x32_bf16 v[106:109], v[164:167], v[196:199], v[106:109]
	v_mfma_f32_16x16x32_bf16 v[94:97], v[156:159], v[204:207], v[94:97]
	v_mfma_f32_16x16x32_bf16 v[90:93], v[164:167], v[204:207], v[90:93]
	v_mfma_f32_16x16x32_bf16 v[78:81], v[156:159], v[212:215], v[78:81]
	v_mfma_f32_16x16x32_bf16 v[74:77], v[164:167], v[212:215], v[74:77]
	v_mfma_f32_16x16x32_bf16 v[118:121], v[168:171], v[184:187], v[118:121]
	v_mfma_f32_16x16x32_bf16 v[114:117], v[176:179], v[184:187], v[114:117]
	v_mfma_f32_16x16x32_bf16 v[102:105], v[168:171], v[192:195], v[102:105]
	v_mfma_f32_16x16x32_bf16 v[98:101], v[176:179], v[192:195], v[98:101]
	v_mfma_f32_16x16x32_bf16 v[86:89], v[168:171], v[200:203], v[86:89]
	v_mfma_f32_16x16x32_bf16 v[82:85], v[176:179], v[200:203], v[82:85]
	v_mfma_f32_16x16x32_bf16 v[70:73], v[168:171], v[208:211], v[70:73]
	v_mfma_f32_16x16x32_bf16 v[66:69], v[176:179], v[208:211], v[66:69]
	v_mfma_f32_16x16x32_bf16 v[118:121], v[172:175], v[188:191], v[118:121]
	v_mfma_f32_16x16x32_bf16 v[114:117], v[180:183], v[188:191], v[114:117]
	v_mfma_f32_16x16x32_bf16 v[102:105], v[172:175], v[196:199], v[102:105]
	v_mfma_f32_16x16x32_bf16 v[98:101], v[180:183], v[196:199], v[98:101]
	v_mfma_f32_16x16x32_bf16 v[86:89], v[172:175], v[204:207], v[86:89]
	v_mfma_f32_16x16x32_bf16 v[82:85], v[180:183], v[204:207], v[82:85]
	v_mfma_f32_16x16x32_bf16 v[70:73], v[172:175], v[212:215], v[70:73]
	v_mfma_f32_16x16x32_bf16 v[66:69], v[180:183], v[212:215], v[66:69]
	s_barrier
	s_setprio 0
	s_add_i32 s30, s65, s37
	v_lshl_add_u64 v[216:217], v[216:217], 0, s[20:21]
	s_mov_b32 m0, s30
	ds_read_b128 v[184:187], v154 offset:49152
	ds_read_b128 v[188:191], v154 offset:50176
	ds_read_b128 v[192:195], v154 offset:51200
	ds_read_b128 v[196:199], v154 offset:52224
	ds_read_b128 v[200:203], v154 offset:53248
	ds_read_b128 v[204:207], v154 offset:54272
	ds_read_b128 v[208:211], v154 offset:55296
	ds_read_b128 v[212:215], v154 offset:56320
	global_load_lds_dwordx4 v[216:217], off
	s_add_i32 m0, s30, 0x2000
	s_add_u32 s28, s28, 0x2b0080
	v_lshl_add_u64 v[216:217], v[218:219], 0, s[20:21]
	s_addc_u32 s29, s29, 0
	s_add_i32 s30, s66, s37
	global_load_lds_dwordx4 v[216:217], off
	s_mov_b32 m0, s30
	s_nop 0
	global_load_lds_dwordx4 v132, s[28:29]
	s_add_i32 m0, s30, 0x2000
	s_nop 0
	global_load_lds_dwordx4 v136, s[28:29]
	v_lshl_add_u64 v[216:217], v[220:221], 0, s[20:21]
	s_mov_b32 m0, s44
	s_nop 0
	global_load_lds_dwordx4 v[216:217], off
	v_lshl_add_u64 v[216:217], v[222:223], 0, s[20:21]
	s_mov_b32 m0, s45
	s_nop 0
	global_load_lds_dwordx4 v[216:217], off
	s_add_i32 s64, s64, 2
	s_add_u32 s62, s62, 0x100
	s_addc_u32 s63, s63, 0
	s_add_u32 s26, s26, 0x100
	s_addc_u32 s27, s27, 0
	s_cmpk_gt_u32 s64, 0xa9
	s_waitcnt vmcnt(8)
	s_waitcnt lgkmcnt(0)
	s_setprio 1
	s_barrier
	v_mfma_f32_16x16x32_bf16 v[62:65], v[146:149], v[184:187], v[62:65]
	v_mfma_f32_16x16x32_bf16 v[58:61], v[160:163], v[184:187], v[58:61]
	v_mfma_f32_16x16x32_bf16 v[46:49], v[146:149], v[192:195], v[46:49]
	v_mfma_f32_16x16x32_bf16 v[42:45], v[160:163], v[192:195], v[42:45]
	v_mfma_f32_16x16x32_bf16 v[30:33], v[146:149], v[200:203], v[30:33]
	v_mfma_f32_16x16x32_bf16 v[26:29], v[160:163], v[200:203], v[26:29]
	v_mfma_f32_16x16x32_bf16 v[14:17], v[146:149], v[208:211], v[14:17]
	v_mfma_f32_16x16x32_bf16 v[10:13], v[160:163], v[208:211], v[10:13]
	v_mfma_f32_16x16x32_bf16 v[62:65], v[156:159], v[188:191], v[62:65]
	v_mfma_f32_16x16x32_bf16 v[58:61], v[164:167], v[188:191], v[58:61]
	v_mfma_f32_16x16x32_bf16 v[46:49], v[156:159], v[196:199], v[46:49]
	v_mfma_f32_16x16x32_bf16 v[42:45], v[164:167], v[196:199], v[42:45]
	v_mfma_f32_16x16x32_bf16 v[30:33], v[156:159], v[204:207], v[30:33]
	v_mfma_f32_16x16x32_bf16 v[26:29], v[164:167], v[204:207], v[26:29]
	v_mfma_f32_16x16x32_bf16 v[14:17], v[156:159], v[212:215], v[14:17]
	v_mfma_f32_16x16x32_bf16 v[10:13], v[164:167], v[212:215], v[10:13]
	v_mfma_f32_16x16x32_bf16 v[54:57], v[168:171], v[184:187], v[54:57]
	v_mfma_f32_16x16x32_bf16 v[50:53], v[176:179], v[184:187], v[50:53]
	v_mfma_f32_16x16x32_bf16 v[38:41], v[168:171], v[192:195], v[38:41]
	v_mfma_f32_16x16x32_bf16 v[34:37], v[176:179], v[192:195], v[34:37]
	v_mfma_f32_16x16x32_bf16 v[22:25], v[168:171], v[200:203], v[22:25]
	v_mfma_f32_16x16x32_bf16 v[18:21], v[176:179], v[200:203], v[18:21]
	v_mfma_f32_16x16x32_bf16 v[6:9], v[168:171], v[208:211], v[6:9]
	v_mfma_f32_16x16x32_bf16 v[2:5], v[176:179], v[208:211], v[2:5]
	v_mfma_f32_16x16x32_bf16 v[54:57], v[172:175], v[188:191], v[54:57]
	v_mfma_f32_16x16x32_bf16 v[50:53], v[180:183], v[188:191], v[50:53]
	v_mfma_f32_16x16x32_bf16 v[38:41], v[172:175], v[196:199], v[38:41]
	v_mfma_f32_16x16x32_bf16 v[34:37], v[180:183], v[196:199], v[34:37]
	v_mfma_f32_16x16x32_bf16 v[22:25], v[172:175], v[204:207], v[22:25]
	v_mfma_f32_16x16x32_bf16 v[18:21], v[180:183], v[204:207], v[18:21]
	v_mfma_f32_16x16x32_bf16 v[6:9], v[172:175], v[212:215], v[6:9]
	v_mfma_f32_16x16x32_bf16 v[2:5], v[180:183], v[212:215], v[2:5]
	s_cbranch_scc1 .Ltb16_e
	s_barrier
	s_setprio 0
	s_branch .LBB0_2248
.Ltb16_e:
	s_setprio 0
	v_lshl_add_u32 v245, s60, 8, v1
	v_lshl_or_b32 v246, s61, 8, v151
	v_lshlrev_b32_e32 v245, 13, v245
	v_lshl_add_u32 v245, v246, 1, v245
	global_load_dwordx4 v[146:149], v245, s[16:17]
	global_load_dwordx4 v[156:159], v245, s[16:17] offset:256
	s_add_u32 s26, s16, 0x20000
	s_addc_u32 s27, s17, 0
	global_load_dwordx4 v[160:163], v245, s[26:27]
	global_load_dwordx4 v[164:167], v245, s[26:27] offset:256
	s_add_u32 s26, s16, 0x40000
	s_addc_u32 s27, s17, 0
	global_load_dwordx4 v[168:171], v245, s[26:27]
	global_load_dwordx4 v[172:175], v245, s[26:27] offset:256
	s_add_u32 s26, s16, 0x60000
	s_addc_u32 s27, s17, 0
	global_load_dwordx4 v[176:179], v245, s[26:27]
	global_load_dwordx4 v[180:183], v245, s[26:27] offset:256
	s_add_u32 s26, s16, 0x100000
	s_addc_u32 s27, s17, 0
	global_load_dwordx4 v[184:187], v245, s[26:27]
	global_load_dwordx4 v[188:191], v245, s[26:27] offset:256
	s_add_u32 s26, s16, 0x120000
	s_addc_u32 s27, s17, 0
	global_load_dwordx4 v[192:195], v245, s[26:27]
	global_load_dwordx4 v[196:199], v245, s[26:27] offset:256
	s_add_u32 s26, s16, 0x140000
	s_addc_u32 s27, s17, 0
	global_load_dwordx4 v[200:203], v245, s[26:27]
	global_load_dwordx4 v[204:207], v245, s[26:27] offset:256
	s_add_u32 s26, s16, 0x160000
	s_addc_u32 s27, s17, 0
	global_load_dwordx4 v[208:211], v245, s[26:27]
	global_load_dwordx4 v[212:215], v245, s[26:27] offset:256
	s_and_b64 vcc, exec, s[22:23]
	s_cbranch_vccz .LBB0_2251
	s_barrier
